# K-loop handover: s_setprio 1 before the pre-MFMA barrier, barrier before s_setprio 0, redundant lgkmcnt(0) dropped
# speedup vs baseline: 1.0019x; 1.0019x over previous
.LBB0_297:
	s_add_u32 s0, s36, 0xfff80080
	s_addc_u32 s6, s37, -1
	s_add_i32 s49, 0, 0x10000
	s_cmp_eq_u32 s55, 28
	s_cselect_b32 s35, s25, s6
	s_cselect_b32 s34, s33, s0
	v_add_u32_e32 v156, s49, v159
	s_cselect_b32 s31, s40, s39
	s_cselect_b32 s30, s50, s38
	s_add_i32 s0, 0, 0x14000
	ds_read_b128 v[144:147], v156
	ds_read_b128 v[148:151], v156 offset:1024
	ds_read_b128 v[152:155], v156 offset:2048
	ds_read_b128 v[164:167], v156 offset:3072
	v_add_u32_e32 v156, s0, v159
	ds_read_b128 v[168:171], v156
	ds_read_b128 v[172:175], v156 offset:1024
	ds_read_b128 v[176:179], v156 offset:2048
	ds_read_b128 v[180:183], v156 offset:3072
	v_lshl_add_u64 v[156:157], s[36:37], 0, v[140:141]
	s_add_i32 m0, s47, 0xc000
	ds_read_b128 v[184:187], v163
	ds_read_b128 v[188:191], v163 offset:1024
	ds_read_b128 v[192:195], v163 offset:2048
	ds_read_b128 v[200:203], v163 offset:3072
	ds_read_b128 v[204:207], v163 offset:4096
	ds_read_b128 v[208:211], v163 offset:5120
	ds_read_b128 v[212:215], v163 offset:6144
	ds_read_b128 v[216:219], v163 offset:7168
	global_load_lds_dwordx4 v[156:157], off
	v_lshl_add_u64 v[156:157], s[36:37], 0, v[142:143]
	s_add_i32 m0, s47, 0xe000
	s_nop 0
	global_load_lds_dwordx4 v[156:157], off
	s_waitcnt vmcnt(8)
	s_waitcnt lgkmcnt(0)
	s_setprio 1
	s_barrier
	v_mfma_f32_16x16x32_bf16 v[128:131], v[144:147], v[184:187], v[128:131]
	v_mfma_f32_16x16x32_bf16 v[124:127], v[152:155], v[184:187], v[124:127]
	v_mfma_f32_16x16x32_bf16 v[112:115], v[144:147], v[192:195], v[112:115]
	v_mfma_f32_16x16x32_bf16 v[108:111], v[152:155], v[192:195], v[108:111]
	v_mfma_f32_16x16x32_bf16 v[96:99], v[144:147], v[204:207], v[96:99]
	v_mfma_f32_16x16x32_bf16 v[92:95], v[152:155], v[204:207], v[92:95]
	v_mfma_f32_16x16x32_bf16 v[80:83], v[144:147], v[212:215], v[80:83]
	v_mfma_f32_16x16x32_bf16 v[76:79], v[152:155], v[212:215], v[76:79]
	v_mfma_f32_16x16x32_bf16 v[128:131], v[148:151], v[188:191], v[128:131]
	v_mfma_f32_16x16x32_bf16 v[124:127], v[164:167], v[188:191], v[124:127]
	v_mfma_f32_16x16x32_bf16 v[112:115], v[148:151], v[200:203], v[112:115]
	v_mfma_f32_16x16x32_bf16 v[108:111], v[164:167], v[200:203], v[108:111]
	v_mfma_f32_16x16x32_bf16 v[96:99], v[148:151], v[208:211], v[96:99]
	v_mfma_f32_16x16x32_bf16 v[92:95], v[164:167], v[208:211], v[92:95]
	v_mfma_f32_16x16x32_bf16 v[80:83], v[148:151], v[216:219], v[80:83]
	v_mfma_f32_16x16x32_bf16 v[76:79], v[164:167], v[216:219], v[76:79]
	s_setprio 0
	s_setprio 1
	v_mfma_f32_16x16x32_bf16 v[120:123], v[168:171], v[184:187], v[120:123]
	v_mfma_f32_16x16x32_bf16 v[116:119], v[176:179], v[184:187], v[116:119]
	v_mfma_f32_16x16x32_bf16 v[104:107], v[168:171], v[192:195], v[104:107]
	v_mfma_f32_16x16x32_bf16 v[100:103], v[176:179], v[192:195], v[100:103]
	v_mfma_f32_16x16x32_bf16 v[88:91], v[168:171], v[204:207], v[88:91]
	v_mfma_f32_16x16x32_bf16 v[84:87], v[176:179], v[204:207], v[84:87]
	v_mfma_f32_16x16x32_bf16 v[72:75], v[168:171], v[212:215], v[72:75]
	v_mfma_f32_16x16x32_bf16 v[68:71], v[176:179], v[212:215], v[68:71]
	v_mfma_f32_16x16x32_bf16 v[120:123], v[172:175], v[188:191], v[120:123]
	v_mfma_f32_16x16x32_bf16 v[116:119], v[180:183], v[188:191], v[116:119]
	v_mfma_f32_16x16x32_bf16 v[104:107], v[172:175], v[200:203], v[104:107]
	v_mfma_f32_16x16x32_bf16 v[100:103], v[180:183], v[200:203], v[100:103]
	v_mfma_f32_16x16x32_bf16 v[88:91], v[172:175], v[208:211], v[88:91]
	v_mfma_f32_16x16x32_bf16 v[84:87], v[180:183], v[208:211], v[84:87]
	v_mfma_f32_16x16x32_bf16 v[72:75], v[172:175], v[216:219], v[72:75]
	v_mfma_f32_16x16x32_bf16 v[68:71], v[180:183], v[216:219], v[68:71]
	s_barrier
	s_setprio 0
	s_add_i32 s6, s49, s46
	v_lshl_add_u64 v[156:157], s[30:31], 0, v[136:137]
	s_mov_b32 m0, s6
	ds_read_b128 v[184:187], v163 offset:16384
	ds_read_b128 v[188:191], v163 offset:17408
	ds_read_b128 v[192:195], v163 offset:18432
	ds_read_b128 v[200:203], v163 offset:19456
	ds_read_b128 v[204:207], v163 offset:20480
	ds_read_b128 v[208:211], v163 offset:21504
	ds_read_b128 v[212:215], v163 offset:22528
	ds_read_b128 v[216:219], v163 offset:23552
	global_load_lds_dwordx4 v[156:157], off
	s_add_i32 m0, s6, 0x2000
	s_add_u32 s66, s30, 0x80000
	v_lshl_add_u64 v[220:221], s[30:31], 0, v[132:133]
	s_addc_u32 s67, s31, 0
	s_add_i32 s0, s0, s46
	global_load_lds_dwordx4 v[220:221], off
	v_lshl_add_u64 v[222:223], s[66:67], 0, v[136:137]
	s_mov_b32 m0, s0
	v_lshl_add_u64 v[224:225], s[34:35], 0, v[134:135]
	global_load_lds_dwordx4 v[222:223], off
	v_lshl_add_u64 v[222:223], s[66:67], 0, v[132:133]
	s_add_i32 m0, s0, 0x2000
	s_nop 0
	global_load_lds_dwordx4 v[222:223], off
	v_lshl_add_u64 v[222:223], s[34:35], 0, v[138:139]
	s_mov_b32 m0, s47
	s_nop 0
	global_load_lds_dwordx4 v[222:223], off
	s_mov_b32 m0, s52
	s_nop 0
	global_load_lds_dwordx4 v[224:225], off
	s_waitcnt vmcnt(8)
	s_waitcnt lgkmcnt(0)
	s_setprio 1
	s_barrier
	v_mfma_f32_16x16x32_bf16 v[64:67], v[144:147], v[184:187], v[64:67]
	v_mfma_f32_16x16x32_bf16 v[60:63], v[152:155], v[184:187], v[60:63]
	v_mfma_f32_16x16x32_bf16 v[48:51], v[144:147], v[192:195], v[48:51]
	v_mfma_f32_16x16x32_bf16 v[44:47], v[152:155], v[192:195], v[44:47]
	v_mfma_f32_16x16x32_bf16 v[32:35], v[144:147], v[204:207], v[32:35]
	v_mfma_f32_16x16x32_bf16 v[28:31], v[152:155], v[204:207], v[28:31]
	v_mfma_f32_16x16x32_bf16 v[16:19], v[144:147], v[212:215], v[16:19]
	v_mfma_f32_16x16x32_bf16 v[12:15], v[152:155], v[212:215], v[12:15]
	v_mfma_f32_16x16x32_bf16 v[64:67], v[148:151], v[188:191], v[64:67]
	v_mfma_f32_16x16x32_bf16 v[60:63], v[164:167], v[188:191], v[60:63]
	v_mfma_f32_16x16x32_bf16 v[48:51], v[148:151], v[200:203], v[48:51]
	v_mfma_f32_16x16x32_bf16 v[44:47], v[164:167], v[200:203], v[44:47]
	v_mfma_f32_16x16x32_bf16 v[32:35], v[148:151], v[208:211], v[32:35]
	v_mfma_f32_16x16x32_bf16 v[28:31], v[164:167], v[208:211], v[28:31]
	v_mfma_f32_16x16x32_bf16 v[16:19], v[148:151], v[216:219], v[16:19]
	v_mfma_f32_16x16x32_bf16 v[12:15], v[164:167], v[216:219], v[12:15]
	s_setprio 0
	s_setprio 1
	v_mfma_f32_16x16x32_bf16 v[56:59], v[168:171], v[184:187], v[56:59]
	v_mfma_f32_16x16x32_bf16 v[52:55], v[176:179], v[184:187], v[52:55]
	v_mfma_f32_16x16x32_bf16 v[40:43], v[168:171], v[192:195], v[40:43]
	v_mfma_f32_16x16x32_bf16 v[36:39], v[176:179], v[192:195], v[36:39]
	v_mfma_f32_16x16x32_bf16 v[24:27], v[168:171], v[204:207], v[24:27]
	v_mfma_f32_16x16x32_bf16 v[20:23], v[176:179], v[204:207], v[20:23]
	v_mfma_f32_16x16x32_bf16 v[8:11], v[168:171], v[212:215], v[8:11]
	v_mfma_f32_16x16x32_bf16 v[4:7], v[176:179], v[212:215], v[4:7]
	v_mfma_f32_16x16x32_bf16 v[56:59], v[172:175], v[188:191], v[56:59]
	v_mfma_f32_16x16x32_bf16 v[52:55], v[180:183], v[188:191], v[52:55]
	v_mfma_f32_16x16x32_bf16 v[40:43], v[172:175], v[200:203], v[40:43]
	v_mfma_f32_16x16x32_bf16 v[36:39], v[180:183], v[200:203], v[36:39]
	v_mfma_f32_16x16x32_bf16 v[24:27], v[172:175], v[208:211], v[24:27]
	v_mfma_f32_16x16x32_bf16 v[20:23], v[180:183], v[208:211], v[20:23]
	v_mfma_f32_16x16x32_bf16 v[8:11], v[172:175], v[216:219], v[8:11]
	v_mfma_f32_16x16x32_bf16 v[4:7], v[180:183], v[216:219], v[4:7]
	s_barrier
	s_setprio 0
	s_add_i32 s0, 0, 0x18000
	v_add_u32_e32 v158, s0, v159
	s_add_i32 s6, 0, 0x1c000
	ds_read_b128 v[144:147], v158
	ds_read_b128 v[148:151], v158 offset:1024
	ds_read_b128 v[152:155], v158 offset:2048
	ds_read_b128 v[164:167], v158 offset:3072
	v_add_u32_e32 v158, s6, v159
	ds_read_b128 v[168:171], v158
	ds_read_b128 v[172:175], v158 offset:1024
	ds_read_b128 v[176:179], v158 offset:2048
	ds_read_b128 v[180:183], v158 offset:3072
	s_add_u32 s34, s34, 0x80000
	s_addc_u32 s35, s35, 0
	s_mov_b32 m0, s53
	v_lshl_add_u64 v[226:227], s[34:35], 0, v[138:139]
	ds_read_b128 v[184:187], v163 offset:32768
	ds_read_b128 v[188:191], v163 offset:33792
	ds_read_b128 v[192:195], v163 offset:34816
	ds_read_b128 v[200:203], v163 offset:35840
	ds_read_b128 v[204:207], v163 offset:36864
	ds_read_b128 v[208:211], v163 offset:37888
	ds_read_b128 v[212:215], v163 offset:38912
	ds_read_b128 v[216:219], v163 offset:39936
	global_load_lds_dwordx4 v[226:227], off
	v_lshl_add_u64 v[226:227], s[34:35], 0, v[134:135]
	s_mov_b32 m0, s60
	s_nop 0
	global_load_lds_dwordx4 v[226:227], off
	s_waitcnt vmcnt(8)
	s_waitcnt lgkmcnt(0)
	s_setprio 1
	s_barrier
	v_mfma_f32_16x16x32_bf16 v[128:131], v[144:147], v[184:187], v[128:131]
	v_mfma_f32_16x16x32_bf16 v[124:127], v[152:155], v[184:187], v[124:127]
	v_mfma_f32_16x16x32_bf16 v[112:115], v[144:147], v[192:195], v[112:115]
	v_mfma_f32_16x16x32_bf16 v[108:111], v[152:155], v[192:195], v[108:111]
	v_mfma_f32_16x16x32_bf16 v[96:99], v[144:147], v[204:207], v[96:99]
	v_mfma_f32_16x16x32_bf16 v[92:95], v[152:155], v[204:207], v[92:95]
	v_mfma_f32_16x16x32_bf16 v[80:83], v[144:147], v[212:215], v[80:83]
	v_mfma_f32_16x16x32_bf16 v[76:79], v[152:155], v[212:215], v[76:79]
	v_mfma_f32_16x16x32_bf16 v[128:131], v[148:151], v[188:191], v[128:131]
	v_mfma_f32_16x16x32_bf16 v[124:127], v[164:167], v[188:191], v[124:127]
	v_mfma_f32_16x16x32_bf16 v[112:115], v[148:151], v[200:203], v[112:115]
	v_mfma_f32_16x16x32_bf16 v[108:111], v[164:167], v[200:203], v[108:111]
	v_mfma_f32_16x16x32_bf16 v[96:99], v[148:151], v[208:211], v[96:99]
	v_mfma_f32_16x16x32_bf16 v[92:95], v[164:167], v[208:211], v[92:95]
	v_mfma_f32_16x16x32_bf16 v[80:83], v[148:151], v[216:219], v[80:83]
	v_mfma_f32_16x16x32_bf16 v[76:79], v[164:167], v[216:219], v[76:79]
	s_setprio 0
	s_setprio 1
	v_mfma_f32_16x16x32_bf16 v[120:123], v[168:171], v[184:187], v[120:123]
	v_mfma_f32_16x16x32_bf16 v[116:119], v[176:179], v[184:187], v[116:119]
	v_mfma_f32_16x16x32_bf16 v[104:107], v[168:171], v[192:195], v[104:107]
	v_mfma_f32_16x16x32_bf16 v[100:103], v[176:179], v[192:195], v[100:103]
	v_mfma_f32_16x16x32_bf16 v[88:91], v[168:171], v[204:207], v[88:91]
	v_mfma_f32_16x16x32_bf16 v[84:87], v[176:179], v[204:207], v[84:87]
	v_mfma_f32_16x16x32_bf16 v[72:75], v[168:171], v[212:215], v[72:75]
	v_mfma_f32_16x16x32_bf16 v[68:71], v[176:179], v[212:215], v[68:71]
	v_mfma_f32_16x16x32_bf16 v[120:123], v[172:175], v[188:191], v[120:123]
	v_mfma_f32_16x16x32_bf16 v[116:119], v[180:183], v[188:191], v[116:119]
	v_mfma_f32_16x16x32_bf16 v[104:107], v[172:175], v[200:203], v[104:107]
	v_mfma_f32_16x16x32_bf16 v[100:103], v[180:183], v[200:203], v[100:103]
	v_mfma_f32_16x16x32_bf16 v[88:91], v[172:175], v[208:211], v[88:91]
	v_mfma_f32_16x16x32_bf16 v[84:87], v[180:183], v[208:211], v[84:87]
	v_mfma_f32_16x16x32_bf16 v[72:75], v[172:175], v[216:219], v[72:75]
	v_mfma_f32_16x16x32_bf16 v[68:71], v[180:183], v[216:219], v[68:71]
	s_barrier
	s_setprio 0
	s_add_i32 s0, s0, s46
	v_lshl_add_u64 v[156:157], v[156:157], 0, s[90:91]
	s_mov_b32 m0, s0
	ds_read_b128 v[184:187], v163 offset:49152
	ds_read_b128 v[188:191], v163 offset:50176
	ds_read_b128 v[192:195], v163 offset:51200
	ds_read_b128 v[200:203], v163 offset:52224
	ds_read_b128 v[204:207], v163 offset:53248
	ds_read_b128 v[208:211], v163 offset:54272
	ds_read_b128 v[212:215], v163 offset:55296
	ds_read_b128 v[216:219], v163 offset:56320
	global_load_lds_dwordx4 v[156:157], off
	s_add_i32 m0, s0, 0x2000
	s_add_u32 s30, s30, 0x80080
	v_lshl_add_u64 v[156:157], v[220:221], 0, s[90:91]
	s_addc_u32 s31, s31, 0
	s_add_i32 s0, s6, s46
	global_load_lds_dwordx4 v[156:157], off
	v_lshl_add_u64 v[156:157], s[30:31], 0, v[136:137]
	s_mov_b32 m0, s0
	s_nop 0
	global_load_lds_dwordx4 v[156:157], off
	v_lshl_add_u64 v[156:157], s[30:31], 0, v[132:133]
	s_add_i32 m0, s0, 0x2000
	s_nop 0
	global_load_lds_dwordx4 v[156:157], off
	v_lshl_add_u64 v[156:157], v[222:223], 0, s[90:91]
	s_mov_b32 m0, s62
	s_nop 0
	global_load_lds_dwordx4 v[156:157], off
	v_lshl_add_u64 v[156:157], v[224:225], 0, s[90:91]
	s_mov_b32 m0, s51
	s_nop 0
	global_load_lds_dwordx4 v[156:157], off
	s_waitcnt vmcnt(8)
	s_waitcnt lgkmcnt(0)
	s_setprio 1
	s_barrier
	v_mfma_f32_16x16x32_bf16 v[64:67], v[144:147], v[184:187], v[64:67]
	v_mfma_f32_16x16x32_bf16 v[60:63], v[152:155], v[184:187], v[60:63]
	v_mfma_f32_16x16x32_bf16 v[48:51], v[144:147], v[192:195], v[48:51]
	v_mfma_f32_16x16x32_bf16 v[44:47], v[152:155], v[192:195], v[44:47]
	v_mfma_f32_16x16x32_bf16 v[32:35], v[144:147], v[204:207], v[32:35]
	v_mfma_f32_16x16x32_bf16 v[28:31], v[152:155], v[204:207], v[28:31]
	v_mfma_f32_16x16x32_bf16 v[16:19], v[144:147], v[212:215], v[16:19]
	v_mfma_f32_16x16x32_bf16 v[12:15], v[152:155], v[212:215], v[12:15]
	v_mfma_f32_16x16x32_bf16 v[64:67], v[148:151], v[188:191], v[64:67]
	v_mfma_f32_16x16x32_bf16 v[60:63], v[164:167], v[188:191], v[60:63]
	v_mfma_f32_16x16x32_bf16 v[48:51], v[148:151], v[200:203], v[48:51]
	v_mfma_f32_16x16x32_bf16 v[44:47], v[164:167], v[200:203], v[44:47]
	v_mfma_f32_16x16x32_bf16 v[32:35], v[148:151], v[208:211], v[32:35]
	v_mfma_f32_16x16x32_bf16 v[28:31], v[164:167], v[208:211], v[28:31]
	v_mfma_f32_16x16x32_bf16 v[16:19], v[148:151], v[216:219], v[16:19]
	v_mfma_f32_16x16x32_bf16 v[12:15], v[164:167], v[216:219], v[12:15]
	s_setprio 0
	s_setprio 1
	v_mfma_f32_16x16x32_bf16 v[56:59], v[168:171], v[184:187], v[56:59]
	v_mfma_f32_16x16x32_bf16 v[52:55], v[176:179], v[184:187], v[52:55]
	v_mfma_f32_16x16x32_bf16 v[40:43], v[168:171], v[192:195], v[40:43]
	v_mfma_f32_16x16x32_bf16 v[36:39], v[176:179], v[192:195], v[36:39]
	v_mfma_f32_16x16x32_bf16 v[24:27], v[168:171], v[204:207], v[24:27]
	v_mfma_f32_16x16x32_bf16 v[20:23], v[176:179], v[204:207], v[20:23]
	v_mfma_f32_16x16x32_bf16 v[8:11], v[168:171], v[212:215], v[8:11]
	v_mfma_f32_16x16x32_bf16 v[4:7], v[176:179], v[212:215], v[4:7]
	v_mfma_f32_16x16x32_bf16 v[56:59], v[172:175], v[188:191], v[56:59]
	v_mfma_f32_16x16x32_bf16 v[52:55], v[180:183], v[188:191], v[52:55]
	v_mfma_f32_16x16x32_bf16 v[40:43], v[172:175], v[200:203], v[40:43]
	v_mfma_f32_16x16x32_bf16 v[36:39], v[180:183], v[200:203], v[36:39]
	v_mfma_f32_16x16x32_bf16 v[24:27], v[172:175], v[208:211], v[24:27]
	v_mfma_f32_16x16x32_bf16 v[20:23], v[180:183], v[208:211], v[20:23]
	v_mfma_f32_16x16x32_bf16 v[8:11], v[172:175], v[216:219], v[8:11]
	v_mfma_f32_16x16x32_bf16 v[4:7], v[180:183], v[216:219], v[4:7]
	s_barrier
	s_setprio 0
	s_add_i32 s55, s55, 2
	s_add_u32 s36, s36, 0x100
	s_addc_u32 s37, s37, 0
	s_add_u32 s38, s38, 0x100
	s_addc_u32 s39, s39, 0
	s_cmp_gt_u32 s55, 29
	s_cbranch_scc0 .LBB0_297
	s_and_b64 vcc, exec, s[22:23]
	s_cbranch_vccz .LBB0_300
	s_barrier

.LBB0_336:
	s_add_u32 s0, s36, 0xfff80080
	s_addc_u32 s6, s37, -1
	s_add_i32 s49, 0, 0x10000
	s_cmp_eq_u32 s50, 28
	s_cselect_b32 s35, s24, s6
	s_cselect_b32 s34, s25, s0
	v_add_u32_e32 v156, s49, v159
	s_cselect_b32 s31, s33, s39
	s_cselect_b32 s30, s40, s38
	s_add_i32 s0, 0, 0x14000
	ds_read_b128 v[144:147], v156
	ds_read_b128 v[148:151], v156 offset:1024
	ds_read_b128 v[152:155], v156 offset:2048
	ds_read_b128 v[164:167], v156 offset:3072
	v_add_u32_e32 v156, s0, v159
	ds_read_b128 v[168:171], v156
	ds_read_b128 v[172:175], v156 offset:1024
	ds_read_b128 v[176:179], v156 offset:2048
	ds_read_b128 v[180:183], v156 offset:3072
	v_lshl_add_u64 v[156:157], s[36:37], 0, v[140:141]
	s_add_i32 m0, s45, 0xc000
	ds_read_b128 v[184:187], v163
	ds_read_b128 v[188:191], v163 offset:1024
	ds_read_b128 v[192:195], v163 offset:2048
	ds_read_b128 v[200:203], v163 offset:3072
	ds_read_b128 v[204:207], v163 offset:4096
	ds_read_b128 v[208:211], v163 offset:5120
	ds_read_b128 v[212:215], v163 offset:6144
	ds_read_b128 v[216:219], v163 offset:7168
	global_load_lds_dwordx4 v[156:157], off
	v_lshl_add_u64 v[156:157], s[36:37], 0, v[142:143]
	s_add_i32 m0, s45, 0xe000
	s_nop 0
	global_load_lds_dwordx4 v[156:157], off
	s_waitcnt vmcnt(8)
	s_waitcnt lgkmcnt(0)
	s_setprio 1
	s_barrier
	v_mfma_f32_16x16x32_bf16 v[128:131], v[144:147], v[184:187], v[128:131]
	v_mfma_f32_16x16x32_bf16 v[124:127], v[152:155], v[184:187], v[124:127]
	v_mfma_f32_16x16x32_bf16 v[112:115], v[144:147], v[192:195], v[112:115]
	v_mfma_f32_16x16x32_bf16 v[108:111], v[152:155], v[192:195], v[108:111]
	v_mfma_f32_16x16x32_bf16 v[96:99], v[144:147], v[204:207], v[96:99]
	v_mfma_f32_16x16x32_bf16 v[92:95], v[152:155], v[204:207], v[92:95]
	v_mfma_f32_16x16x32_bf16 v[80:83], v[144:147], v[212:215], v[80:83]
	v_mfma_f32_16x16x32_bf16 v[76:79], v[152:155], v[212:215], v[76:79]
	v_mfma_f32_16x16x32_bf16 v[128:131], v[148:151], v[188:191], v[128:131]
	v_mfma_f32_16x16x32_bf16 v[124:127], v[164:167], v[188:191], v[124:127]
	v_mfma_f32_16x16x32_bf16 v[112:115], v[148:151], v[200:203], v[112:115]
	v_mfma_f32_16x16x32_bf16 v[108:111], v[164:167], v[200:203], v[108:111]
	v_mfma_f32_16x16x32_bf16 v[96:99], v[148:151], v[208:211], v[96:99]
	v_mfma_f32_16x16x32_bf16 v[92:95], v[164:167], v[208:211], v[92:95]
	v_mfma_f32_16x16x32_bf16 v[80:83], v[148:151], v[216:219], v[80:83]
	v_mfma_f32_16x16x32_bf16 v[76:79], v[164:167], v[216:219], v[76:79]
	s_setprio 0
	s_setprio 1
	v_mfma_f32_16x16x32_bf16 v[120:123], v[168:171], v[184:187], v[120:123]
	v_mfma_f32_16x16x32_bf16 v[116:119], v[176:179], v[184:187], v[116:119]
	v_mfma_f32_16x16x32_bf16 v[104:107], v[168:171], v[192:195], v[104:107]
	v_mfma_f32_16x16x32_bf16 v[100:103], v[176:179], v[192:195], v[100:103]
	v_mfma_f32_16x16x32_bf16 v[88:91], v[168:171], v[204:207], v[88:91]
	v_mfma_f32_16x16x32_bf16 v[84:87], v[176:179], v[204:207], v[84:87]
	v_mfma_f32_16x16x32_bf16 v[72:75], v[168:171], v[212:215], v[72:75]
	v_mfma_f32_16x16x32_bf16 v[68:71], v[176:179], v[212:215], v[68:71]
	v_mfma_f32_16x16x32_bf16 v[120:123], v[172:175], v[188:191], v[120:123]
	v_mfma_f32_16x16x32_bf16 v[116:119], v[180:183], v[188:191], v[116:119]
	v_mfma_f32_16x16x32_bf16 v[104:107], v[172:175], v[200:203], v[104:107]
	v_mfma_f32_16x16x32_bf16 v[100:103], v[180:183], v[200:203], v[100:103]
	v_mfma_f32_16x16x32_bf16 v[88:91], v[172:175], v[208:211], v[88:91]
	v_mfma_f32_16x16x32_bf16 v[84:87], v[180:183], v[208:211], v[84:87]
	v_mfma_f32_16x16x32_bf16 v[72:75], v[172:175], v[216:219], v[72:75]
	v_mfma_f32_16x16x32_bf16 v[68:71], v[180:183], v[216:219], v[68:71]
	s_barrier
	s_setprio 0
	s_add_i32 s6, s49, s47
	v_lshl_add_u64 v[156:157], s[30:31], 0, v[136:137]
	s_mov_b32 m0, s6
	ds_read_b128 v[184:187], v163 offset:16384
	ds_read_b128 v[188:191], v163 offset:17408
	ds_read_b128 v[192:195], v163 offset:18432
	ds_read_b128 v[200:203], v163 offset:19456
	ds_read_b128 v[204:207], v163 offset:20480
	ds_read_b128 v[208:211], v163 offset:21504
	ds_read_b128 v[212:215], v163 offset:22528
	ds_read_b128 v[216:219], v163 offset:23552
	global_load_lds_dwordx4 v[156:157], off
	s_add_i32 m0, s6, 0x2000
	s_add_u32 s54, s30, 0x80000
	v_lshl_add_u64 v[220:221], s[30:31], 0, v[132:133]
	s_addc_u32 s55, s31, 0
	s_add_i32 s0, s0, s47
	global_load_lds_dwordx4 v[220:221], off
	v_lshl_add_u64 v[222:223], s[54:55], 0, v[136:137]
	s_mov_b32 m0, s0
	v_lshl_add_u64 v[224:225], s[34:35], 0, v[134:135]
	global_load_lds_dwordx4 v[222:223], off
	v_lshl_add_u64 v[222:223], s[54:55], 0, v[132:133]
	s_add_i32 m0, s0, 0x2000
	s_nop 0
	global_load_lds_dwordx4 v[222:223], off
	v_lshl_add_u64 v[222:223], s[34:35], 0, v[138:139]
	s_mov_b32 m0, s45
	s_nop 0
	global_load_lds_dwordx4 v[222:223], off
	s_mov_b32 m0, s61
	s_nop 0
	global_load_lds_dwordx4 v[224:225], off
	s_waitcnt vmcnt(8)
	s_waitcnt lgkmcnt(0)
	s_setprio 1
	s_barrier
	v_mfma_f32_16x16x32_bf16 v[64:67], v[144:147], v[184:187], v[64:67]
	v_mfma_f32_16x16x32_bf16 v[60:63], v[152:155], v[184:187], v[60:63]
	v_mfma_f32_16x16x32_bf16 v[48:51], v[144:147], v[192:195], v[48:51]
	v_mfma_f32_16x16x32_bf16 v[44:47], v[152:155], v[192:195], v[44:47]
	v_mfma_f32_16x16x32_bf16 v[32:35], v[144:147], v[204:207], v[32:35]
	v_mfma_f32_16x16x32_bf16 v[28:31], v[152:155], v[204:207], v[28:31]
	v_mfma_f32_16x16x32_bf16 v[16:19], v[144:147], v[212:215], v[16:19]
	v_mfma_f32_16x16x32_bf16 v[12:15], v[152:155], v[212:215], v[12:15]
	v_mfma_f32_16x16x32_bf16 v[64:67], v[148:151], v[188:191], v[64:67]
	v_mfma_f32_16x16x32_bf16 v[60:63], v[164:167], v[188:191], v[60:63]
	v_mfma_f32_16x16x32_bf16 v[48:51], v[148:151], v[200:203], v[48:51]
	v_mfma_f32_16x16x32_bf16 v[44:47], v[164:167], v[200:203], v[44:47]
	v_mfma_f32_16x16x32_bf16 v[32:35], v[148:151], v[208:211], v[32:35]
	v_mfma_f32_16x16x32_bf16 v[28:31], v[164:167], v[208:211], v[28:31]
	v_mfma_f32_16x16x32_bf16 v[16:19], v[148:151], v[216:219], v[16:19]
	v_mfma_f32_16x16x32_bf16 v[12:15], v[164:167], v[216:219], v[12:15]
	s_setprio 0
	s_setprio 1
	v_mfma_f32_16x16x32_bf16 v[56:59], v[168:171], v[184:187], v[56:59]
	v_mfma_f32_16x16x32_bf16 v[52:55], v[176:179], v[184:187], v[52:55]
	v_mfma_f32_16x16x32_bf16 v[40:43], v[168:171], v[192:195], v[40:43]
	v_mfma_f32_16x16x32_bf16 v[36:39], v[176:179], v[192:195], v[36:39]
	v_mfma_f32_16x16x32_bf16 v[24:27], v[168:171], v[204:207], v[24:27]
	v_mfma_f32_16x16x32_bf16 v[20:23], v[176:179], v[204:207], v[20:23]
	v_mfma_f32_16x16x32_bf16 v[8:11], v[168:171], v[212:215], v[8:11]
	v_mfma_f32_16x16x32_bf16 v[4:7], v[176:179], v[212:215], v[4:7]
	v_mfma_f32_16x16x32_bf16 v[56:59], v[172:175], v[188:191], v[56:59]
	v_mfma_f32_16x16x32_bf16 v[52:55], v[180:183], v[188:191], v[52:55]
	v_mfma_f32_16x16x32_bf16 v[40:43], v[172:175], v[200:203], v[40:43]
	v_mfma_f32_16x16x32_bf16 v[36:39], v[180:183], v[200:203], v[36:39]
	v_mfma_f32_16x16x32_bf16 v[24:27], v[172:175], v[208:211], v[24:27]
	v_mfma_f32_16x16x32_bf16 v[20:23], v[180:183], v[208:211], v[20:23]
	v_mfma_f32_16x16x32_bf16 v[8:11], v[172:175], v[216:219], v[8:11]
	v_mfma_f32_16x16x32_bf16 v[4:7], v[180:183], v[216:219], v[4:7]
	s_barrier
	s_setprio 0
	s_add_i32 s0, 0, 0x18000
	v_add_u32_e32 v158, s0, v159
	s_add_i32 s6, 0, 0x1c000
	ds_read_b128 v[144:147], v158
	ds_read_b128 v[148:151], v158 offset:1024
	ds_read_b128 v[152:155], v158 offset:2048
	ds_read_b128 v[164:167], v158 offset:3072
	v_add_u32_e32 v158, s6, v159
	ds_read_b128 v[168:171], v158
	ds_read_b128 v[172:175], v158 offset:1024
	ds_read_b128 v[176:179], v158 offset:2048
	ds_read_b128 v[180:183], v158 offset:3072
	s_add_u32 s34, s34, 0x80000
	s_addc_u32 s35, s35, 0
	s_mov_b32 m0, s62
	v_lshl_add_u64 v[226:227], s[34:35], 0, v[138:139]
	ds_read_b128 v[184:187], v163 offset:32768
	ds_read_b128 v[188:191], v163 offset:33792
	ds_read_b128 v[192:195], v163 offset:34816
	ds_read_b128 v[200:203], v163 offset:35840
	ds_read_b128 v[204:207], v163 offset:36864
	ds_read_b128 v[208:211], v163 offset:37888
	ds_read_b128 v[212:215], v163 offset:38912
	ds_read_b128 v[216:219], v163 offset:39936
	global_load_lds_dwordx4 v[226:227], off
	v_lshl_add_u64 v[226:227], s[34:35], 0, v[134:135]
	s_mov_b32 m0, s63
	s_nop 0
	global_load_lds_dwordx4 v[226:227], off
	s_waitcnt vmcnt(8)
	s_waitcnt lgkmcnt(0)
	s_setprio 1
	s_barrier
	v_mfma_f32_16x16x32_bf16 v[128:131], v[144:147], v[184:187], v[128:131]
	v_mfma_f32_16x16x32_bf16 v[124:127], v[152:155], v[184:187], v[124:127]
	v_mfma_f32_16x16x32_bf16 v[112:115], v[144:147], v[192:195], v[112:115]
	v_mfma_f32_16x16x32_bf16 v[108:111], v[152:155], v[192:195], v[108:111]
	v_mfma_f32_16x16x32_bf16 v[96:99], v[144:147], v[204:207], v[96:99]
	v_mfma_f32_16x16x32_bf16 v[92:95], v[152:155], v[204:207], v[92:95]
	v_mfma_f32_16x16x32_bf16 v[80:83], v[144:147], v[212:215], v[80:83]
	v_mfma_f32_16x16x32_bf16 v[76:79], v[152:155], v[212:215], v[76:79]
	v_mfma_f32_16x16x32_bf16 v[128:131], v[148:151], v[188:191], v[128:131]
	v_mfma_f32_16x16x32_bf16 v[124:127], v[164:167], v[188:191], v[124:127]
	v_mfma_f32_16x16x32_bf16 v[112:115], v[148:151], v[200:203], v[112:115]
	v_mfma_f32_16x16x32_bf16 v[108:111], v[164:167], v[200:203], v[108:111]
	v_mfma_f32_16x16x32_bf16 v[96:99], v[148:151], v[208:211], v[96:99]
	v_mfma_f32_16x16x32_bf16 v[92:95], v[164:167], v[208:211], v[92:95]
	v_mfma_f32_16x16x32_bf16 v[80:83], v[148:151], v[216:219], v[80:83]
	v_mfma_f32_16x16x32_bf16 v[76:79], v[164:167], v[216:219], v[76:79]
	s_setprio 0
	s_setprio 1
	v_mfma_f32_16x16x32_bf16 v[120:123], v[168:171], v[184:187], v[120:123]
	v_mfma_f32_16x16x32_bf16 v[116:119], v[176:179], v[184:187], v[116:119]
	v_mfma_f32_16x16x32_bf16 v[104:107], v[168:171], v[192:195], v[104:107]
	v_mfma_f32_16x16x32_bf16 v[100:103], v[176:179], v[192:195], v[100:103]
	v_mfma_f32_16x16x32_bf16 v[88:91], v[168:171], v[204:207], v[88:91]
	v_mfma_f32_16x16x32_bf16 v[84:87], v[176:179], v[204:207], v[84:87]
	v_mfma_f32_16x16x32_bf16 v[72:75], v[168:171], v[212:215], v[72:75]
	v_mfma_f32_16x16x32_bf16 v[68:71], v[176:179], v[212:215], v[68:71]
	v_mfma_f32_16x16x32_bf16 v[120:123], v[172:175], v[188:191], v[120:123]
	v_mfma_f32_16x16x32_bf16 v[116:119], v[180:183], v[188:191], v[116:119]
	v_mfma_f32_16x16x32_bf16 v[104:107], v[172:175], v[200:203], v[104:107]
	v_mfma_f32_16x16x32_bf16 v[100:103], v[180:183], v[200:203], v[100:103]
	v_mfma_f32_16x16x32_bf16 v[88:91], v[172:175], v[208:211], v[88:91]
	v_mfma_f32_16x16x32_bf16 v[84:87], v[180:183], v[208:211], v[84:87]
	v_mfma_f32_16x16x32_bf16 v[72:75], v[172:175], v[216:219], v[72:75]
	v_mfma_f32_16x16x32_bf16 v[68:71], v[180:183], v[216:219], v[68:71]
	s_barrier
	s_setprio 0
	s_add_i32 s0, s0, s47
	v_lshl_add_u64 v[156:157], v[156:157], 0, s[90:91]
	s_mov_b32 m0, s0
	ds_read_b128 v[184:187], v163 offset:49152
	ds_read_b128 v[188:191], v163 offset:50176
	ds_read_b128 v[192:195], v163 offset:51200
	ds_read_b128 v[200:203], v163 offset:52224
	ds_read_b128 v[204:207], v163 offset:53248
	ds_read_b128 v[208:211], v163 offset:54272
	ds_read_b128 v[212:215], v163 offset:55296
	ds_read_b128 v[216:219], v163 offset:56320
	global_load_lds_dwordx4 v[156:157], off
	s_add_i32 m0, s0, 0x2000
	s_add_u32 s30, s30, 0x80080
	v_lshl_add_u64 v[156:157], v[220:221], 0, s[90:91]
	s_addc_u32 s31, s31, 0
	s_add_i32 s0, s6, s47
	global_load_lds_dwordx4 v[156:157], off
	v_lshl_add_u64 v[156:157], s[30:31], 0, v[136:137]
	s_mov_b32 m0, s0
	s_nop 0
	global_load_lds_dwordx4 v[156:157], off
	v_lshl_add_u64 v[156:157], s[30:31], 0, v[132:133]
	s_add_i32 m0, s0, 0x2000
	s_nop 0
	global_load_lds_dwordx4 v[156:157], off
	v_lshl_add_u64 v[156:157], v[222:223], 0, s[90:91]
	s_mov_b32 m0, s51
	s_nop 0
	global_load_lds_dwordx4 v[156:157], off
	v_lshl_add_u64 v[156:157], v[224:225], 0, s[90:91]
	s_mov_b32 m0, s4
	s_nop 0
	global_load_lds_dwordx4 v[156:157], off
	s_waitcnt vmcnt(8)
	s_waitcnt lgkmcnt(0)
	s_setprio 1
	s_barrier
	v_mfma_f32_16x16x32_bf16 v[64:67], v[144:147], v[184:187], v[64:67]
	v_mfma_f32_16x16x32_bf16 v[60:63], v[152:155], v[184:187], v[60:63]
	v_mfma_f32_16x16x32_bf16 v[48:51], v[144:147], v[192:195], v[48:51]
	v_mfma_f32_16x16x32_bf16 v[44:47], v[152:155], v[192:195], v[44:47]
	v_mfma_f32_16x16x32_bf16 v[32:35], v[144:147], v[204:207], v[32:35]
	v_mfma_f32_16x16x32_bf16 v[28:31], v[152:155], v[204:207], v[28:31]
	v_mfma_f32_16x16x32_bf16 v[16:19], v[144:147], v[212:215], v[16:19]
	v_mfma_f32_16x16x32_bf16 v[12:15], v[152:155], v[212:215], v[12:15]
	v_mfma_f32_16x16x32_bf16 v[64:67], v[148:151], v[188:191], v[64:67]
	v_mfma_f32_16x16x32_bf16 v[60:63], v[164:167], v[188:191], v[60:63]
	v_mfma_f32_16x16x32_bf16 v[48:51], v[148:151], v[200:203], v[48:51]
	v_mfma_f32_16x16x32_bf16 v[44:47], v[164:167], v[200:203], v[44:47]
	v_mfma_f32_16x16x32_bf16 v[32:35], v[148:151], v[208:211], v[32:35]
	v_mfma_f32_16x16x32_bf16 v[28:31], v[164:167], v[208:211], v[28:31]
	v_mfma_f32_16x16x32_bf16 v[16:19], v[148:151], v[216:219], v[16:19]
	v_mfma_f32_16x16x32_bf16 v[12:15], v[164:167], v[216:219], v[12:15]
	s_setprio 0
	s_setprio 1
	v_mfma_f32_16x16x32_bf16 v[56:59], v[168:171], v[184:187], v[56:59]
	v_mfma_f32_16x16x32_bf16 v[52:55], v[176:179], v[184:187], v[52:55]
	v_mfma_f32_16x16x32_bf16 v[40:43], v[168:171], v[192:195], v[40:43]
	v_mfma_f32_16x16x32_bf16 v[36:39], v[176:179], v[192:195], v[36:39]
	v_mfma_f32_16x16x32_bf16 v[24:27], v[168:171], v[204:207], v[24:27]
	v_mfma_f32_16x16x32_bf16 v[20:23], v[176:179], v[204:207], v[20:23]
	v_mfma_f32_16x16x32_bf16 v[8:11], v[168:171], v[212:215], v[8:11]
	v_mfma_f32_16x16x32_bf16 v[4:7], v[176:179], v[212:215], v[4:7]
	v_mfma_f32_16x16x32_bf16 v[56:59], v[172:175], v[188:191], v[56:59]
	v_mfma_f32_16x16x32_bf16 v[52:55], v[180:183], v[188:191], v[52:55]
	v_mfma_f32_16x16x32_bf16 v[40:43], v[172:175], v[200:203], v[40:43]
	v_mfma_f32_16x16x32_bf16 v[36:39], v[180:183], v[200:203], v[36:39]
	v_mfma_f32_16x16x32_bf16 v[24:27], v[172:175], v[208:211], v[24:27]
	v_mfma_f32_16x16x32_bf16 v[20:23], v[180:183], v[208:211], v[20:23]
	v_mfma_f32_16x16x32_bf16 v[8:11], v[172:175], v[216:219], v[8:11]
	v_mfma_f32_16x16x32_bf16 v[4:7], v[180:183], v[216:219], v[4:7]
	s_barrier
	s_setprio 0
	s_add_i32 s50, s50, 2
	s_add_u32 s36, s36, 0x100
	s_addc_u32 s37, s37, 0
	s_add_u32 s38, s38, 0x100
	s_addc_u32 s39, s39, 0
	s_cmp_gt_u32 s50, 29
	s_cbranch_scc0 .LBB0_336
	s_and_b64 vcc, exec, s[22:23]
	s_cbranch_vccz .LBB0_339
	s_barrier

.LBB0_747:
	s_add_i32 s0, s6, 2
	s_add_u32 s25, s66, 0xfffc0080
	s_addc_u32 s29, s67, -1
	s_add_i32 s33, 0, 0x10000
	s_cmp_eq_u32 s13, s6
	s_cselect_b32 s35, s45, s29
	s_cselect_b32 s34, s44, s25
	v_add_u32_e32 v3, s33, v237
	s_cselect_b32 s31, s61, s24
	s_cselect_b32 s30, s60, s15
	s_add_i32 s6, 0, 0x14000
	ds_read_b128 v[146:149], v3
	ds_read_b128 v[150:153], v3 offset:1024
	ds_read_b128 v[154:157], v3 offset:2048
	ds_read_b128 v[158:161], v3 offset:3072
	v_add_u32_e32 v3, s6, v237
	ds_read_b128 v[162:165], v3
	ds_read_b128 v[166:169], v3 offset:1024
	ds_read_b128 v[170:173], v3 offset:2048
	ds_read_b128 v[174:177], v3 offset:3072
	v_lshl_add_u64 v[4:5], s[66:67], 0, v[142:143]
	s_add_i32 m0, s52, 0xc000
	ds_read_b128 v[178:181], v249
	ds_read_b128 v[182:185], v249 offset:1024
	ds_read_b128 v[186:189], v249 offset:2048
	ds_read_b128 v[190:193], v249 offset:3072
	ds_read_b128 v[200:203], v249 offset:4096
	ds_read_b128 v[204:207], v249 offset:5120
	ds_read_b128 v[208:211], v249 offset:6144
	ds_read_b128 v[212:215], v249 offset:7168
	global_load_lds_dwordx4 v[4:5], off
	v_lshl_add_u64 v[4:5], s[66:67], 0, v[144:145]
	s_add_i32 m0, s52, 0xe000
	s_nop 0
	global_load_lds_dwordx4 v[4:5], off
	s_waitcnt vmcnt(8)
	s_waitcnt lgkmcnt(0)
	s_setprio 1
	s_barrier
	v_mfma_f32_16x16x32_bf16 v[130:133], v[146:149], v[178:181], v[130:133]
	v_mfma_f32_16x16x32_bf16 v[126:129], v[154:157], v[178:181], v[126:129]
	v_mfma_f32_16x16x32_bf16 v[122:125], v[146:149], v[186:189], v[122:125]
	v_mfma_f32_16x16x32_bf16 v[118:121], v[154:157], v[186:189], v[118:121]
	v_mfma_f32_16x16x32_bf16 v[114:117], v[146:149], v[200:203], v[114:117]
	v_mfma_f32_16x16x32_bf16 v[110:113], v[154:157], v[200:203], v[110:113]
	v_mfma_f32_16x16x32_bf16 v[106:109], v[146:149], v[208:211], v[106:109]
	v_mfma_f32_16x16x32_bf16 v[102:105], v[154:157], v[208:211], v[102:105]
	v_mfma_f32_16x16x32_bf16 v[130:133], v[150:153], v[182:185], v[130:133]
	v_mfma_f32_16x16x32_bf16 v[126:129], v[158:161], v[182:185], v[126:129]
	v_mfma_f32_16x16x32_bf16 v[122:125], v[150:153], v[190:193], v[122:125]
	v_mfma_f32_16x16x32_bf16 v[118:121], v[158:161], v[190:193], v[118:121]
	v_mfma_f32_16x16x32_bf16 v[114:117], v[150:153], v[204:207], v[114:117]
	v_mfma_f32_16x16x32_bf16 v[110:113], v[158:161], v[204:207], v[110:113]
	v_mfma_f32_16x16x32_bf16 v[106:109], v[150:153], v[212:215], v[106:109]
	v_mfma_f32_16x16x32_bf16 v[102:105], v[158:161], v[212:215], v[102:105]
	s_setprio 0
	s_setprio 1
	v_mfma_f32_16x16x32_bf16 v[98:101], v[162:165], v[178:181], v[98:101]
	v_mfma_f32_16x16x32_bf16 v[94:97], v[170:173], v[178:181], v[94:97]
	v_mfma_f32_16x16x32_bf16 v[90:93], v[162:165], v[186:189], v[90:93]
	v_mfma_f32_16x16x32_bf16 v[86:89], v[170:173], v[186:189], v[86:89]
	v_mfma_f32_16x16x32_bf16 v[82:85], v[162:165], v[200:203], v[82:85]
	v_mfma_f32_16x16x32_bf16 v[78:81], v[170:173], v[200:203], v[78:81]
	v_mfma_f32_16x16x32_bf16 v[74:77], v[162:165], v[208:211], v[74:77]
	v_mfma_f32_16x16x32_bf16 v[70:73], v[170:173], v[208:211], v[70:73]
	v_mfma_f32_16x16x32_bf16 v[98:101], v[166:169], v[182:185], v[98:101]
	v_mfma_f32_16x16x32_bf16 v[94:97], v[174:177], v[182:185], v[94:97]
	v_mfma_f32_16x16x32_bf16 v[90:93], v[166:169], v[190:193], v[90:93]
	v_mfma_f32_16x16x32_bf16 v[86:89], v[174:177], v[190:193], v[86:89]
	v_mfma_f32_16x16x32_bf16 v[82:85], v[166:169], v[204:207], v[82:85]
	v_mfma_f32_16x16x32_bf16 v[78:81], v[174:177], v[204:207], v[78:81]
	v_mfma_f32_16x16x32_bf16 v[74:77], v[166:169], v[212:215], v[74:77]
	v_mfma_f32_16x16x32_bf16 v[70:73], v[174:177], v[212:215], v[70:73]
	s_barrier
	s_setprio 0
	s_add_i32 s25, s33, s47
	v_lshl_add_u64 v[194:195], s[30:31], 0, v[136:137]
	s_mov_b32 m0, s25
	ds_read_b128 v[178:181], v249 offset:16384
	ds_read_b128 v[182:185], v249 offset:17408
	ds_read_b128 v[186:189], v249 offset:18432
	ds_read_b128 v[190:193], v249 offset:19456
	ds_read_b128 v[200:203], v249 offset:20480
	ds_read_b128 v[204:207], v249 offset:21504
	ds_read_b128 v[208:211], v249 offset:22528
	ds_read_b128 v[212:215], v249 offset:23552
	global_load_lds_dwordx4 v[194:195], off
	s_add_i32 m0, s25, 0x2000
	s_add_u32 s36, s30, 0x40000
	v_lshl_add_u64 v[216:217], s[30:31], 0, v[140:141]
	s_addc_u32 s37, s31, 0
	s_add_i32 s6, s6, s47
	global_load_lds_dwordx4 v[216:217], off
	v_lshl_add_u64 v[4:5], s[36:37], 0, v[136:137]
	s_mov_b32 m0, s6
	v_lshl_add_u64 v[218:219], s[34:35], 0, v[134:135]
	global_load_lds_dwordx4 v[4:5], off
	v_lshl_add_u64 v[4:5], s[36:37], 0, v[140:141]
	s_add_i32 m0, s6, 0x2000
	v_lshl_add_u64 v[220:221], s[34:35], 0, v[138:139]
	global_load_lds_dwordx4 v[4:5], off
	s_mov_b32 m0, s52
	s_nop 0
	global_load_lds_dwordx4 v[218:219], off
	s_mov_b32 m0, s53
	s_nop 0
	global_load_lds_dwordx4 v[220:221], off
	s_waitcnt vmcnt(8)
	s_waitcnt lgkmcnt(0)
	s_setprio 1
	s_barrier
	v_mfma_f32_16x16x32_bf16 v[66:69], v[146:149], v[178:181], v[66:69]
	v_mfma_f32_16x16x32_bf16 v[62:65], v[154:157], v[178:181], v[62:65]
	v_mfma_f32_16x16x32_bf16 v[58:61], v[146:149], v[186:189], v[58:61]
	v_mfma_f32_16x16x32_bf16 v[54:57], v[154:157], v[186:189], v[54:57]
	v_mfma_f32_16x16x32_bf16 v[50:53], v[146:149], v[200:203], v[50:53]
	v_mfma_f32_16x16x32_bf16 v[46:49], v[154:157], v[200:203], v[46:49]
	v_mfma_f32_16x16x32_bf16 v[42:45], v[146:149], v[208:211], v[42:45]
	v_mfma_f32_16x16x32_bf16 v[38:41], v[154:157], v[208:211], v[38:41]
	v_mfma_f32_16x16x32_bf16 v[66:69], v[150:153], v[182:185], v[66:69]
	v_mfma_f32_16x16x32_bf16 v[62:65], v[158:161], v[182:185], v[62:65]
	v_mfma_f32_16x16x32_bf16 v[58:61], v[150:153], v[190:193], v[58:61]
	v_mfma_f32_16x16x32_bf16 v[54:57], v[158:161], v[190:193], v[54:57]
	v_mfma_f32_16x16x32_bf16 v[50:53], v[150:153], v[204:207], v[50:53]
	v_mfma_f32_16x16x32_bf16 v[46:49], v[158:161], v[204:207], v[46:49]
	v_mfma_f32_16x16x32_bf16 v[42:45], v[150:153], v[212:215], v[42:45]
	v_mfma_f32_16x16x32_bf16 v[38:41], v[158:161], v[212:215], v[38:41]
	s_setprio 0
	s_setprio 1
	v_mfma_f32_16x16x32_bf16 v[34:37], v[162:165], v[178:181], v[34:37]
	v_mfma_f32_16x16x32_bf16 v[30:33], v[170:173], v[178:181], v[30:33]
	v_mfma_f32_16x16x32_bf16 v[26:29], v[162:165], v[186:189], v[26:29]
	v_mfma_f32_16x16x32_bf16 v[22:25], v[170:173], v[186:189], v[22:25]
	v_mfma_f32_16x16x32_bf16 v[18:21], v[162:165], v[200:203], v[18:21]
	v_mfma_f32_16x16x32_bf16 v[14:17], v[170:173], v[200:203], v[14:17]
	v_mfma_f32_16x16x32_bf16 v[10:13], v[162:165], v[208:211], v[10:13]
	v_mfma_f32_16x16x32_bf16 v[4:7], v[170:173], v[208:211], v[6:9]
	v_mfma_f32_16x16x32_bf16 v[34:37], v[166:169], v[182:185], v[34:37]
	v_mfma_f32_16x16x32_bf16 v[30:33], v[174:177], v[182:185], v[30:33]
	v_mfma_f32_16x16x32_bf16 v[26:29], v[166:169], v[190:193], v[26:29]
	v_mfma_f32_16x16x32_bf16 v[22:25], v[174:177], v[190:193], v[22:25]
	v_mfma_f32_16x16x32_bf16 v[18:21], v[166:169], v[204:207], v[18:21]
	v_mfma_f32_16x16x32_bf16 v[14:17], v[174:177], v[204:207], v[14:17]
	v_mfma_f32_16x16x32_bf16 v[10:13], v[166:169], v[212:215], v[10:13]
	v_mfma_f32_16x16x32_bf16 v[4:7], v[174:177], v[212:215], v[4:7]
	s_barrier
	s_setprio 0
	s_add_i32 s6, 0, 0x18000
	v_add_u32_e32 v3, s6, v237
	s_add_i32 s25, 0, 0x1c000
	ds_read_b128 v[146:149], v3
	ds_read_b128 v[150:153], v3 offset:1024
	ds_read_b128 v[154:157], v3 offset:2048
	ds_read_b128 v[158:161], v3 offset:3072
	v_add_u32_e32 v3, s25, v237
	ds_read_b128 v[162:165], v3
	ds_read_b128 v[166:169], v3 offset:1024
	ds_read_b128 v[170:173], v3 offset:2048
	ds_read_b128 v[174:177], v3 offset:3072
	s_add_u32 s34, s34, 0x40000
	s_addc_u32 s35, s35, 0
	s_mov_b32 m0, s59
	v_lshl_add_u64 v[8:9], s[34:35], 0, v[134:135]
	ds_read_b128 v[178:181], v249 offset:32768
	ds_read_b128 v[182:185], v249 offset:33792
	ds_read_b128 v[186:189], v249 offset:34816
	ds_read_b128 v[190:193], v249 offset:35840
	ds_read_b128 v[200:203], v249 offset:36864
	ds_read_b128 v[204:207], v249 offset:37888
	ds_read_b128 v[208:211], v249 offset:38912
	ds_read_b128 v[212:215], v249 offset:39936
	global_load_lds_dwordx4 v[8:9], off
	v_lshl_add_u64 v[8:9], s[34:35], 0, v[138:139]
	s_mov_b32 m0, s63
	s_nop 0
	global_load_lds_dwordx4 v[8:9], off
	s_waitcnt vmcnt(8)
	s_waitcnt lgkmcnt(0)
	s_setprio 1
	s_barrier
	v_mfma_f32_16x16x32_bf16 v[130:133], v[146:149], v[178:181], v[130:133]
	v_mfma_f32_16x16x32_bf16 v[126:129], v[154:157], v[178:181], v[126:129]
	v_mfma_f32_16x16x32_bf16 v[122:125], v[146:149], v[186:189], v[122:125]
	v_mfma_f32_16x16x32_bf16 v[118:121], v[154:157], v[186:189], v[118:121]
	v_mfma_f32_16x16x32_bf16 v[114:117], v[146:149], v[200:203], v[114:117]
	v_mfma_f32_16x16x32_bf16 v[110:113], v[154:157], v[200:203], v[110:113]
	v_mfma_f32_16x16x32_bf16 v[106:109], v[146:149], v[208:211], v[106:109]
	v_mfma_f32_16x16x32_bf16 v[102:105], v[154:157], v[208:211], v[102:105]
	v_mfma_f32_16x16x32_bf16 v[130:133], v[150:153], v[182:185], v[130:133]
	v_mfma_f32_16x16x32_bf16 v[126:129], v[158:161], v[182:185], v[126:129]
	v_mfma_f32_16x16x32_bf16 v[122:125], v[150:153], v[190:193], v[122:125]
	v_mfma_f32_16x16x32_bf16 v[118:121], v[158:161], v[190:193], v[118:121]
	v_mfma_f32_16x16x32_bf16 v[114:117], v[150:153], v[204:207], v[114:117]
	v_mfma_f32_16x16x32_bf16 v[110:113], v[158:161], v[204:207], v[110:113]
	v_mfma_f32_16x16x32_bf16 v[106:109], v[150:153], v[212:215], v[106:109]
	v_mfma_f32_16x16x32_bf16 v[102:105], v[158:161], v[212:215], v[102:105]
	s_setprio 0
	s_setprio 1
	v_mfma_f32_16x16x32_bf16 v[98:101], v[162:165], v[178:181], v[98:101]
	v_mfma_f32_16x16x32_bf16 v[94:97], v[170:173], v[178:181], v[94:97]
	v_mfma_f32_16x16x32_bf16 v[90:93], v[162:165], v[186:189], v[90:93]
	v_mfma_f32_16x16x32_bf16 v[86:89], v[170:173], v[186:189], v[86:89]
	v_mfma_f32_16x16x32_bf16 v[82:85], v[162:165], v[200:203], v[82:85]
	v_mfma_f32_16x16x32_bf16 v[78:81], v[170:173], v[200:203], v[78:81]
	v_mfma_f32_16x16x32_bf16 v[74:77], v[162:165], v[208:211], v[74:77]
	v_mfma_f32_16x16x32_bf16 v[70:73], v[170:173], v[208:211], v[70:73]
	v_mfma_f32_16x16x32_bf16 v[98:101], v[166:169], v[182:185], v[98:101]
	v_mfma_f32_16x16x32_bf16 v[94:97], v[174:177], v[182:185], v[94:97]
	v_mfma_f32_16x16x32_bf16 v[90:93], v[166:169], v[190:193], v[90:93]
	v_mfma_f32_16x16x32_bf16 v[86:89], v[174:177], v[190:193], v[86:89]
	v_mfma_f32_16x16x32_bf16 v[82:85], v[166:169], v[204:207], v[82:85]
	v_mfma_f32_16x16x32_bf16 v[78:81], v[174:177], v[204:207], v[78:81]
	v_mfma_f32_16x16x32_bf16 v[74:77], v[166:169], v[212:215], v[74:77]
	v_mfma_f32_16x16x32_bf16 v[70:73], v[174:177], v[212:215], v[70:73]
	s_barrier
	s_setprio 0
	s_add_i32 s6, s6, s47
	v_lshl_add_u64 v[8:9], v[194:195], 0, s[90:91]
	s_mov_b32 m0, s6
	ds_read_b128 v[178:181], v249 offset:49152
	ds_read_b128 v[182:185], v249 offset:50176
	ds_read_b128 v[186:189], v249 offset:51200
	ds_read_b128 v[190:193], v249 offset:52224
	ds_read_b128 v[200:203], v249 offset:53248
	ds_read_b128 v[204:207], v249 offset:54272
	ds_read_b128 v[208:211], v249 offset:55296
	ds_read_b128 v[212:215], v249 offset:56320
	global_load_lds_dwordx4 v[8:9], off
	s_add_i32 m0, s6, 0x2000
	s_add_u32 s30, s30, 0x40080
	v_lshl_add_u64 v[8:9], v[216:217], 0, s[90:91]
	s_addc_u32 s31, s31, 0
	s_add_i32 s6, s25, s47
	global_load_lds_dwordx4 v[8:9], off
	v_lshl_add_u64 v[8:9], s[30:31], 0, v[136:137]
	s_mov_b32 m0, s6
	s_nop 0
	global_load_lds_dwordx4 v[8:9], off
	v_lshl_add_u64 v[8:9], s[30:31], 0, v[140:141]
	s_add_i32 m0, s6, 0x2000
	s_nop 0
	global_load_lds_dwordx4 v[8:9], off
	v_lshl_add_u64 v[8:9], v[218:219], 0, s[90:91]
	s_mov_b32 m0, s80
	s_nop 0
	global_load_lds_dwordx4 v[8:9], off
	v_lshl_add_u64 v[8:9], v[220:221], 0, s[90:91]
	s_mov_b32 m0, s81
	s_nop 0
	global_load_lds_dwordx4 v[8:9], off
	s_waitcnt vmcnt(8)
	s_waitcnt lgkmcnt(0)
	s_setprio 1
	s_barrier
	v_mfma_f32_16x16x32_bf16 v[66:69], v[146:149], v[178:181], v[66:69]
	v_mfma_f32_16x16x32_bf16 v[62:65], v[154:157], v[178:181], v[62:65]
	v_mfma_f32_16x16x32_bf16 v[58:61], v[146:149], v[186:189], v[58:61]
	v_mfma_f32_16x16x32_bf16 v[54:57], v[154:157], v[186:189], v[54:57]
	v_mfma_f32_16x16x32_bf16 v[50:53], v[146:149], v[200:203], v[50:53]
	v_mfma_f32_16x16x32_bf16 v[46:49], v[154:157], v[200:203], v[46:49]
	v_mfma_f32_16x16x32_bf16 v[42:45], v[146:149], v[208:211], v[42:45]
	v_mfma_f32_16x16x32_bf16 v[38:41], v[154:157], v[208:211], v[38:41]
	v_mfma_f32_16x16x32_bf16 v[66:69], v[150:153], v[182:185], v[66:69]
	v_mfma_f32_16x16x32_bf16 v[62:65], v[158:161], v[182:185], v[62:65]
	v_mfma_f32_16x16x32_bf16 v[58:61], v[150:153], v[190:193], v[58:61]
	v_mfma_f32_16x16x32_bf16 v[54:57], v[158:161], v[190:193], v[54:57]
	v_mfma_f32_16x16x32_bf16 v[50:53], v[150:153], v[204:207], v[50:53]
	v_mfma_f32_16x16x32_bf16 v[46:49], v[158:161], v[204:207], v[46:49]
	v_mfma_f32_16x16x32_bf16 v[42:45], v[150:153], v[212:215], v[42:45]
	v_mfma_f32_16x16x32_bf16 v[38:41], v[158:161], v[212:215], v[38:41]
	s_setprio 0
	s_setprio 1
	v_mfma_f32_16x16x32_bf16 v[34:37], v[162:165], v[178:181], v[34:37]
	v_mfma_f32_16x16x32_bf16 v[30:33], v[170:173], v[178:181], v[30:33]
	v_mfma_f32_16x16x32_bf16 v[26:29], v[162:165], v[186:189], v[26:29]
	v_mfma_f32_16x16x32_bf16 v[22:25], v[170:173], v[186:189], v[22:25]
	v_mfma_f32_16x16x32_bf16 v[18:21], v[162:165], v[200:203], v[18:21]
	v_mfma_f32_16x16x32_bf16 v[14:17], v[170:173], v[200:203], v[14:17]
	v_mfma_f32_16x16x32_bf16 v[8:11], v[162:165], v[208:211], v[10:13]
	v_mfma_f32_16x16x32_bf16 v[4:7], v[170:173], v[208:211], v[4:7]
	v_mfma_f32_16x16x32_bf16 v[34:37], v[166:169], v[182:185], v[34:37]
	v_mfma_f32_16x16x32_bf16 v[30:33], v[174:177], v[182:185], v[30:33]
	v_mfma_f32_16x16x32_bf16 v[26:29], v[166:169], v[190:193], v[26:29]
	v_mfma_f32_16x16x32_bf16 v[22:25], v[174:177], v[190:193], v[22:25]
	v_mfma_f32_16x16x32_bf16 v[18:21], v[166:169], v[204:207], v[18:21]
	v_mfma_f32_16x16x32_bf16 v[14:17], v[174:177], v[204:207], v[14:17]
	v_mfma_f32_16x16x32_bf16 v[10:13], v[166:169], v[212:215], v[8:11]
	v_mfma_f32_16x16x32_bf16 v[6:9], v[174:177], v[212:215], v[4:7]
	s_barrier
	s_setprio 0
	s_add_u32 s66, s66, 0x100
	s_addc_u32 s67, s67, 0
	s_add_u32 s15, s15, 0x100
	s_addc_u32 s24, s24, 0
	s_cmp_ge_i32 s0, s1
	s_mov_b32 s6, s0
	s_cbranch_scc0 .LBB0_747

.LBB0_967:
	s_add_u32 s0, s36, 0xfff80080
	s_addc_u32 s6, s37, -1
	s_add_i32 s49, 0, 0x10000
	s_cmp_eq_u32 s55, 28
	s_cselect_b32 s35, s65, s6
	s_cselect_b32 s34, s64, s0
	s_cselect_b32 s31, s67, s39
	s_cselect_b32 s30, s66, s38
	s_add_i32 s0, 0, 0x14000
	v_add_u32_e32 v144, s49, v3
	v_add_u32_e32 v160, s0, v3
	ds_read_b128 v[124:127], v144
	ds_read_b128 v[128:131], v144 offset:1024
	ds_read_b128 v[140:143], v144 offset:2048
	ds_read_b128 v[144:147], v144 offset:3072
	ds_read_b128 v[148:151], v160
	ds_read_b128 v[152:155], v160 offset:1024
	ds_read_b128 v[156:159], v160 offset:2048
	ds_read_b128 v[160:163], v160 offset:3072
	v_lshl_add_u64 v[198:199], s[36:37], 0, v[212:213]
	s_add_i32 m0, s4, 0xc000
	ds_read_b128 v[164:167], v250
	ds_read_b128 v[168:171], v250 offset:1024
	ds_read_b128 v[172:175], v250 offset:2048
	ds_read_b128 v[176:179], v250 offset:3072
	ds_read_b128 v[180:183], v250 offset:4096
	ds_read_b128 v[184:187], v250 offset:5120
	ds_read_b128 v[188:191], v250 offset:6144
	ds_read_b128 v[192:195], v250 offset:7168
	global_load_lds_dwordx4 v[198:199], off
	v_lshl_add_u64 v[198:199], s[36:37], 0, v[214:215]
	s_add_i32 m0, s4, 0xe000
	s_nop 0
	global_load_lds_dwordx4 v[198:199], off
	s_waitcnt vmcnt(8)
	s_waitcnt lgkmcnt(0)
	s_setprio 1
	s_barrier
	v_mfma_f32_16x16x32_bf16 v[136:139], v[124:127], v[164:167], v[136:139]
	v_mfma_f32_16x16x32_bf16 v[132:135], v[140:143], v[164:167], v[132:135]
	v_mfma_f32_16x16x32_bf16 v[112:115], v[124:127], v[172:175], v[112:115]
	v_mfma_f32_16x16x32_bf16 v[108:111], v[140:143], v[172:175], v[108:111]
	v_mfma_f32_16x16x32_bf16 v[96:99], v[124:127], v[180:183], v[96:99]
	v_mfma_f32_16x16x32_bf16 v[92:95], v[140:143], v[180:183], v[92:95]
	v_mfma_f32_16x16x32_bf16 v[80:83], v[124:127], v[188:191], v[80:83]
	v_mfma_f32_16x16x32_bf16 v[76:79], v[140:143], v[188:191], v[76:79]
	v_mfma_f32_16x16x32_bf16 v[136:139], v[128:131], v[168:171], v[136:139]
	v_mfma_f32_16x16x32_bf16 v[132:135], v[144:147], v[168:171], v[132:135]
	v_mfma_f32_16x16x32_bf16 v[112:115], v[128:131], v[176:179], v[112:115]
	v_mfma_f32_16x16x32_bf16 v[108:111], v[144:147], v[176:179], v[108:111]
	v_mfma_f32_16x16x32_bf16 v[96:99], v[128:131], v[184:187], v[96:99]
	v_mfma_f32_16x16x32_bf16 v[92:95], v[144:147], v[184:187], v[92:95]
	v_mfma_f32_16x16x32_bf16 v[80:83], v[128:131], v[192:195], v[80:83]
	v_mfma_f32_16x16x32_bf16 v[76:79], v[144:147], v[192:195], v[76:79]
	s_setprio 0
	s_setprio 1
	v_mfma_f32_16x16x32_bf16 v[120:123], v[148:151], v[164:167], v[120:123]
	v_mfma_f32_16x16x32_bf16 v[116:119], v[156:159], v[164:167], v[116:119]
	v_mfma_f32_16x16x32_bf16 v[104:107], v[148:151], v[172:175], v[104:107]
	v_mfma_f32_16x16x32_bf16 v[100:103], v[156:159], v[172:175], v[100:103]
	v_mfma_f32_16x16x32_bf16 v[88:91], v[148:151], v[180:183], v[88:91]
	v_mfma_f32_16x16x32_bf16 v[84:87], v[156:159], v[180:183], v[84:87]
	v_mfma_f32_16x16x32_bf16 v[72:75], v[148:151], v[188:191], v[72:75]
	v_mfma_f32_16x16x32_bf16 v[68:71], v[156:159], v[188:191], v[68:71]
	v_mfma_f32_16x16x32_bf16 v[120:123], v[152:155], v[168:171], v[120:123]
	v_mfma_f32_16x16x32_bf16 v[116:119], v[160:163], v[168:171], v[116:119]
	v_mfma_f32_16x16x32_bf16 v[104:107], v[152:155], v[176:179], v[104:107]
	v_mfma_f32_16x16x32_bf16 v[100:103], v[160:163], v[176:179], v[100:103]
	v_mfma_f32_16x16x32_bf16 v[88:91], v[152:155], v[184:187], v[88:91]
	v_mfma_f32_16x16x32_bf16 v[84:87], v[160:163], v[184:187], v[84:87]
	v_mfma_f32_16x16x32_bf16 v[72:75], v[152:155], v[192:195], v[72:75]
	v_mfma_f32_16x16x32_bf16 v[68:71], v[160:163], v[192:195], v[68:71]
	s_barrier
	s_setprio 0
	s_add_i32 s6, s49, s1
	v_lshl_add_u64 v[198:199], s[30:31], 0, v[204:205]
	s_mov_b32 m0, s6
	ds_read_b128 v[164:167], v250 offset:16384
	ds_read_b128 v[168:171], v250 offset:17408
	ds_read_b128 v[172:175], v250 offset:18432
	ds_read_b128 v[176:179], v250 offset:19456
	ds_read_b128 v[180:183], v250 offset:20480
	ds_read_b128 v[184:187], v250 offset:21504
	ds_read_b128 v[188:191], v250 offset:22528
	ds_read_b128 v[192:195], v250 offset:23552
	global_load_lds_dwordx4 v[198:199], off
	s_add_i32 m0, s6, 0x2000
	s_add_u32 s68, s30, 0x80000
	v_lshl_add_u64 v[216:217], s[30:31], 0, v[200:201]
	s_addc_u32 s69, s31, 0
	s_add_i32 s0, s0, s1
	global_load_lds_dwordx4 v[216:217], off
	v_lshl_add_u64 v[218:219], s[68:69], 0, v[204:205]
	s_mov_b32 m0, s0
	v_lshl_add_u64 v[220:221], s[34:35], 0, v[202:203]
	global_load_lds_dwordx4 v[218:219], off
	v_lshl_add_u64 v[218:219], s[68:69], 0, v[200:201]
	s_add_i32 m0, s0, 0x2000
	s_nop 0
	global_load_lds_dwordx4 v[218:219], off
	v_lshl_add_u64 v[218:219], s[34:35], 0, v[206:207]
	s_mov_b32 m0, s4
	s_nop 0
	global_load_lds_dwordx4 v[218:219], off
	s_mov_b32 m0, s24
	s_nop 0
	global_load_lds_dwordx4 v[220:221], off
	s_waitcnt vmcnt(8)
	s_waitcnt lgkmcnt(0)
	s_setprio 1
	s_barrier
	v_mfma_f32_16x16x32_bf16 v[64:67], v[124:127], v[164:167], v[64:67]
	v_mfma_f32_16x16x32_bf16 v[60:63], v[140:143], v[164:167], v[60:63]
	v_mfma_f32_16x16x32_bf16 v[48:51], v[124:127], v[172:175], v[48:51]
	v_mfma_f32_16x16x32_bf16 v[44:47], v[140:143], v[172:175], v[44:47]
	v_mfma_f32_16x16x32_bf16 v[32:35], v[124:127], v[180:183], v[32:35]
	v_mfma_f32_16x16x32_bf16 v[28:31], v[140:143], v[180:183], v[28:31]
	v_mfma_f32_16x16x32_bf16 v[16:19], v[124:127], v[188:191], v[16:19]
	v_mfma_f32_16x16x32_bf16 v[12:15], v[140:143], v[188:191], v[12:15]
	v_mfma_f32_16x16x32_bf16 v[64:67], v[128:131], v[168:171], v[64:67]
	v_mfma_f32_16x16x32_bf16 v[60:63], v[144:147], v[168:171], v[60:63]
	v_mfma_f32_16x16x32_bf16 v[48:51], v[128:131], v[176:179], v[48:51]
	v_mfma_f32_16x16x32_bf16 v[44:47], v[144:147], v[176:179], v[44:47]
	v_mfma_f32_16x16x32_bf16 v[32:35], v[128:131], v[184:187], v[32:35]
	v_mfma_f32_16x16x32_bf16 v[28:31], v[144:147], v[184:187], v[28:31]
	v_mfma_f32_16x16x32_bf16 v[16:19], v[128:131], v[192:195], v[16:19]
	v_mfma_f32_16x16x32_bf16 v[12:15], v[144:147], v[192:195], v[12:15]
	s_setprio 0
	s_setprio 1
	v_mfma_f32_16x16x32_bf16 v[56:59], v[148:151], v[164:167], v[56:59]
	v_mfma_f32_16x16x32_bf16 v[52:55], v[156:159], v[164:167], v[52:55]
	v_mfma_f32_16x16x32_bf16 v[40:43], v[148:151], v[172:175], v[40:43]
	v_mfma_f32_16x16x32_bf16 v[36:39], v[156:159], v[172:175], v[36:39]
	v_mfma_f32_16x16x32_bf16 v[24:27], v[148:151], v[180:183], v[24:27]
	v_mfma_f32_16x16x32_bf16 v[20:23], v[156:159], v[180:183], v[20:23]
	v_mfma_f32_16x16x32_bf16 v[8:11], v[148:151], v[188:191], v[8:11]
	v_mfma_f32_16x16x32_bf16 v[4:7], v[156:159], v[188:191], v[4:7]
	v_mfma_f32_16x16x32_bf16 v[56:59], v[152:155], v[168:171], v[56:59]
	v_mfma_f32_16x16x32_bf16 v[52:55], v[160:163], v[168:171], v[52:55]
	v_mfma_f32_16x16x32_bf16 v[40:43], v[152:155], v[176:179], v[40:43]
	v_mfma_f32_16x16x32_bf16 v[36:39], v[160:163], v[176:179], v[36:39]
	v_mfma_f32_16x16x32_bf16 v[24:27], v[152:155], v[184:187], v[24:27]
	v_mfma_f32_16x16x32_bf16 v[20:23], v[160:163], v[184:187], v[20:23]
	v_mfma_f32_16x16x32_bf16 v[8:11], v[152:155], v[192:195], v[8:11]
	v_mfma_f32_16x16x32_bf16 v[4:7], v[160:163], v[192:195], v[4:7]
	s_barrier
	s_setprio 0
	s_add_i32 s0, 0, 0x18000
	s_add_i32 s6, 0, 0x1c000
	v_add_u32_e32 v144, s0, v3
	v_add_u32_e32 v160, s6, v3
	ds_read_b128 v[124:127], v144
	ds_read_b128 v[128:131], v144 offset:1024
	ds_read_b128 v[140:143], v144 offset:2048
	ds_read_b128 v[144:147], v144 offset:3072
	ds_read_b128 v[148:151], v160
	ds_read_b128 v[152:155], v160 offset:1024
	ds_read_b128 v[156:159], v160 offset:2048
	ds_read_b128 v[160:163], v160 offset:3072
	s_add_u32 s34, s34, 0x80000
	s_addc_u32 s35, s35, 0
	s_mov_b32 m0, s25
	v_lshl_add_u64 v[222:223], s[34:35], 0, v[206:207]
	ds_read_b128 v[164:167], v250 offset:32768
	ds_read_b128 v[168:171], v250 offset:33792
	ds_read_b128 v[172:175], v250 offset:34816
	ds_read_b128 v[176:179], v250 offset:35840
	ds_read_b128 v[180:183], v250 offset:36864
	ds_read_b128 v[184:187], v250 offset:37888
	ds_read_b128 v[188:191], v250 offset:38912
	ds_read_b128 v[192:195], v250 offset:39936
	global_load_lds_dwordx4 v[222:223], off
	v_lshl_add_u64 v[222:223], s[34:35], 0, v[202:203]
	s_mov_b32 m0, s29
	s_nop 0
	global_load_lds_dwordx4 v[222:223], off
	s_waitcnt vmcnt(8)
	s_waitcnt lgkmcnt(0)
	s_setprio 1
	s_barrier
	v_mfma_f32_16x16x32_bf16 v[136:139], v[124:127], v[164:167], v[136:139]
	v_mfma_f32_16x16x32_bf16 v[132:135], v[140:143], v[164:167], v[132:135]
	v_mfma_f32_16x16x32_bf16 v[112:115], v[124:127], v[172:175], v[112:115]
	v_mfma_f32_16x16x32_bf16 v[108:111], v[140:143], v[172:175], v[108:111]
	v_mfma_f32_16x16x32_bf16 v[96:99], v[124:127], v[180:183], v[96:99]
	v_mfma_f32_16x16x32_bf16 v[92:95], v[140:143], v[180:183], v[92:95]
	v_mfma_f32_16x16x32_bf16 v[80:83], v[124:127], v[188:191], v[80:83]
	v_mfma_f32_16x16x32_bf16 v[76:79], v[140:143], v[188:191], v[76:79]
	v_mfma_f32_16x16x32_bf16 v[136:139], v[128:131], v[168:171], v[136:139]
	v_mfma_f32_16x16x32_bf16 v[132:135], v[144:147], v[168:171], v[132:135]
	v_mfma_f32_16x16x32_bf16 v[112:115], v[128:131], v[176:179], v[112:115]
	v_mfma_f32_16x16x32_bf16 v[108:111], v[144:147], v[176:179], v[108:111]
	v_mfma_f32_16x16x32_bf16 v[96:99], v[128:131], v[184:187], v[96:99]
	v_mfma_f32_16x16x32_bf16 v[92:95], v[144:147], v[184:187], v[92:95]
	v_mfma_f32_16x16x32_bf16 v[80:83], v[128:131], v[192:195], v[80:83]
	v_mfma_f32_16x16x32_bf16 v[76:79], v[144:147], v[192:195], v[76:79]
	s_setprio 0
	s_setprio 1
	v_mfma_f32_16x16x32_bf16 v[120:123], v[148:151], v[164:167], v[120:123]
	v_mfma_f32_16x16x32_bf16 v[116:119], v[156:159], v[164:167], v[116:119]
	v_mfma_f32_16x16x32_bf16 v[104:107], v[148:151], v[172:175], v[104:107]
	v_mfma_f32_16x16x32_bf16 v[100:103], v[156:159], v[172:175], v[100:103]
	v_mfma_f32_16x16x32_bf16 v[88:91], v[148:151], v[180:183], v[88:91]
	v_mfma_f32_16x16x32_bf16 v[84:87], v[156:159], v[180:183], v[84:87]
	v_mfma_f32_16x16x32_bf16 v[72:75], v[148:151], v[188:191], v[72:75]
	v_mfma_f32_16x16x32_bf16 v[68:71], v[156:159], v[188:191], v[68:71]
	v_mfma_f32_16x16x32_bf16 v[120:123], v[152:155], v[168:171], v[120:123]
	v_mfma_f32_16x16x32_bf16 v[116:119], v[160:163], v[168:171], v[116:119]
	v_mfma_f32_16x16x32_bf16 v[104:107], v[152:155], v[176:179], v[104:107]
	v_mfma_f32_16x16x32_bf16 v[100:103], v[160:163], v[176:179], v[100:103]
	v_mfma_f32_16x16x32_bf16 v[88:91], v[152:155], v[184:187], v[88:91]
	v_mfma_f32_16x16x32_bf16 v[84:87], v[160:163], v[184:187], v[84:87]
	v_mfma_f32_16x16x32_bf16 v[72:75], v[152:155], v[192:195], v[72:75]
	v_mfma_f32_16x16x32_bf16 v[68:71], v[160:163], v[192:195], v[68:71]
	s_barrier
	s_setprio 0
	s_add_i32 s0, s0, s1
	v_lshl_add_u64 v[198:199], v[198:199], 0, s[90:91]
	s_mov_b32 m0, s0
	ds_read_b128 v[164:167], v250 offset:49152
	ds_read_b128 v[168:171], v250 offset:50176
	ds_read_b128 v[172:175], v250 offset:51200
	ds_read_b128 v[176:179], v250 offset:52224
	ds_read_b128 v[180:183], v250 offset:53248
	ds_read_b128 v[184:187], v250 offset:54272
	ds_read_b128 v[188:191], v250 offset:55296
	ds_read_b128 v[192:195], v250 offset:56320
	global_load_lds_dwordx4 v[198:199], off
	s_add_i32 m0, s0, 0x2000
	s_add_u32 s30, s30, 0x80080
	v_lshl_add_u64 v[198:199], v[216:217], 0, s[90:91]
	s_addc_u32 s31, s31, 0
	s_add_i32 s0, s6, s1
	global_load_lds_dwordx4 v[198:199], off
	v_lshl_add_u64 v[198:199], s[30:31], 0, v[204:205]
	s_mov_b32 m0, s0
	s_nop 0
	global_load_lds_dwordx4 v[198:199], off
	v_lshl_add_u64 v[198:199], s[30:31], 0, v[200:201]
	s_add_i32 m0, s0, 0x2000
	s_nop 0
	global_load_lds_dwordx4 v[198:199], off
	v_lshl_add_u64 v[198:199], v[218:219], 0, s[90:91]
	s_mov_b32 m0, s33
	s_nop 0
	global_load_lds_dwordx4 v[198:199], off
	v_lshl_add_u64 v[198:199], v[220:221], 0, s[90:91]
	s_mov_b32 m0, s40
	s_nop 0
	global_load_lds_dwordx4 v[198:199], off
	s_waitcnt vmcnt(8)
	s_waitcnt lgkmcnt(0)
	s_setprio 1
	s_barrier
	v_mfma_f32_16x16x32_bf16 v[64:67], v[124:127], v[164:167], v[64:67]
	v_mfma_f32_16x16x32_bf16 v[60:63], v[140:143], v[164:167], v[60:63]
	v_mfma_f32_16x16x32_bf16 v[48:51], v[124:127], v[172:175], v[48:51]
	v_mfma_f32_16x16x32_bf16 v[44:47], v[140:143], v[172:175], v[44:47]
	v_mfma_f32_16x16x32_bf16 v[32:35], v[124:127], v[180:183], v[32:35]
	v_mfma_f32_16x16x32_bf16 v[28:31], v[140:143], v[180:183], v[28:31]
	v_mfma_f32_16x16x32_bf16 v[16:19], v[124:127], v[188:191], v[16:19]
	v_mfma_f32_16x16x32_bf16 v[12:15], v[140:143], v[188:191], v[12:15]
	v_mfma_f32_16x16x32_bf16 v[64:67], v[128:131], v[168:171], v[64:67]
	v_mfma_f32_16x16x32_bf16 v[60:63], v[144:147], v[168:171], v[60:63]
	v_mfma_f32_16x16x32_bf16 v[48:51], v[128:131], v[176:179], v[48:51]
	v_mfma_f32_16x16x32_bf16 v[44:47], v[144:147], v[176:179], v[44:47]
	v_mfma_f32_16x16x32_bf16 v[32:35], v[128:131], v[184:187], v[32:35]
	v_mfma_f32_16x16x32_bf16 v[28:31], v[144:147], v[184:187], v[28:31]
	v_mfma_f32_16x16x32_bf16 v[16:19], v[128:131], v[192:195], v[16:19]
	v_mfma_f32_16x16x32_bf16 v[12:15], v[144:147], v[192:195], v[12:15]
	s_setprio 0
	s_setprio 1
	v_mfma_f32_16x16x32_bf16 v[56:59], v[148:151], v[164:167], v[56:59]
	v_mfma_f32_16x16x32_bf16 v[52:55], v[156:159], v[164:167], v[52:55]
	v_mfma_f32_16x16x32_bf16 v[40:43], v[148:151], v[172:175], v[40:43]
	v_mfma_f32_16x16x32_bf16 v[36:39], v[156:159], v[172:175], v[36:39]
	v_mfma_f32_16x16x32_bf16 v[24:27], v[148:151], v[180:183], v[24:27]
	v_mfma_f32_16x16x32_bf16 v[20:23], v[156:159], v[180:183], v[20:23]
	v_mfma_f32_16x16x32_bf16 v[8:11], v[148:151], v[188:191], v[8:11]
	v_mfma_f32_16x16x32_bf16 v[4:7], v[156:159], v[188:191], v[4:7]
	v_mfma_f32_16x16x32_bf16 v[56:59], v[152:155], v[168:171], v[56:59]
	v_mfma_f32_16x16x32_bf16 v[52:55], v[160:163], v[168:171], v[52:55]
	v_mfma_f32_16x16x32_bf16 v[40:43], v[152:155], v[176:179], v[40:43]
	v_mfma_f32_16x16x32_bf16 v[36:39], v[160:163], v[176:179], v[36:39]
	v_mfma_f32_16x16x32_bf16 v[24:27], v[152:155], v[184:187], v[24:27]
	v_mfma_f32_16x16x32_bf16 v[20:23], v[160:163], v[184:187], v[20:23]
	v_mfma_f32_16x16x32_bf16 v[8:11], v[152:155], v[192:195], v[8:11]
	v_mfma_f32_16x16x32_bf16 v[4:7], v[160:163], v[192:195], v[4:7]
	s_barrier
	s_setprio 0
	s_add_i32 s55, s55, 2
	s_add_u32 s36, s36, 0x100
	s_addc_u32 s37, s37, 0
	s_add_u32 s38, s38, 0x100
	s_addc_u32 s39, s39, 0
	s_cmp_gt_u32 s55, 29
	s_cbranch_scc0 .LBB0_967
	s_and_b64 vcc, exec, s[44:45]
	s_cbranch_vccz .LBB0_970
	s_barrier

.LBB0_1017:
	s_add_u32 s0, s68, s30
	s_addc_u32 s6, s69, 0
	s_add_u32 s31, s0, 0x100
	s_addc_u32 s38, s6, 0
	s_and_b64 s[34:35], s[36:37], exec
	s_cselect_b32 vcc_hi, s65, s38
	s_cselect_b32 vcc_lo, s64, s31
	s_add_u32 s30, s74, s30
	s_addc_u32 s31, s75, 0
	s_add_u32 s34, s30, 0x100
	s_addc_u32 s35, s31, 0
	s_add_i32 s78, 0, 0x10000
	s_and_b64 s[30:31], s[36:37], exec
	s_cselect_b32 s53, s67, s35
	s_cselect_b32 s52, s66, s34
	s_add_i32 s37, 0, 0x14000
	s_add_u32 s34, s0, 0x80080
	s_addc_u32 s35, s6, 0
	s_add_i32 s73, s78, s1
	s_add_i32 m0, s4, 0xc000
	s_add_i32 s83, s4, 0xe000
	s_add_i32 s6, s73, 0x2000
	s_add_u32 s30, s52, 0x80000
	v_add_u32_e32 v144, s78, v3
	v_add_u32_e32 v160, s37, v3
	s_addc_u32 s31, s53, 0
	s_add_i32 s49, s37, s1
	ds_read_b128 v[132:135], v144
	ds_read_b128 v[136:139], v144 offset:1024
	ds_read_b128 v[140:143], v144 offset:2048
	ds_read_b128 v[144:147], v144 offset:3072
	ds_read_b128 v[148:151], v160
	ds_read_b128 v[152:155], v160 offset:1024
	ds_read_b128 v[156:159], v160 offset:2048
	ds_read_b128 v[160:163], v160 offset:3072
	s_add_i32 s63, s49, 0x2000
	s_add_i32 s54, 0, 0x18000
	s_add_i32 s61, 0, 0x1c000
	s_add_u32 s38, vcc_lo, 0x80000
	s_addc_u32 s39, vcc_hi, 0
	s_add_i32 s0, s54, s1
	s_add_i32 s45, s0, 0x2000
	s_add_u32 s36, s52, 0x80080
	s_addc_u32 s37, s53, 0
	s_add_i32 s82, s61, s1
	s_add_i32 s78, s82, 0x2000
	v_lshl_add_u64 v[198:199], s[34:35], 0, v[206:207]
	ds_read_b128 v[164:167], v236
	ds_read_b128 v[168:171], v236 offset:1024
	ds_read_b128 v[172:175], v236 offset:2048
	ds_read_b128 v[176:179], v236 offset:3072
	ds_read_b128 v[180:183], v236 offset:4096
	ds_read_b128 v[184:187], v236 offset:5120
	ds_read_b128 v[188:191], v236 offset:6144
	ds_read_b128 v[192:195], v236 offset:7168
	global_load_lds_dwordx4 v[198:199], off
	v_lshl_add_u64 v[198:199], s[34:35], 0, v[202:203]
	s_mov_b32 m0, s83
	s_nop 0
	global_load_lds_dwordx4 v[198:199], off
	s_waitcnt vmcnt(8)
	s_waitcnt lgkmcnt(0)
	s_setprio 1
	s_barrier
	v_mfma_f32_16x16x32_bf16 v[128:131], v[132:135], v[164:167], v[128:131]
	v_mfma_f32_16x16x32_bf16 v[124:127], v[140:143], v[164:167], v[124:127]
	v_mfma_f32_16x16x32_bf16 v[112:115], v[132:135], v[172:175], v[112:115]
	v_mfma_f32_16x16x32_bf16 v[108:111], v[140:143], v[172:175], v[108:111]
	v_mfma_f32_16x16x32_bf16 v[96:99], v[132:135], v[180:183], v[96:99]
	v_mfma_f32_16x16x32_bf16 v[92:95], v[140:143], v[180:183], v[92:95]
	v_mfma_f32_16x16x32_bf16 v[80:83], v[132:135], v[188:191], v[80:83]
	v_mfma_f32_16x16x32_bf16 v[76:79], v[140:143], v[188:191], v[76:79]
	v_mfma_f32_16x16x32_bf16 v[128:131], v[136:139], v[168:171], v[128:131]
	v_mfma_f32_16x16x32_bf16 v[124:127], v[144:147], v[168:171], v[124:127]
	v_mfma_f32_16x16x32_bf16 v[112:115], v[136:139], v[176:179], v[112:115]
	v_mfma_f32_16x16x32_bf16 v[108:111], v[144:147], v[176:179], v[108:111]
	v_mfma_f32_16x16x32_bf16 v[96:99], v[136:139], v[184:187], v[96:99]
	v_mfma_f32_16x16x32_bf16 v[92:95], v[144:147], v[184:187], v[92:95]
	v_mfma_f32_16x16x32_bf16 v[80:83], v[136:139], v[192:195], v[80:83]
	v_mfma_f32_16x16x32_bf16 v[76:79], v[144:147], v[192:195], v[76:79]
	s_setprio 0
	s_setprio 1
	v_mfma_f32_16x16x32_bf16 v[120:123], v[148:151], v[164:167], v[120:123]
	v_mfma_f32_16x16x32_bf16 v[116:119], v[156:159], v[164:167], v[116:119]
	v_mfma_f32_16x16x32_bf16 v[104:107], v[148:151], v[172:175], v[104:107]
	v_mfma_f32_16x16x32_bf16 v[100:103], v[156:159], v[172:175], v[100:103]
	v_mfma_f32_16x16x32_bf16 v[88:91], v[148:151], v[180:183], v[88:91]
	v_mfma_f32_16x16x32_bf16 v[84:87], v[156:159], v[180:183], v[84:87]
	v_mfma_f32_16x16x32_bf16 v[72:75], v[148:151], v[188:191], v[72:75]
	v_mfma_f32_16x16x32_bf16 v[68:71], v[156:159], v[188:191], v[68:71]
	v_mfma_f32_16x16x32_bf16 v[120:123], v[152:155], v[168:171], v[120:123]
	v_mfma_f32_16x16x32_bf16 v[116:119], v[160:163], v[168:171], v[116:119]
	v_mfma_f32_16x16x32_bf16 v[104:107], v[152:155], v[176:179], v[104:107]
	v_mfma_f32_16x16x32_bf16 v[100:103], v[160:163], v[176:179], v[100:103]
	v_mfma_f32_16x16x32_bf16 v[88:91], v[152:155], v[184:187], v[88:91]
	v_mfma_f32_16x16x32_bf16 v[84:87], v[160:163], v[184:187], v[84:87]
	v_mfma_f32_16x16x32_bf16 v[72:75], v[152:155], v[192:195], v[72:75]
	v_mfma_f32_16x16x32_bf16 v[68:71], v[160:163], v[192:195], v[68:71]
	s_barrier
	s_setprio 0
	s_mov_b32 m0, s73
	v_lshl_add_u64 v[198:199], s[52:53], 0, v[204:205]
	ds_read_b128 v[164:167], v236 offset:16384
	ds_read_b128 v[168:171], v236 offset:17408
	ds_read_b128 v[172:175], v236 offset:18432
	ds_read_b128 v[176:179], v236 offset:19456
	ds_read_b128 v[180:183], v236 offset:20480
	ds_read_b128 v[184:187], v236 offset:21504
	ds_read_b128 v[188:191], v236 offset:22528
	ds_read_b128 v[192:195], v236 offset:23552
	global_load_lds_dwordx4 v[198:199], off
	v_lshl_add_u64 v[212:213], s[52:53], 0, v[200:201]
	s_mov_b32 m0, s6
	v_lshl_add_u64 v[214:215], s[30:31], 0, v[204:205]
	global_load_lds_dwordx4 v[212:213], off
	s_mov_b32 m0, s49
	v_lshl_add_u64 v[216:217], vcc, 0, v[202:203]
	global_load_lds_dwordx4 v[214:215], off
	v_lshl_add_u64 v[214:215], s[30:31], 0, v[200:201]
	s_mov_b32 m0, s63
	s_nop 0
	global_load_lds_dwordx4 v[214:215], off
	v_lshl_add_u64 v[214:215], vcc, 0, v[206:207]
	s_mov_b32 m0, s4
	s_nop 0
	global_load_lds_dwordx4 v[214:215], off
	s_mov_b32 m0, s24
	s_nop 0
	global_load_lds_dwordx4 v[216:217], off
	s_waitcnt vmcnt(8)
	s_waitcnt lgkmcnt(0)
	s_setprio 1
	s_barrier
	v_mfma_f32_16x16x32_bf16 v[64:67], v[132:135], v[164:167], v[64:67]
	v_mfma_f32_16x16x32_bf16 v[60:63], v[140:143], v[164:167], v[60:63]
	v_mfma_f32_16x16x32_bf16 v[48:51], v[132:135], v[172:175], v[48:51]
	v_mfma_f32_16x16x32_bf16 v[44:47], v[140:143], v[172:175], v[44:47]
	v_mfma_f32_16x16x32_bf16 v[32:35], v[132:135], v[180:183], v[32:35]
	v_mfma_f32_16x16x32_bf16 v[28:31], v[140:143], v[180:183], v[28:31]
	v_mfma_f32_16x16x32_bf16 v[16:19], v[132:135], v[188:191], v[16:19]
	v_mfma_f32_16x16x32_bf16 v[12:15], v[140:143], v[188:191], v[12:15]
	v_mfma_f32_16x16x32_bf16 v[64:67], v[136:139], v[168:171], v[64:67]
	v_mfma_f32_16x16x32_bf16 v[60:63], v[144:147], v[168:171], v[60:63]
	v_mfma_f32_16x16x32_bf16 v[48:51], v[136:139], v[176:179], v[48:51]
	v_mfma_f32_16x16x32_bf16 v[44:47], v[144:147], v[176:179], v[44:47]
	v_mfma_f32_16x16x32_bf16 v[32:35], v[136:139], v[184:187], v[32:35]
	v_mfma_f32_16x16x32_bf16 v[28:31], v[144:147], v[184:187], v[28:31]
	v_mfma_f32_16x16x32_bf16 v[16:19], v[136:139], v[192:195], v[16:19]
	v_mfma_f32_16x16x32_bf16 v[12:15], v[144:147], v[192:195], v[12:15]
	s_setprio 0
	s_setprio 1
	v_mfma_f32_16x16x32_bf16 v[56:59], v[148:151], v[164:167], v[56:59]
	v_mfma_f32_16x16x32_bf16 v[52:55], v[156:159], v[164:167], v[52:55]
	v_mfma_f32_16x16x32_bf16 v[40:43], v[148:151], v[172:175], v[40:43]
	v_mfma_f32_16x16x32_bf16 v[36:39], v[156:159], v[172:175], v[36:39]
	v_mfma_f32_16x16x32_bf16 v[24:27], v[148:151], v[180:183], v[24:27]
	v_mfma_f32_16x16x32_bf16 v[20:23], v[156:159], v[180:183], v[20:23]
	v_mfma_f32_16x16x32_bf16 v[8:11], v[148:151], v[188:191], v[8:11]
	v_mfma_f32_16x16x32_bf16 v[4:7], v[156:159], v[188:191], v[4:7]
	v_mfma_f32_16x16x32_bf16 v[56:59], v[152:155], v[168:171], v[56:59]
	v_mfma_f32_16x16x32_bf16 v[52:55], v[160:163], v[168:171], v[52:55]
	v_mfma_f32_16x16x32_bf16 v[40:43], v[152:155], v[176:179], v[40:43]
	v_mfma_f32_16x16x32_bf16 v[36:39], v[160:163], v[176:179], v[36:39]
	v_mfma_f32_16x16x32_bf16 v[24:27], v[152:155], v[184:187], v[24:27]
	v_mfma_f32_16x16x32_bf16 v[20:23], v[160:163], v[184:187], v[20:23]
	v_mfma_f32_16x16x32_bf16 v[8:11], v[152:155], v[192:195], v[8:11]
	v_mfma_f32_16x16x32_bf16 v[4:7], v[160:163], v[192:195], v[4:7]
	s_barrier
	s_setprio 0
	v_add_u32_e32 v144, s54, v3
	v_add_u32_e32 v160, s61, v3
	ds_read_b128 v[132:135], v144
	ds_read_b128 v[136:139], v144 offset:1024
	ds_read_b128 v[140:143], v144 offset:2048
	ds_read_b128 v[144:147], v144 offset:3072
	ds_read_b128 v[148:151], v160
	ds_read_b128 v[152:155], v160 offset:1024
	ds_read_b128 v[156:159], v160 offset:2048
	ds_read_b128 v[160:163], v160 offset:3072
	s_mov_b32 m0, s25
	v_lshl_add_u64 v[218:219], s[38:39], 0, v[206:207]
	ds_read_b128 v[164:167], v236 offset:32768
	ds_read_b128 v[168:171], v236 offset:33792
	ds_read_b128 v[172:175], v236 offset:34816
	ds_read_b128 v[176:179], v236 offset:35840
	ds_read_b128 v[180:183], v236 offset:36864
	ds_read_b128 v[184:187], v236 offset:37888
	ds_read_b128 v[188:191], v236 offset:38912
	ds_read_b128 v[192:195], v236 offset:39936
	global_load_lds_dwordx4 v[218:219], off
	v_lshl_add_u64 v[218:219], s[38:39], 0, v[202:203]
	s_mov_b32 m0, s33
	s_nop 0
	global_load_lds_dwordx4 v[218:219], off
	s_waitcnt vmcnt(8)
	s_waitcnt lgkmcnt(0)
	s_setprio 1
	s_barrier
	v_mfma_f32_16x16x32_bf16 v[128:131], v[132:135], v[164:167], v[128:131]
	v_mfma_f32_16x16x32_bf16 v[124:127], v[140:143], v[164:167], v[124:127]
	v_mfma_f32_16x16x32_bf16 v[112:115], v[132:135], v[172:175], v[112:115]
	v_mfma_f32_16x16x32_bf16 v[108:111], v[140:143], v[172:175], v[108:111]
	v_mfma_f32_16x16x32_bf16 v[96:99], v[132:135], v[180:183], v[96:99]
	v_mfma_f32_16x16x32_bf16 v[92:95], v[140:143], v[180:183], v[92:95]
	v_mfma_f32_16x16x32_bf16 v[80:83], v[132:135], v[188:191], v[80:83]
	v_mfma_f32_16x16x32_bf16 v[76:79], v[140:143], v[188:191], v[76:79]
	v_mfma_f32_16x16x32_bf16 v[128:131], v[136:139], v[168:171], v[128:131]
	v_mfma_f32_16x16x32_bf16 v[124:127], v[144:147], v[168:171], v[124:127]
	v_mfma_f32_16x16x32_bf16 v[112:115], v[136:139], v[176:179], v[112:115]
	v_mfma_f32_16x16x32_bf16 v[108:111], v[144:147], v[176:179], v[108:111]
	v_mfma_f32_16x16x32_bf16 v[96:99], v[136:139], v[184:187], v[96:99]
	v_mfma_f32_16x16x32_bf16 v[92:95], v[144:147], v[184:187], v[92:95]
	v_mfma_f32_16x16x32_bf16 v[80:83], v[136:139], v[192:195], v[80:83]
	v_mfma_f32_16x16x32_bf16 v[76:79], v[144:147], v[192:195], v[76:79]
	s_setprio 0
	s_setprio 1
	v_mfma_f32_16x16x32_bf16 v[120:123], v[148:151], v[164:167], v[120:123]
	v_mfma_f32_16x16x32_bf16 v[116:119], v[156:159], v[164:167], v[116:119]
	v_mfma_f32_16x16x32_bf16 v[104:107], v[148:151], v[172:175], v[104:107]
	v_mfma_f32_16x16x32_bf16 v[100:103], v[156:159], v[172:175], v[100:103]
	v_mfma_f32_16x16x32_bf16 v[88:91], v[148:151], v[180:183], v[88:91]
	v_mfma_f32_16x16x32_bf16 v[84:87], v[156:159], v[180:183], v[84:87]
	v_mfma_f32_16x16x32_bf16 v[72:75], v[148:151], v[188:191], v[72:75]
	v_mfma_f32_16x16x32_bf16 v[68:71], v[156:159], v[188:191], v[68:71]
	v_mfma_f32_16x16x32_bf16 v[120:123], v[152:155], v[168:171], v[120:123]
	v_mfma_f32_16x16x32_bf16 v[116:119], v[160:163], v[168:171], v[116:119]
	v_mfma_f32_16x16x32_bf16 v[104:107], v[152:155], v[176:179], v[104:107]
	v_mfma_f32_16x16x32_bf16 v[100:103], v[160:163], v[176:179], v[100:103]
	v_mfma_f32_16x16x32_bf16 v[88:91], v[152:155], v[184:187], v[88:91]
	v_mfma_f32_16x16x32_bf16 v[84:87], v[160:163], v[184:187], v[84:87]
	v_mfma_f32_16x16x32_bf16 v[72:75], v[152:155], v[192:195], v[72:75]
	v_mfma_f32_16x16x32_bf16 v[68:71], v[160:163], v[192:195], v[68:71]
	s_barrier
	s_setprio 0
	s_mov_b32 m0, s0
	v_lshl_add_u64 v[198:199], v[198:199], 0, s[90:91]
	ds_read_b128 v[164:167], v236 offset:49152
	ds_read_b128 v[168:171], v236 offset:50176
	ds_read_b128 v[172:175], v236 offset:51200
	ds_read_b128 v[176:179], v236 offset:52224
	ds_read_b128 v[180:183], v236 offset:53248
	ds_read_b128 v[184:187], v236 offset:54272
	ds_read_b128 v[188:191], v236 offset:55296
	ds_read_b128 v[192:195], v236 offset:56320
	global_load_lds_dwordx4 v[198:199], off
	v_lshl_add_u64 v[198:199], v[212:213], 0, s[90:91]
	s_mov_b32 m0, s45
	s_nop 0
	global_load_lds_dwordx4 v[198:199], off
	v_lshl_add_u64 v[198:199], s[36:37], 0, v[204:205]
	s_mov_b32 m0, s82
	s_nop 0
	global_load_lds_dwordx4 v[198:199], off
	v_lshl_add_u64 v[198:199], s[36:37], 0, v[200:201]
	s_mov_b32 m0, s78
	s_nop 0
	global_load_lds_dwordx4 v[198:199], off
	v_lshl_add_u64 v[198:199], v[214:215], 0, s[90:91]
	s_mov_b32 m0, s40
	s_nop 0
	global_load_lds_dwordx4 v[198:199], off
	v_lshl_add_u64 v[198:199], v[216:217], 0, s[90:91]
	s_mov_b32 m0, s50
	s_nop 0
	global_load_lds_dwordx4 v[198:199], off
	s_waitcnt vmcnt(8)
	s_waitcnt lgkmcnt(0)
	s_setprio 1
	s_barrier
	v_mfma_f32_16x16x32_bf16 v[64:67], v[132:135], v[164:167], v[64:67]
	v_mfma_f32_16x16x32_bf16 v[60:63], v[140:143], v[164:167], v[60:63]
	v_mfma_f32_16x16x32_bf16 v[48:51], v[132:135], v[172:175], v[48:51]
	v_mfma_f32_16x16x32_bf16 v[44:47], v[140:143], v[172:175], v[44:47]
	v_mfma_f32_16x16x32_bf16 v[32:35], v[132:135], v[180:183], v[32:35]
	v_mfma_f32_16x16x32_bf16 v[28:31], v[140:143], v[180:183], v[28:31]
	v_mfma_f32_16x16x32_bf16 v[16:19], v[132:135], v[188:191], v[16:19]
	v_mfma_f32_16x16x32_bf16 v[12:15], v[140:143], v[188:191], v[12:15]
	v_mfma_f32_16x16x32_bf16 v[64:67], v[136:139], v[168:171], v[64:67]
	v_mfma_f32_16x16x32_bf16 v[60:63], v[144:147], v[168:171], v[60:63]
	v_mfma_f32_16x16x32_bf16 v[48:51], v[136:139], v[176:179], v[48:51]
	v_mfma_f32_16x16x32_bf16 v[44:47], v[144:147], v[176:179], v[44:47]
	v_mfma_f32_16x16x32_bf16 v[32:35], v[136:139], v[184:187], v[32:35]
	v_mfma_f32_16x16x32_bf16 v[28:31], v[144:147], v[184:187], v[28:31]
	v_mfma_f32_16x16x32_bf16 v[16:19], v[136:139], v[192:195], v[16:19]
	v_mfma_f32_16x16x32_bf16 v[12:15], v[144:147], v[192:195], v[12:15]
	s_setprio 0
	s_setprio 1
	v_mfma_f32_16x16x32_bf16 v[56:59], v[148:151], v[164:167], v[56:59]
	v_mfma_f32_16x16x32_bf16 v[52:55], v[156:159], v[164:167], v[52:55]
	v_mfma_f32_16x16x32_bf16 v[40:43], v[148:151], v[172:175], v[40:43]
	v_mfma_f32_16x16x32_bf16 v[36:39], v[156:159], v[172:175], v[36:39]
	v_mfma_f32_16x16x32_bf16 v[24:27], v[148:151], v[180:183], v[24:27]
	v_mfma_f32_16x16x32_bf16 v[20:23], v[156:159], v[180:183], v[20:23]
	v_mfma_f32_16x16x32_bf16 v[8:11], v[148:151], v[188:191], v[8:11]
	v_mfma_f32_16x16x32_bf16 v[4:7], v[156:159], v[188:191], v[4:7]
	v_mfma_f32_16x16x32_bf16 v[56:59], v[152:155], v[168:171], v[56:59]
	v_mfma_f32_16x16x32_bf16 v[52:55], v[160:163], v[168:171], v[52:55]
	v_mfma_f32_16x16x32_bf16 v[40:43], v[152:155], v[176:179], v[40:43]
	v_mfma_f32_16x16x32_bf16 v[36:39], v[160:163], v[176:179], v[36:39]
	v_mfma_f32_16x16x32_bf16 v[24:27], v[152:155], v[184:187], v[24:27]
	v_mfma_f32_16x16x32_bf16 v[20:23], v[160:163], v[184:187], v[20:23]
	v_mfma_f32_16x16x32_bf16 v[8:11], v[152:155], v[192:195], v[8:11]
	v_mfma_f32_16x16x32_bf16 v[4:7], v[160:163], v[192:195], v[4:7]
	s_barrier
	s_setprio 0
	s_movk_i32 s30, 0x100
	s_andn2_b64 vcc, exec, s[80:81]
	s_mov_b64 s[36:37], -1
	s_mov_b64 s[80:81], 0
	s_cbranch_vccz .LBB0_1017
	s_and_b64 vcc, exec, s[42:43]
	s_cbranch_vccz .LBB0_1020
	s_barrier

.LBB0_1137:
	s_add_u32 s0, s36, 0xfff80080
	s_addc_u32 s6, s37, -1
	s_add_i32 s49, 0, 0x10000
	s_cmp_eq_u32 s66, 28
	s_cselect_b32 s35, s29, s6
	s_cselect_b32 s34, s64, s0
	v_add_u32_e32 v156, s49, v157
	s_cselect_b32 s31, s23, s39
	s_cselect_b32 s30, s65, s38
	s_add_i32 s0, 0, 0x14000
	ds_read_b128 v[144:147], v156
	ds_read_b128 v[148:151], v156 offset:1024
	ds_read_b128 v[152:155], v156 offset:2048
	ds_read_b128 v[162:165], v156 offset:3072
	v_add_u32_e32 v156, s0, v157
	ds_read_b128 v[166:169], v156
	ds_read_b128 v[170:173], v156 offset:1024
	ds_read_b128 v[174:177], v156 offset:2048
	ds_read_b128 v[178:181], v156 offset:3072
	v_lshl_add_u64 v[194:195], s[36:37], 0, v[140:141]
	s_add_i32 m0, s33, 0xc000
	ds_read_b128 v[182:185], v161
	ds_read_b128 v[186:189], v161 offset:1024
	ds_read_b128 v[190:193], v161 offset:2048
	ds_read_b128 v[200:203], v161 offset:3072
	ds_read_b128 v[204:207], v161 offset:4096
	ds_read_b128 v[208:211], v161 offset:5120
	ds_read_b128 v[212:215], v161 offset:6144
	ds_read_b128 v[216:219], v161 offset:7168
	global_load_lds_dwordx4 v[194:195], off
	v_lshl_add_u64 v[194:195], s[36:37], 0, v[142:143]
	s_add_i32 m0, s33, 0xe000
	s_nop 0
	global_load_lds_dwordx4 v[194:195], off
	s_waitcnt vmcnt(8)
	s_waitcnt lgkmcnt(0)
	s_setprio 1
	s_barrier
	v_mfma_f32_16x16x32_bf16 v[128:131], v[144:147], v[182:185], v[128:131]
	v_mfma_f32_16x16x32_bf16 v[124:127], v[152:155], v[182:185], v[124:127]
	v_mfma_f32_16x16x32_bf16 v[112:115], v[144:147], v[190:193], v[112:115]
	v_mfma_f32_16x16x32_bf16 v[108:111], v[152:155], v[190:193], v[108:111]
	v_mfma_f32_16x16x32_bf16 v[96:99], v[144:147], v[204:207], v[96:99]
	v_mfma_f32_16x16x32_bf16 v[92:95], v[152:155], v[204:207], v[92:95]
	v_mfma_f32_16x16x32_bf16 v[80:83], v[144:147], v[212:215], v[80:83]
	v_mfma_f32_16x16x32_bf16 v[76:79], v[152:155], v[212:215], v[76:79]
	v_mfma_f32_16x16x32_bf16 v[128:131], v[148:151], v[186:189], v[128:131]
	v_mfma_f32_16x16x32_bf16 v[124:127], v[162:165], v[186:189], v[124:127]
	v_mfma_f32_16x16x32_bf16 v[112:115], v[148:151], v[200:203], v[112:115]
	v_mfma_f32_16x16x32_bf16 v[108:111], v[162:165], v[200:203], v[108:111]
	v_mfma_f32_16x16x32_bf16 v[96:99], v[148:151], v[208:211], v[96:99]
	v_mfma_f32_16x16x32_bf16 v[92:95], v[162:165], v[208:211], v[92:95]
	v_mfma_f32_16x16x32_bf16 v[80:83], v[148:151], v[216:219], v[80:83]
	v_mfma_f32_16x16x32_bf16 v[76:79], v[162:165], v[216:219], v[76:79]
	s_setprio 0
	s_setprio 1
	v_mfma_f32_16x16x32_bf16 v[120:123], v[166:169], v[182:185], v[120:123]
	v_mfma_f32_16x16x32_bf16 v[116:119], v[174:177], v[182:185], v[116:119]
	v_mfma_f32_16x16x32_bf16 v[104:107], v[166:169], v[190:193], v[104:107]
	v_mfma_f32_16x16x32_bf16 v[100:103], v[174:177], v[190:193], v[100:103]
	v_mfma_f32_16x16x32_bf16 v[88:91], v[166:169], v[204:207], v[88:91]
	v_mfma_f32_16x16x32_bf16 v[84:87], v[174:177], v[204:207], v[84:87]
	v_mfma_f32_16x16x32_bf16 v[72:75], v[166:169], v[212:215], v[72:75]
	v_mfma_f32_16x16x32_bf16 v[68:71], v[174:177], v[212:215], v[68:71]
	v_mfma_f32_16x16x32_bf16 v[120:123], v[170:173], v[186:189], v[120:123]
	v_mfma_f32_16x16x32_bf16 v[116:119], v[178:181], v[186:189], v[116:119]
	v_mfma_f32_16x16x32_bf16 v[104:107], v[170:173], v[200:203], v[104:107]
	v_mfma_f32_16x16x32_bf16 v[100:103], v[178:181], v[200:203], v[100:103]
	v_mfma_f32_16x16x32_bf16 v[88:91], v[170:173], v[208:211], v[88:91]
	v_mfma_f32_16x16x32_bf16 v[84:87], v[178:181], v[208:211], v[84:87]
	v_mfma_f32_16x16x32_bf16 v[72:75], v[170:173], v[216:219], v[72:75]
	v_mfma_f32_16x16x32_bf16 v[68:71], v[178:181], v[216:219], v[68:71]
	s_barrier
	s_setprio 0
	s_add_i32 s6, s49, s25
	v_lshl_add_u64 v[194:195], s[30:31], 0, v[136:137]
	s_mov_b32 m0, s6
	ds_read_b128 v[182:185], v161 offset:16384
	ds_read_b128 v[186:189], v161 offset:17408
	ds_read_b128 v[190:193], v161 offset:18432
	ds_read_b128 v[200:203], v161 offset:19456
	ds_read_b128 v[204:207], v161 offset:20480
	ds_read_b128 v[208:211], v161 offset:21504
	ds_read_b128 v[212:215], v161 offset:22528
	ds_read_b128 v[216:219], v161 offset:23552
	global_load_lds_dwordx4 v[194:195], off
	s_add_i32 m0, s6, 0x2000
	s_add_u32 s68, s30, 0x80000
	v_lshl_add_u64 v[198:199], s[30:31], 0, v[132:133]
	s_addc_u32 s69, s31, 0
	s_add_i32 s0, s0, s25
	global_load_lds_dwordx4 v[198:199], off
	v_lshl_add_u64 v[220:221], s[68:69], 0, v[136:137]
	s_mov_b32 m0, s0
	v_lshl_add_u64 v[222:223], s[34:35], 0, v[134:135]
	global_load_lds_dwordx4 v[220:221], off
	v_lshl_add_u64 v[220:221], s[68:69], 0, v[132:133]
	s_add_i32 m0, s0, 0x2000
	s_nop 0
	global_load_lds_dwordx4 v[220:221], off
	v_lshl_add_u64 v[220:221], s[34:35], 0, v[138:139]
	s_mov_b32 m0, s33
	s_nop 0
	global_load_lds_dwordx4 v[220:221], off
	s_mov_b32 m0, s40
	s_nop 0
	global_load_lds_dwordx4 v[222:223], off
	s_waitcnt vmcnt(8)
	s_waitcnt lgkmcnt(0)
	s_setprio 1
	s_barrier
	v_mfma_f32_16x16x32_bf16 v[64:67], v[144:147], v[182:185], v[64:67]
	v_mfma_f32_16x16x32_bf16 v[60:63], v[152:155], v[182:185], v[60:63]
	v_mfma_f32_16x16x32_bf16 v[48:51], v[144:147], v[190:193], v[48:51]
	v_mfma_f32_16x16x32_bf16 v[44:47], v[152:155], v[190:193], v[44:47]
	v_mfma_f32_16x16x32_bf16 v[32:35], v[144:147], v[204:207], v[32:35]
	v_mfma_f32_16x16x32_bf16 v[28:31], v[152:155], v[204:207], v[28:31]
	v_mfma_f32_16x16x32_bf16 v[16:19], v[144:147], v[212:215], v[16:19]
	v_mfma_f32_16x16x32_bf16 v[12:15], v[152:155], v[212:215], v[12:15]
	v_mfma_f32_16x16x32_bf16 v[64:67], v[148:151], v[186:189], v[64:67]
	v_mfma_f32_16x16x32_bf16 v[60:63], v[162:165], v[186:189], v[60:63]
	v_mfma_f32_16x16x32_bf16 v[48:51], v[148:151], v[200:203], v[48:51]
	v_mfma_f32_16x16x32_bf16 v[44:47], v[162:165], v[200:203], v[44:47]
	v_mfma_f32_16x16x32_bf16 v[32:35], v[148:151], v[208:211], v[32:35]
	v_mfma_f32_16x16x32_bf16 v[28:31], v[162:165], v[208:211], v[28:31]
	v_mfma_f32_16x16x32_bf16 v[16:19], v[148:151], v[216:219], v[16:19]
	v_mfma_f32_16x16x32_bf16 v[12:15], v[162:165], v[216:219], v[12:15]
	s_setprio 0
	s_setprio 1
	v_mfma_f32_16x16x32_bf16 v[56:59], v[166:169], v[182:185], v[56:59]
	v_mfma_f32_16x16x32_bf16 v[52:55], v[174:177], v[182:185], v[52:55]
	v_mfma_f32_16x16x32_bf16 v[40:43], v[166:169], v[190:193], v[40:43]
	v_mfma_f32_16x16x32_bf16 v[36:39], v[174:177], v[190:193], v[36:39]
	v_mfma_f32_16x16x32_bf16 v[24:27], v[166:169], v[204:207], v[24:27]
	v_mfma_f32_16x16x32_bf16 v[20:23], v[174:177], v[204:207], v[20:23]
	v_mfma_f32_16x16x32_bf16 v[8:11], v[166:169], v[212:215], v[8:11]
	v_mfma_f32_16x16x32_bf16 v[4:7], v[174:177], v[212:215], v[4:7]
	v_mfma_f32_16x16x32_bf16 v[56:59], v[170:173], v[186:189], v[56:59]
	v_mfma_f32_16x16x32_bf16 v[52:55], v[178:181], v[186:189], v[52:55]
	v_mfma_f32_16x16x32_bf16 v[40:43], v[170:173], v[200:203], v[40:43]
	v_mfma_f32_16x16x32_bf16 v[36:39], v[178:181], v[200:203], v[36:39]
	v_mfma_f32_16x16x32_bf16 v[24:27], v[170:173], v[208:211], v[24:27]
	v_mfma_f32_16x16x32_bf16 v[20:23], v[178:181], v[208:211], v[20:23]
	v_mfma_f32_16x16x32_bf16 v[8:11], v[170:173], v[216:219], v[8:11]
	v_mfma_f32_16x16x32_bf16 v[4:7], v[178:181], v[216:219], v[4:7]
	s_barrier
	s_setprio 0
	s_add_i32 s0, 0, 0x18000
	v_add_u32_e32 v156, s0, v157
	s_add_i32 s6, 0, 0x1c000
	ds_read_b128 v[144:147], v156
	ds_read_b128 v[148:151], v156 offset:1024
	ds_read_b128 v[152:155], v156 offset:2048
	ds_read_b128 v[162:165], v156 offset:3072
	v_add_u32_e32 v156, s6, v157
	ds_read_b128 v[166:169], v156
	ds_read_b128 v[170:173], v156 offset:1024
	ds_read_b128 v[174:177], v156 offset:2048
	ds_read_b128 v[178:181], v156 offset:3072
	s_add_u32 s34, s34, 0x80000
	s_addc_u32 s35, s35, 0
	s_mov_b32 m0, s50
	v_lshl_add_u64 v[224:225], s[34:35], 0, v[138:139]
	ds_read_b128 v[182:185], v161 offset:32768
	ds_read_b128 v[186:189], v161 offset:33792
	ds_read_b128 v[190:193], v161 offset:34816
	ds_read_b128 v[200:203], v161 offset:35840
	ds_read_b128 v[204:207], v161 offset:36864
	ds_read_b128 v[208:211], v161 offset:37888
	ds_read_b128 v[212:215], v161 offset:38912
	ds_read_b128 v[216:219], v161 offset:39936
	global_load_lds_dwordx4 v[224:225], off
	v_lshl_add_u64 v[224:225], s[34:35], 0, v[134:135]
	s_mov_b32 m0, s51
	s_nop 0
	global_load_lds_dwordx4 v[224:225], off
	s_waitcnt vmcnt(8)
	s_waitcnt lgkmcnt(0)
	s_setprio 1
	s_barrier
	v_mfma_f32_16x16x32_bf16 v[128:131], v[144:147], v[182:185], v[128:131]
	v_mfma_f32_16x16x32_bf16 v[124:127], v[152:155], v[182:185], v[124:127]
	v_mfma_f32_16x16x32_bf16 v[112:115], v[144:147], v[190:193], v[112:115]
	v_mfma_f32_16x16x32_bf16 v[108:111], v[152:155], v[190:193], v[108:111]
	v_mfma_f32_16x16x32_bf16 v[96:99], v[144:147], v[204:207], v[96:99]
	v_mfma_f32_16x16x32_bf16 v[92:95], v[152:155], v[204:207], v[92:95]
	v_mfma_f32_16x16x32_bf16 v[80:83], v[144:147], v[212:215], v[80:83]
	v_mfma_f32_16x16x32_bf16 v[76:79], v[152:155], v[212:215], v[76:79]
	v_mfma_f32_16x16x32_bf16 v[128:131], v[148:151], v[186:189], v[128:131]
	v_mfma_f32_16x16x32_bf16 v[124:127], v[162:165], v[186:189], v[124:127]
	v_mfma_f32_16x16x32_bf16 v[112:115], v[148:151], v[200:203], v[112:115]
	v_mfma_f32_16x16x32_bf16 v[108:111], v[162:165], v[200:203], v[108:111]
	v_mfma_f32_16x16x32_bf16 v[96:99], v[148:151], v[208:211], v[96:99]
	v_mfma_f32_16x16x32_bf16 v[92:95], v[162:165], v[208:211], v[92:95]
	v_mfma_f32_16x16x32_bf16 v[80:83], v[148:151], v[216:219], v[80:83]
	v_mfma_f32_16x16x32_bf16 v[76:79], v[162:165], v[216:219], v[76:79]
	s_setprio 0
	s_setprio 1
	v_mfma_f32_16x16x32_bf16 v[120:123], v[166:169], v[182:185], v[120:123]
	v_mfma_f32_16x16x32_bf16 v[116:119], v[174:177], v[182:185], v[116:119]
	v_mfma_f32_16x16x32_bf16 v[104:107], v[166:169], v[190:193], v[104:107]
	v_mfma_f32_16x16x32_bf16 v[100:103], v[174:177], v[190:193], v[100:103]
	v_mfma_f32_16x16x32_bf16 v[88:91], v[166:169], v[204:207], v[88:91]
	v_mfma_f32_16x16x32_bf16 v[84:87], v[174:177], v[204:207], v[84:87]
	v_mfma_f32_16x16x32_bf16 v[72:75], v[166:169], v[212:215], v[72:75]
	v_mfma_f32_16x16x32_bf16 v[68:71], v[174:177], v[212:215], v[68:71]
	v_mfma_f32_16x16x32_bf16 v[120:123], v[170:173], v[186:189], v[120:123]
	v_mfma_f32_16x16x32_bf16 v[116:119], v[178:181], v[186:189], v[116:119]
	v_mfma_f32_16x16x32_bf16 v[104:107], v[170:173], v[200:203], v[104:107]
	v_mfma_f32_16x16x32_bf16 v[100:103], v[178:181], v[200:203], v[100:103]
	v_mfma_f32_16x16x32_bf16 v[88:91], v[170:173], v[208:211], v[88:91]
	v_mfma_f32_16x16x32_bf16 v[84:87], v[178:181], v[208:211], v[84:87]
	v_mfma_f32_16x16x32_bf16 v[72:75], v[170:173], v[216:219], v[72:75]
	v_mfma_f32_16x16x32_bf16 v[68:71], v[178:181], v[216:219], v[68:71]
	s_barrier
	s_setprio 0
	s_add_i32 s0, s0, s25
	v_lshl_add_u64 v[194:195], v[194:195], 0, s[90:91]
	s_mov_b32 m0, s0
	ds_read_b128 v[182:185], v161 offset:49152
	ds_read_b128 v[186:189], v161 offset:50176
	ds_read_b128 v[190:193], v161 offset:51200
	ds_read_b128 v[200:203], v161 offset:52224
	ds_read_b128 v[204:207], v161 offset:53248
	ds_read_b128 v[208:211], v161 offset:54272
	ds_read_b128 v[212:215], v161 offset:55296
	ds_read_b128 v[216:219], v161 offset:56320
	global_load_lds_dwordx4 v[194:195], off
	s_add_i32 m0, s0, 0x2000
	s_add_u32 s30, s30, 0x80080
	v_lshl_add_u64 v[194:195], v[198:199], 0, s[90:91]
	s_addc_u32 s31, s31, 0
	s_add_i32 s0, s6, s25
	global_load_lds_dwordx4 v[194:195], off
	v_lshl_add_u64 v[194:195], s[30:31], 0, v[136:137]
	s_mov_b32 m0, s0
	s_nop 0
	global_load_lds_dwordx4 v[194:195], off
	v_lshl_add_u64 v[194:195], s[30:31], 0, v[132:133]
	s_add_i32 m0, s0, 0x2000
	s_nop 0
	global_load_lds_dwordx4 v[194:195], off
	v_lshl_add_u64 v[194:195], v[220:221], 0, s[90:91]
	s_mov_b32 m0, s55
	s_nop 0
	global_load_lds_dwordx4 v[194:195], off
	v_lshl_add_u64 v[194:195], v[222:223], 0, s[90:91]
	s_mov_b32 m0, s60
	s_nop 0
	global_load_lds_dwordx4 v[194:195], off
	s_waitcnt vmcnt(8)
	s_waitcnt lgkmcnt(0)
	s_setprio 1
	s_barrier
	v_mfma_f32_16x16x32_bf16 v[64:67], v[144:147], v[182:185], v[64:67]
	v_mfma_f32_16x16x32_bf16 v[60:63], v[152:155], v[182:185], v[60:63]
	v_mfma_f32_16x16x32_bf16 v[48:51], v[144:147], v[190:193], v[48:51]
	v_mfma_f32_16x16x32_bf16 v[44:47], v[152:155], v[190:193], v[44:47]
	v_mfma_f32_16x16x32_bf16 v[32:35], v[144:147], v[204:207], v[32:35]
	v_mfma_f32_16x16x32_bf16 v[28:31], v[152:155], v[204:207], v[28:31]
	v_mfma_f32_16x16x32_bf16 v[16:19], v[144:147], v[212:215], v[16:19]
	v_mfma_f32_16x16x32_bf16 v[12:15], v[152:155], v[212:215], v[12:15]
	v_mfma_f32_16x16x32_bf16 v[64:67], v[148:151], v[186:189], v[64:67]
	v_mfma_f32_16x16x32_bf16 v[60:63], v[162:165], v[186:189], v[60:63]
	v_mfma_f32_16x16x32_bf16 v[48:51], v[148:151], v[200:203], v[48:51]
	v_mfma_f32_16x16x32_bf16 v[44:47], v[162:165], v[200:203], v[44:47]
	v_mfma_f32_16x16x32_bf16 v[32:35], v[148:151], v[208:211], v[32:35]
	v_mfma_f32_16x16x32_bf16 v[28:31], v[162:165], v[208:211], v[28:31]
	v_mfma_f32_16x16x32_bf16 v[16:19], v[148:151], v[216:219], v[16:19]
	v_mfma_f32_16x16x32_bf16 v[12:15], v[162:165], v[216:219], v[12:15]
	s_setprio 0
	s_setprio 1
	v_mfma_f32_16x16x32_bf16 v[56:59], v[166:169], v[182:185], v[56:59]
	v_mfma_f32_16x16x32_bf16 v[52:55], v[174:177], v[182:185], v[52:55]
	v_mfma_f32_16x16x32_bf16 v[40:43], v[166:169], v[190:193], v[40:43]
	v_mfma_f32_16x16x32_bf16 v[36:39], v[174:177], v[190:193], v[36:39]
	v_mfma_f32_16x16x32_bf16 v[24:27], v[166:169], v[204:207], v[24:27]
	v_mfma_f32_16x16x32_bf16 v[20:23], v[174:177], v[204:207], v[20:23]
	v_mfma_f32_16x16x32_bf16 v[8:11], v[166:169], v[212:215], v[8:11]
	v_mfma_f32_16x16x32_bf16 v[4:7], v[174:177], v[212:215], v[4:7]
	v_mfma_f32_16x16x32_bf16 v[56:59], v[170:173], v[186:189], v[56:59]
	v_mfma_f32_16x16x32_bf16 v[52:55], v[178:181], v[186:189], v[52:55]
	v_mfma_f32_16x16x32_bf16 v[40:43], v[170:173], v[200:203], v[40:43]
	v_mfma_f32_16x16x32_bf16 v[36:39], v[178:181], v[200:203], v[36:39]
	v_mfma_f32_16x16x32_bf16 v[24:27], v[170:173], v[208:211], v[24:27]
	v_mfma_f32_16x16x32_bf16 v[20:23], v[178:181], v[208:211], v[20:23]
	v_mfma_f32_16x16x32_bf16 v[8:11], v[170:173], v[216:219], v[8:11]
	v_mfma_f32_16x16x32_bf16 v[4:7], v[178:181], v[216:219], v[4:7]
	s_barrier
	s_setprio 0
	s_add_i32 s66, s66, 2
	s_add_u32 s36, s36, 0x100
	s_addc_u32 s37, s37, 0
	s_add_u32 s38, s38, 0x100
	s_addc_u32 s39, s39, 0
	s_cmp_gt_u32 s66, 29
	s_cbranch_scc0 .LBB0_1137
	s_and_b64 vcc, exec, s[20:21]
	s_cbranch_vccz .LBB0_1140
	s_barrier

.LBB0_1167:
	s_add_u32 s0, s36, 0xfff80080
	s_addc_u32 s6, s37, -1
	s_add_i32 s49, 0, 0x10000
	s_cmp_eq_u32 s67, 28
	s_cselect_b32 s35, s43, s6
	s_cselect_b32 s34, s65, s0
	v_add_u32_e32 v156, s49, v157
	s_cselect_b32 s31, s29, s39
	s_cselect_b32 s30, s66, s38
	s_add_i32 s0, 0, 0x14000
	ds_read_b128 v[144:147], v156
	ds_read_b128 v[148:151], v156 offset:1024
	ds_read_b128 v[152:155], v156 offset:2048
	ds_read_b128 v[162:165], v156 offset:3072
	v_add_u32_e32 v156, s0, v157
	ds_read_b128 v[166:169], v156
	ds_read_b128 v[170:173], v156 offset:1024
	ds_read_b128 v[174:177], v156 offset:2048
	ds_read_b128 v[178:181], v156 offset:3072
	v_lshl_add_u64 v[194:195], s[36:37], 0, v[140:141]
	s_add_i32 m0, s25, 0xc000
	ds_read_b128 v[182:185], v161
	ds_read_b128 v[186:189], v161 offset:1024
	ds_read_b128 v[190:193], v161 offset:2048
	ds_read_b128 v[200:203], v161 offset:3072
	ds_read_b128 v[204:207], v161 offset:4096
	ds_read_b128 v[208:211], v161 offset:5120
	ds_read_b128 v[212:215], v161 offset:6144
	ds_read_b128 v[216:219], v161 offset:7168
	global_load_lds_dwordx4 v[194:195], off
	v_lshl_add_u64 v[194:195], s[36:37], 0, v[142:143]
	s_add_i32 m0, s25, 0xe000
	s_nop 0
	global_load_lds_dwordx4 v[194:195], off
	s_waitcnt vmcnt(8)
	s_waitcnt lgkmcnt(0)
	s_setprio 1
	s_barrier
	v_mfma_f32_16x16x32_bf16 v[128:131], v[144:147], v[182:185], v[128:131]
	v_mfma_f32_16x16x32_bf16 v[124:127], v[152:155], v[182:185], v[124:127]
	v_mfma_f32_16x16x32_bf16 v[112:115], v[144:147], v[190:193], v[112:115]
	v_mfma_f32_16x16x32_bf16 v[108:111], v[152:155], v[190:193], v[108:111]
	v_mfma_f32_16x16x32_bf16 v[96:99], v[144:147], v[204:207], v[96:99]
	v_mfma_f32_16x16x32_bf16 v[92:95], v[152:155], v[204:207], v[92:95]
	v_mfma_f32_16x16x32_bf16 v[80:83], v[144:147], v[212:215], v[80:83]
	v_mfma_f32_16x16x32_bf16 v[76:79], v[152:155], v[212:215], v[76:79]
	v_mfma_f32_16x16x32_bf16 v[128:131], v[148:151], v[186:189], v[128:131]
	v_mfma_f32_16x16x32_bf16 v[124:127], v[162:165], v[186:189], v[124:127]
	v_mfma_f32_16x16x32_bf16 v[112:115], v[148:151], v[200:203], v[112:115]
	v_mfma_f32_16x16x32_bf16 v[108:111], v[162:165], v[200:203], v[108:111]
	v_mfma_f32_16x16x32_bf16 v[96:99], v[148:151], v[208:211], v[96:99]
	v_mfma_f32_16x16x32_bf16 v[92:95], v[162:165], v[208:211], v[92:95]
	v_mfma_f32_16x16x32_bf16 v[80:83], v[148:151], v[216:219], v[80:83]
	v_mfma_f32_16x16x32_bf16 v[76:79], v[162:165], v[216:219], v[76:79]
	s_setprio 0
	s_setprio 1
	v_mfma_f32_16x16x32_bf16 v[120:123], v[166:169], v[182:185], v[120:123]
	v_mfma_f32_16x16x32_bf16 v[116:119], v[174:177], v[182:185], v[116:119]
	v_mfma_f32_16x16x32_bf16 v[104:107], v[166:169], v[190:193], v[104:107]
	v_mfma_f32_16x16x32_bf16 v[100:103], v[174:177], v[190:193], v[100:103]
	v_mfma_f32_16x16x32_bf16 v[88:91], v[166:169], v[204:207], v[88:91]
	v_mfma_f32_16x16x32_bf16 v[84:87], v[174:177], v[204:207], v[84:87]
	v_mfma_f32_16x16x32_bf16 v[72:75], v[166:169], v[212:215], v[72:75]
	v_mfma_f32_16x16x32_bf16 v[68:71], v[174:177], v[212:215], v[68:71]
	v_mfma_f32_16x16x32_bf16 v[120:123], v[170:173], v[186:189], v[120:123]
	v_mfma_f32_16x16x32_bf16 v[116:119], v[178:181], v[186:189], v[116:119]
	v_mfma_f32_16x16x32_bf16 v[104:107], v[170:173], v[200:203], v[104:107]
	v_mfma_f32_16x16x32_bf16 v[100:103], v[178:181], v[200:203], v[100:103]
	v_mfma_f32_16x16x32_bf16 v[88:91], v[170:173], v[208:211], v[88:91]
	v_mfma_f32_16x16x32_bf16 v[84:87], v[178:181], v[208:211], v[84:87]
	v_mfma_f32_16x16x32_bf16 v[72:75], v[170:173], v[216:219], v[72:75]
	v_mfma_f32_16x16x32_bf16 v[68:71], v[178:181], v[216:219], v[68:71]
	s_barrier
	s_setprio 0
	s_add_i32 s6, s49, s1
	v_lshl_add_u64 v[194:195], s[30:31], 0, v[136:137]
	s_mov_b32 m0, s6
	ds_read_b128 v[182:185], v161 offset:16384
	ds_read_b128 v[186:189], v161 offset:17408
	ds_read_b128 v[190:193], v161 offset:18432
	ds_read_b128 v[200:203], v161 offset:19456
	ds_read_b128 v[204:207], v161 offset:20480
	ds_read_b128 v[208:211], v161 offset:21504
	ds_read_b128 v[212:215], v161 offset:22528
	ds_read_b128 v[216:219], v161 offset:23552
	global_load_lds_dwordx4 v[194:195], off
	s_add_i32 m0, s6, 0x2000
	s_add_u32 s68, s30, 0x80000
	v_lshl_add_u64 v[198:199], s[30:31], 0, v[132:133]
	s_addc_u32 s69, s31, 0
	s_add_i32 s0, s0, s1
	global_load_lds_dwordx4 v[198:199], off
	v_lshl_add_u64 v[220:221], s[68:69], 0, v[136:137]
	s_mov_b32 m0, s0
	v_lshl_add_u64 v[222:223], s[34:35], 0, v[134:135]
	global_load_lds_dwordx4 v[220:221], off
	v_lshl_add_u64 v[220:221], s[68:69], 0, v[132:133]
	s_add_i32 m0, s0, 0x2000
	s_nop 0
	global_load_lds_dwordx4 v[220:221], off
	v_lshl_add_u64 v[220:221], s[34:35], 0, v[138:139]
	s_mov_b32 m0, s25
	s_nop 0
	global_load_lds_dwordx4 v[220:221], off
	s_mov_b32 m0, s33
	s_nop 0
	global_load_lds_dwordx4 v[222:223], off
	s_waitcnt vmcnt(8)
	s_waitcnt lgkmcnt(0)
	s_setprio 1
	s_barrier
	v_mfma_f32_16x16x32_bf16 v[64:67], v[144:147], v[182:185], v[64:67]
	v_mfma_f32_16x16x32_bf16 v[60:63], v[152:155], v[182:185], v[60:63]
	v_mfma_f32_16x16x32_bf16 v[48:51], v[144:147], v[190:193], v[48:51]
	v_mfma_f32_16x16x32_bf16 v[44:47], v[152:155], v[190:193], v[44:47]
	v_mfma_f32_16x16x32_bf16 v[32:35], v[144:147], v[204:207], v[32:35]
	v_mfma_f32_16x16x32_bf16 v[28:31], v[152:155], v[204:207], v[28:31]
	v_mfma_f32_16x16x32_bf16 v[16:19], v[144:147], v[212:215], v[16:19]
	v_mfma_f32_16x16x32_bf16 v[12:15], v[152:155], v[212:215], v[12:15]
	v_mfma_f32_16x16x32_bf16 v[64:67], v[148:151], v[186:189], v[64:67]
	v_mfma_f32_16x16x32_bf16 v[60:63], v[162:165], v[186:189], v[60:63]
	v_mfma_f32_16x16x32_bf16 v[48:51], v[148:151], v[200:203], v[48:51]
	v_mfma_f32_16x16x32_bf16 v[44:47], v[162:165], v[200:203], v[44:47]
	v_mfma_f32_16x16x32_bf16 v[32:35], v[148:151], v[208:211], v[32:35]
	v_mfma_f32_16x16x32_bf16 v[28:31], v[162:165], v[208:211], v[28:31]
	v_mfma_f32_16x16x32_bf16 v[16:19], v[148:151], v[216:219], v[16:19]
	v_mfma_f32_16x16x32_bf16 v[12:15], v[162:165], v[216:219], v[12:15]
	s_setprio 0
	s_setprio 1
	v_mfma_f32_16x16x32_bf16 v[56:59], v[166:169], v[182:185], v[56:59]
	v_mfma_f32_16x16x32_bf16 v[52:55], v[174:177], v[182:185], v[52:55]
	v_mfma_f32_16x16x32_bf16 v[40:43], v[166:169], v[190:193], v[40:43]
	v_mfma_f32_16x16x32_bf16 v[36:39], v[174:177], v[190:193], v[36:39]
	v_mfma_f32_16x16x32_bf16 v[24:27], v[166:169], v[204:207], v[24:27]
	v_mfma_f32_16x16x32_bf16 v[20:23], v[174:177], v[204:207], v[20:23]
	v_mfma_f32_16x16x32_bf16 v[8:11], v[166:169], v[212:215], v[8:11]
	v_mfma_f32_16x16x32_bf16 v[4:7], v[174:177], v[212:215], v[4:7]
	v_mfma_f32_16x16x32_bf16 v[56:59], v[170:173], v[186:189], v[56:59]
	v_mfma_f32_16x16x32_bf16 v[52:55], v[178:181], v[186:189], v[52:55]
	v_mfma_f32_16x16x32_bf16 v[40:43], v[170:173], v[200:203], v[40:43]
	v_mfma_f32_16x16x32_bf16 v[36:39], v[178:181], v[200:203], v[36:39]
	v_mfma_f32_16x16x32_bf16 v[24:27], v[170:173], v[208:211], v[24:27]
	v_mfma_f32_16x16x32_bf16 v[20:23], v[178:181], v[208:211], v[20:23]
	v_mfma_f32_16x16x32_bf16 v[8:11], v[170:173], v[216:219], v[8:11]
	v_mfma_f32_16x16x32_bf16 v[4:7], v[178:181], v[216:219], v[4:7]
	s_barrier
	s_setprio 0
	s_add_i32 s0, 0, 0x18000
	v_add_u32_e32 v156, s0, v157
	s_add_i32 s6, 0, 0x1c000
	ds_read_b128 v[144:147], v156
	ds_read_b128 v[148:151], v156 offset:1024
	ds_read_b128 v[152:155], v156 offset:2048
	ds_read_b128 v[162:165], v156 offset:3072
	v_add_u32_e32 v156, s6, v157
	ds_read_b128 v[166:169], v156
	ds_read_b128 v[170:173], v156 offset:1024
	ds_read_b128 v[174:177], v156 offset:2048
	ds_read_b128 v[178:181], v156 offset:3072
	s_add_u32 s34, s34, 0x80000
	s_addc_u32 s35, s35, 0
	s_mov_b32 m0, s40
	v_lshl_add_u64 v[224:225], s[34:35], 0, v[138:139]
	ds_read_b128 v[182:185], v161 offset:32768
	ds_read_b128 v[186:189], v161 offset:33792
	ds_read_b128 v[190:193], v161 offset:34816
	ds_read_b128 v[200:203], v161 offset:35840
	ds_read_b128 v[204:207], v161 offset:36864
	ds_read_b128 v[208:211], v161 offset:37888
	ds_read_b128 v[212:215], v161 offset:38912
	ds_read_b128 v[216:219], v161 offset:39936
	global_load_lds_dwordx4 v[224:225], off
	v_lshl_add_u64 v[224:225], s[34:35], 0, v[134:135]
	s_mov_b32 m0, s50
	s_nop 0
	global_load_lds_dwordx4 v[224:225], off
	s_waitcnt vmcnt(8)
	s_waitcnt lgkmcnt(0)
	s_setprio 1
	s_barrier
	v_mfma_f32_16x16x32_bf16 v[128:131], v[144:147], v[182:185], v[128:131]
	v_mfma_f32_16x16x32_bf16 v[124:127], v[152:155], v[182:185], v[124:127]
	v_mfma_f32_16x16x32_bf16 v[112:115], v[144:147], v[190:193], v[112:115]
	v_mfma_f32_16x16x32_bf16 v[108:111], v[152:155], v[190:193], v[108:111]
	v_mfma_f32_16x16x32_bf16 v[96:99], v[144:147], v[204:207], v[96:99]
	v_mfma_f32_16x16x32_bf16 v[92:95], v[152:155], v[204:207], v[92:95]
	v_mfma_f32_16x16x32_bf16 v[80:83], v[144:147], v[212:215], v[80:83]
	v_mfma_f32_16x16x32_bf16 v[76:79], v[152:155], v[212:215], v[76:79]
	v_mfma_f32_16x16x32_bf16 v[128:131], v[148:151], v[186:189], v[128:131]
	v_mfma_f32_16x16x32_bf16 v[124:127], v[162:165], v[186:189], v[124:127]
	v_mfma_f32_16x16x32_bf16 v[112:115], v[148:151], v[200:203], v[112:115]
	v_mfma_f32_16x16x32_bf16 v[108:111], v[162:165], v[200:203], v[108:111]
	v_mfma_f32_16x16x32_bf16 v[96:99], v[148:151], v[208:211], v[96:99]
	v_mfma_f32_16x16x32_bf16 v[92:95], v[162:165], v[208:211], v[92:95]
	v_mfma_f32_16x16x32_bf16 v[80:83], v[148:151], v[216:219], v[80:83]
	v_mfma_f32_16x16x32_bf16 v[76:79], v[162:165], v[216:219], v[76:79]
	s_setprio 0
	s_setprio 1
	v_mfma_f32_16x16x32_bf16 v[120:123], v[166:169], v[182:185], v[120:123]
	v_mfma_f32_16x16x32_bf16 v[116:119], v[174:177], v[182:185], v[116:119]
	v_mfma_f32_16x16x32_bf16 v[104:107], v[166:169], v[190:193], v[104:107]
	v_mfma_f32_16x16x32_bf16 v[100:103], v[174:177], v[190:193], v[100:103]
	v_mfma_f32_16x16x32_bf16 v[88:91], v[166:169], v[204:207], v[88:91]
	v_mfma_f32_16x16x32_bf16 v[84:87], v[174:177], v[204:207], v[84:87]
	v_mfma_f32_16x16x32_bf16 v[72:75], v[166:169], v[212:215], v[72:75]
	v_mfma_f32_16x16x32_bf16 v[68:71], v[174:177], v[212:215], v[68:71]
	v_mfma_f32_16x16x32_bf16 v[120:123], v[170:173], v[186:189], v[120:123]
	v_mfma_f32_16x16x32_bf16 v[116:119], v[178:181], v[186:189], v[116:119]
	v_mfma_f32_16x16x32_bf16 v[104:107], v[170:173], v[200:203], v[104:107]
	v_mfma_f32_16x16x32_bf16 v[100:103], v[178:181], v[200:203], v[100:103]
	v_mfma_f32_16x16x32_bf16 v[88:91], v[170:173], v[208:211], v[88:91]
	v_mfma_f32_16x16x32_bf16 v[84:87], v[178:181], v[208:211], v[84:87]
	v_mfma_f32_16x16x32_bf16 v[72:75], v[170:173], v[216:219], v[72:75]
	v_mfma_f32_16x16x32_bf16 v[68:71], v[178:181], v[216:219], v[68:71]
	s_barrier
	s_setprio 0
	s_add_i32 s0, s0, s1
	v_lshl_add_u64 v[194:195], v[194:195], 0, s[90:91]
	s_mov_b32 m0, s0
	ds_read_b128 v[182:185], v161 offset:49152
	ds_read_b128 v[186:189], v161 offset:50176
	ds_read_b128 v[190:193], v161 offset:51200
	ds_read_b128 v[200:203], v161 offset:52224
	ds_read_b128 v[204:207], v161 offset:53248
	ds_read_b128 v[208:211], v161 offset:54272
	ds_read_b128 v[212:215], v161 offset:55296
	ds_read_b128 v[216:219], v161 offset:56320
	global_load_lds_dwordx4 v[194:195], off
	s_add_i32 m0, s0, 0x2000
	s_add_u32 s30, s30, 0x80080
	v_lshl_add_u64 v[194:195], v[198:199], 0, s[90:91]
	s_addc_u32 s31, s31, 0
	s_add_i32 s0, s6, s1
	global_load_lds_dwordx4 v[194:195], off
	v_lshl_add_u64 v[194:195], s[30:31], 0, v[136:137]
	s_mov_b32 m0, s0
	s_nop 0
	global_load_lds_dwordx4 v[194:195], off
	v_lshl_add_u64 v[194:195], s[30:31], 0, v[132:133]
	s_add_i32 m0, s0, 0x2000
	s_nop 0
	global_load_lds_dwordx4 v[194:195], off
	v_lshl_add_u64 v[194:195], v[220:221], 0, s[90:91]
	s_mov_b32 m0, s51
	s_nop 0
	global_load_lds_dwordx4 v[194:195], off
	v_lshl_add_u64 v[194:195], v[222:223], 0, s[90:91]
	s_mov_b32 m0, s55
	s_nop 0
	global_load_lds_dwordx4 v[194:195], off
	s_waitcnt vmcnt(8)
	s_waitcnt lgkmcnt(0)
	s_setprio 1
	s_barrier
	v_mfma_f32_16x16x32_bf16 v[64:67], v[144:147], v[182:185], v[64:67]
	v_mfma_f32_16x16x32_bf16 v[60:63], v[152:155], v[182:185], v[60:63]
	v_mfma_f32_16x16x32_bf16 v[48:51], v[144:147], v[190:193], v[48:51]
	v_mfma_f32_16x16x32_bf16 v[44:47], v[152:155], v[190:193], v[44:47]
	v_mfma_f32_16x16x32_bf16 v[32:35], v[144:147], v[204:207], v[32:35]
	v_mfma_f32_16x16x32_bf16 v[28:31], v[152:155], v[204:207], v[28:31]
	v_mfma_f32_16x16x32_bf16 v[16:19], v[144:147], v[212:215], v[16:19]
	v_mfma_f32_16x16x32_bf16 v[12:15], v[152:155], v[212:215], v[12:15]
	v_mfma_f32_16x16x32_bf16 v[64:67], v[148:151], v[186:189], v[64:67]
	v_mfma_f32_16x16x32_bf16 v[60:63], v[162:165], v[186:189], v[60:63]
	v_mfma_f32_16x16x32_bf16 v[48:51], v[148:151], v[200:203], v[48:51]
	v_mfma_f32_16x16x32_bf16 v[44:47], v[162:165], v[200:203], v[44:47]
	v_mfma_f32_16x16x32_bf16 v[32:35], v[148:151], v[208:211], v[32:35]
	v_mfma_f32_16x16x32_bf16 v[28:31], v[162:165], v[208:211], v[28:31]
	v_mfma_f32_16x16x32_bf16 v[16:19], v[148:151], v[216:219], v[16:19]
	v_mfma_f32_16x16x32_bf16 v[12:15], v[162:165], v[216:219], v[12:15]
	s_setprio 0
	s_setprio 1
	v_mfma_f32_16x16x32_bf16 v[56:59], v[166:169], v[182:185], v[56:59]
	v_mfma_f32_16x16x32_bf16 v[52:55], v[174:177], v[182:185], v[52:55]
	v_mfma_f32_16x16x32_bf16 v[40:43], v[166:169], v[190:193], v[40:43]
	v_mfma_f32_16x16x32_bf16 v[36:39], v[174:177], v[190:193], v[36:39]
	v_mfma_f32_16x16x32_bf16 v[24:27], v[166:169], v[204:207], v[24:27]
	v_mfma_f32_16x16x32_bf16 v[20:23], v[174:177], v[204:207], v[20:23]
	v_mfma_f32_16x16x32_bf16 v[8:11], v[166:169], v[212:215], v[8:11]
	v_mfma_f32_16x16x32_bf16 v[4:7], v[174:177], v[212:215], v[4:7]
	v_mfma_f32_16x16x32_bf16 v[56:59], v[170:173], v[186:189], v[56:59]
	v_mfma_f32_16x16x32_bf16 v[52:55], v[178:181], v[186:189], v[52:55]
	v_mfma_f32_16x16x32_bf16 v[40:43], v[170:173], v[200:203], v[40:43]
	v_mfma_f32_16x16x32_bf16 v[36:39], v[178:181], v[200:203], v[36:39]
	v_mfma_f32_16x16x32_bf16 v[24:27], v[170:173], v[208:211], v[24:27]
	v_mfma_f32_16x16x32_bf16 v[20:23], v[178:181], v[208:211], v[20:23]
	v_mfma_f32_16x16x32_bf16 v[8:11], v[170:173], v[216:219], v[8:11]
	v_mfma_f32_16x16x32_bf16 v[4:7], v[178:181], v[216:219], v[4:7]
	s_barrier
	s_setprio 0
	s_add_i32 s67, s67, 2
	s_add_u32 s36, s36, 0x100
	s_addc_u32 s37, s37, 0
	s_add_u32 s38, s38, 0x100
	s_addc_u32 s39, s39, 0
	s_cmp_gt_u32 s67, 29
	s_cbranch_scc0 .LBB0_1167
	s_and_b64 vcc, exec, s[20:21]
	s_cbranch_vccz .LBB0_1170
	s_barrier

.LBB0_1186:
	s_add_u32 s0, s64, s30
	s_addc_u32 s6, s65, 0
	s_add_u32 s31, s0, 0x100
	s_addc_u32 s38, s6, 0
	s_and_b64 s[34:35], s[36:37], exec
	s_cselect_b32 s69, s29, s38
	s_cselect_b32 s68, s77, s31
	s_add_u32 s30, s62, s30
	s_addc_u32 s31, s63, 0
	s_add_u32 s34, s30, 0x100
	s_addc_u32 s35, s31, 0
	s_add_i32 s82, 0, 0x10000
	s_and_b64 s[30:31], s[36:37], exec
	s_cselect_b32 s53, s23, s35
	s_cselect_b32 s52, s78, s34
	s_add_i32 s37, 0, 0x14000
	s_add_u32 s34, s0, 0x10080
	s_addc_u32 s35, s6, 0
	s_add_i32 s84, s82, s4
	s_add_i32 m0, s46, 0xc000
	s_add_i32 s85, s46, 0xe000
	s_add_i32 s6, s84, 0x2000
	v_add_u32_e32 v140, s82, v142
	s_add_u32 s30, s52, 0x10000
	ds_read_b128 v[146:149], v140
	ds_read_b128 v[150:153], v140 offset:1024
	ds_read_b128 v[154:157], v140 offset:2048
	ds_read_b128 v[158:161], v140 offset:3072
	v_add_u32_e32 v140, s37, v142
	s_addc_u32 s31, s53, 0
	s_add_i32 s49, s37, s4
	ds_read_b128 v[162:165], v140
	ds_read_b128 v[166:169], v140 offset:1024
	ds_read_b128 v[170:173], v140 offset:2048
	ds_read_b128 v[174:177], v140 offset:3072
	s_add_i32 s81, s49, 0x2000
	s_add_i32 s54, 0, 0x18000
	s_add_i32 s73, 0, 0x1c000
	s_add_u32 s38, s68, 0x10000
	s_addc_u32 s39, s69, 0
	s_add_i32 s0, s54, s4
	s_add_i32 s80, s0, 0x2000
	s_add_u32 s36, s52, 0x10080
	s_addc_u32 s37, s53, 0
	s_add_i32 s83, s73, s4
	s_add_i32 s82, s83, 0x2000
	v_lshl_add_u64 v[140:141], s[34:35], 0, v[138:139]
	ds_read_b128 v[178:181], v144
	ds_read_b128 v[182:185], v144 offset:1024
	ds_read_b128 v[186:189], v144 offset:2048
	ds_read_b128 v[190:193], v144 offset:3072
	ds_read_b128 v[200:203], v144 offset:4096
	ds_read_b128 v[204:207], v144 offset:5120
	ds_read_b128 v[208:211], v144 offset:6144
	ds_read_b128 v[212:215], v144 offset:7168
	global_load_lds_dwordx4 v[140:141], off
	v_lshl_add_u64 v[140:141], s[34:35], 0, v[134:135]
	s_mov_b32 m0, s85
	s_nop 0
	global_load_lds_dwordx4 v[140:141], off
	s_waitcnt vmcnt(8)
	s_waitcnt lgkmcnt(0)
	s_setprio 1
	s_barrier
	v_mfma_f32_16x16x32_bf16 v[128:131], v[146:149], v[178:181], v[128:131]
	v_mfma_f32_16x16x32_bf16 v[124:127], v[154:157], v[178:181], v[124:127]
	v_mfma_f32_16x16x32_bf16 v[120:123], v[146:149], v[186:189], v[120:123]
	v_mfma_f32_16x16x32_bf16 v[112:115], v[154:157], v[186:189], v[112:115]
	v_mfma_f32_16x16x32_bf16 v[104:107], v[146:149], v[200:203], v[104:107]
	v_mfma_f32_16x16x32_bf16 v[96:99], v[154:157], v[200:203], v[96:99]
	v_mfma_f32_16x16x32_bf16 v[88:91], v[146:149], v[208:211], v[88:91]
	v_mfma_f32_16x16x32_bf16 v[80:83], v[154:157], v[208:211], v[80:83]
	v_mfma_f32_16x16x32_bf16 v[128:131], v[150:153], v[182:185], v[128:131]
	v_mfma_f32_16x16x32_bf16 v[124:127], v[158:161], v[182:185], v[124:127]
	v_mfma_f32_16x16x32_bf16 v[120:123], v[150:153], v[190:193], v[120:123]
	v_mfma_f32_16x16x32_bf16 v[112:115], v[158:161], v[190:193], v[112:115]
	v_mfma_f32_16x16x32_bf16 v[104:107], v[150:153], v[204:207], v[104:107]
	v_mfma_f32_16x16x32_bf16 v[96:99], v[158:161], v[204:207], v[96:99]
	v_mfma_f32_16x16x32_bf16 v[88:91], v[150:153], v[212:215], v[88:91]
	v_mfma_f32_16x16x32_bf16 v[80:83], v[158:161], v[212:215], v[80:83]
	s_setprio 0
	s_setprio 1
	v_mfma_f32_16x16x32_bf16 v[116:119], v[162:165], v[178:181], v[116:119]
	v_mfma_f32_16x16x32_bf16 v[108:111], v[170:173], v[178:181], v[108:111]
	v_mfma_f32_16x16x32_bf16 v[100:103], v[162:165], v[186:189], v[100:103]
	v_mfma_f32_16x16x32_bf16 v[92:95], v[170:173], v[186:189], v[92:95]
	v_mfma_f32_16x16x32_bf16 v[84:87], v[162:165], v[200:203], v[84:87]
	v_mfma_f32_16x16x32_bf16 v[76:79], v[170:173], v[200:203], v[76:79]
	v_mfma_f32_16x16x32_bf16 v[72:75], v[162:165], v[208:211], v[72:75]
	v_mfma_f32_16x16x32_bf16 v[68:71], v[170:173], v[208:211], v[68:71]
	v_mfma_f32_16x16x32_bf16 v[116:119], v[166:169], v[182:185], v[116:119]
	v_mfma_f32_16x16x32_bf16 v[108:111], v[174:177], v[182:185], v[108:111]
	v_mfma_f32_16x16x32_bf16 v[100:103], v[166:169], v[190:193], v[100:103]
	v_mfma_f32_16x16x32_bf16 v[92:95], v[174:177], v[190:193], v[92:95]
	v_mfma_f32_16x16x32_bf16 v[84:87], v[166:169], v[204:207], v[84:87]
	v_mfma_f32_16x16x32_bf16 v[76:79], v[174:177], v[204:207], v[76:79]
	v_mfma_f32_16x16x32_bf16 v[72:75], v[166:169], v[212:215], v[72:75]
	v_mfma_f32_16x16x32_bf16 v[68:71], v[174:177], v[212:215], v[68:71]
	s_barrier
	s_setprio 0
	s_mov_b32 m0, s84
	v_lshl_add_u64 v[140:141], s[52:53], 0, v[136:137]
	ds_read_b128 v[178:181], v144 offset:16384
	ds_read_b128 v[182:185], v144 offset:17408
	ds_read_b128 v[186:189], v144 offset:18432
	ds_read_b128 v[190:193], v144 offset:19456
	ds_read_b128 v[200:203], v144 offset:20480
	ds_read_b128 v[204:207], v144 offset:21504
	ds_read_b128 v[208:211], v144 offset:22528
	ds_read_b128 v[212:215], v144 offset:23552
	global_load_lds_dwordx4 v[140:141], off
	v_lshl_add_u64 v[194:195], s[52:53], 0, v[132:133]
	s_mov_b32 m0, s6
	v_lshl_add_u64 v[198:199], s[30:31], 0, v[136:137]
	global_load_lds_dwordx4 v[194:195], off
	s_mov_b32 m0, s49
	v_lshl_add_u64 v[216:217], s[68:69], 0, v[134:135]
	global_load_lds_dwordx4 v[198:199], off
	v_lshl_add_u64 v[198:199], s[30:31], 0, v[132:133]
	s_mov_b32 m0, s81
	s_nop 0
	global_load_lds_dwordx4 v[198:199], off
	v_lshl_add_u64 v[198:199], s[68:69], 0, v[138:139]
	s_mov_b32 m0, s46
	s_nop 0
	global_load_lds_dwordx4 v[198:199], off
	s_mov_b32 m0, s47
	s_nop 0
	global_load_lds_dwordx4 v[216:217], off
	s_waitcnt vmcnt(8)
	s_waitcnt lgkmcnt(0)
	s_setprio 1
	s_barrier
	v_mfma_f32_16x16x32_bf16 v[64:67], v[146:149], v[178:181], v[64:67]
	v_mfma_f32_16x16x32_bf16 v[60:63], v[154:157], v[178:181], v[60:63]
	v_mfma_f32_16x16x32_bf16 v[56:59], v[146:149], v[186:189], v[56:59]
	v_mfma_f32_16x16x32_bf16 v[48:51], v[154:157], v[186:189], v[48:51]
	v_mfma_f32_16x16x32_bf16 v[40:43], v[146:149], v[200:203], v[40:43]
	v_mfma_f32_16x16x32_bf16 v[32:35], v[154:157], v[200:203], v[32:35]
	v_mfma_f32_16x16x32_bf16 v[24:27], v[146:149], v[208:211], v[24:27]
	v_mfma_f32_16x16x32_bf16 v[16:19], v[154:157], v[208:211], v[16:19]
	v_mfma_f32_16x16x32_bf16 v[64:67], v[150:153], v[182:185], v[64:67]
	v_mfma_f32_16x16x32_bf16 v[60:63], v[158:161], v[182:185], v[60:63]
	v_mfma_f32_16x16x32_bf16 v[56:59], v[150:153], v[190:193], v[56:59]
	v_mfma_f32_16x16x32_bf16 v[48:51], v[158:161], v[190:193], v[48:51]
	v_mfma_f32_16x16x32_bf16 v[40:43], v[150:153], v[204:207], v[40:43]
	v_mfma_f32_16x16x32_bf16 v[32:35], v[158:161], v[204:207], v[32:35]
	v_mfma_f32_16x16x32_bf16 v[24:27], v[150:153], v[212:215], v[24:27]
	v_mfma_f32_16x16x32_bf16 v[16:19], v[158:161], v[212:215], v[16:19]
	s_setprio 0
	s_setprio 1
	v_mfma_f32_16x16x32_bf16 v[52:55], v[162:165], v[178:181], v[52:55]
	v_mfma_f32_16x16x32_bf16 v[44:47], v[170:173], v[178:181], v[44:47]
	v_mfma_f32_16x16x32_bf16 v[36:39], v[162:165], v[186:189], v[36:39]
	v_mfma_f32_16x16x32_bf16 v[28:31], v[170:173], v[186:189], v[28:31]
	v_mfma_f32_16x16x32_bf16 v[20:23], v[162:165], v[200:203], v[20:23]
	v_mfma_f32_16x16x32_bf16 v[12:15], v[170:173], v[200:203], v[12:15]
	v_mfma_f32_16x16x32_bf16 v[8:11], v[162:165], v[208:211], v[8:11]
	v_mfma_f32_16x16x32_bf16 v[4:7], v[170:173], v[208:211], v[4:7]
	v_mfma_f32_16x16x32_bf16 v[52:55], v[166:169], v[182:185], v[52:55]
	v_mfma_f32_16x16x32_bf16 v[44:47], v[174:177], v[182:185], v[44:47]
	v_mfma_f32_16x16x32_bf16 v[36:39], v[166:169], v[190:193], v[36:39]
	v_mfma_f32_16x16x32_bf16 v[28:31], v[174:177], v[190:193], v[28:31]
	v_mfma_f32_16x16x32_bf16 v[20:23], v[166:169], v[204:207], v[20:23]
	v_mfma_f32_16x16x32_bf16 v[12:15], v[174:177], v[204:207], v[12:15]
	v_mfma_f32_16x16x32_bf16 v[8:11], v[166:169], v[212:215], v[8:11]
	v_mfma_f32_16x16x32_bf16 v[4:7], v[174:177], v[212:215], v[4:7]
	s_barrier
	s_setprio 0
	v_add_u32_e32 v145, s54, v142
	ds_read_b128 v[146:149], v145
	ds_read_b128 v[150:153], v145 offset:1024
	ds_read_b128 v[154:157], v145 offset:2048
	ds_read_b128 v[158:161], v145 offset:3072
	v_add_u32_e32 v145, s73, v142
	ds_read_b128 v[162:165], v145
	ds_read_b128 v[166:169], v145 offset:1024
	ds_read_b128 v[170:173], v145 offset:2048
	ds_read_b128 v[174:177], v145 offset:3072
	s_mov_b32 m0, s50
	v_lshl_add_u64 v[218:219], s[38:39], 0, v[138:139]
	ds_read_b128 v[178:181], v144 offset:32768
	ds_read_b128 v[182:185], v144 offset:33792
	ds_read_b128 v[186:189], v144 offset:34816
	ds_read_b128 v[190:193], v144 offset:35840
	ds_read_b128 v[200:203], v144 offset:36864
	ds_read_b128 v[204:207], v144 offset:37888
	ds_read_b128 v[208:211], v144 offset:38912
	ds_read_b128 v[212:215], v144 offset:39936
	global_load_lds_dwordx4 v[218:219], off
	v_lshl_add_u64 v[218:219], s[38:39], 0, v[134:135]
	s_mov_b32 m0, s51
	s_nop 0
	global_load_lds_dwordx4 v[218:219], off
	s_waitcnt vmcnt(8)
	s_waitcnt lgkmcnt(0)
	s_setprio 1
	s_barrier
	v_mfma_f32_16x16x32_bf16 v[128:131], v[146:149], v[178:181], v[128:131]
	v_mfma_f32_16x16x32_bf16 v[124:127], v[154:157], v[178:181], v[124:127]
	v_mfma_f32_16x16x32_bf16 v[120:123], v[146:149], v[186:189], v[120:123]
	v_mfma_f32_16x16x32_bf16 v[112:115], v[154:157], v[186:189], v[112:115]
	v_mfma_f32_16x16x32_bf16 v[104:107], v[146:149], v[200:203], v[104:107]
	v_mfma_f32_16x16x32_bf16 v[96:99], v[154:157], v[200:203], v[96:99]
	v_mfma_f32_16x16x32_bf16 v[88:91], v[146:149], v[208:211], v[88:91]
	v_mfma_f32_16x16x32_bf16 v[80:83], v[154:157], v[208:211], v[80:83]
	v_mfma_f32_16x16x32_bf16 v[128:131], v[150:153], v[182:185], v[128:131]
	v_mfma_f32_16x16x32_bf16 v[124:127], v[158:161], v[182:185], v[124:127]
	v_mfma_f32_16x16x32_bf16 v[120:123], v[150:153], v[190:193], v[120:123]
	v_mfma_f32_16x16x32_bf16 v[112:115], v[158:161], v[190:193], v[112:115]
	v_mfma_f32_16x16x32_bf16 v[104:107], v[150:153], v[204:207], v[104:107]
	v_mfma_f32_16x16x32_bf16 v[96:99], v[158:161], v[204:207], v[96:99]
	v_mfma_f32_16x16x32_bf16 v[88:91], v[150:153], v[212:215], v[88:91]
	v_mfma_f32_16x16x32_bf16 v[80:83], v[158:161], v[212:215], v[80:83]
	s_setprio 0
	s_setprio 1
	v_mfma_f32_16x16x32_bf16 v[116:119], v[162:165], v[178:181], v[116:119]
	v_mfma_f32_16x16x32_bf16 v[108:111], v[170:173], v[178:181], v[108:111]
	v_mfma_f32_16x16x32_bf16 v[100:103], v[162:165], v[186:189], v[100:103]
	v_mfma_f32_16x16x32_bf16 v[92:95], v[170:173], v[186:189], v[92:95]
	v_mfma_f32_16x16x32_bf16 v[84:87], v[162:165], v[200:203], v[84:87]
	v_mfma_f32_16x16x32_bf16 v[76:79], v[170:173], v[200:203], v[76:79]
	v_mfma_f32_16x16x32_bf16 v[72:75], v[162:165], v[208:211], v[72:75]
	v_mfma_f32_16x16x32_bf16 v[68:71], v[170:173], v[208:211], v[68:71]
	v_mfma_f32_16x16x32_bf16 v[116:119], v[166:169], v[182:185], v[116:119]
	v_mfma_f32_16x16x32_bf16 v[108:111], v[174:177], v[182:185], v[108:111]
	v_mfma_f32_16x16x32_bf16 v[100:103], v[166:169], v[190:193], v[100:103]
	v_mfma_f32_16x16x32_bf16 v[92:95], v[174:177], v[190:193], v[92:95]
	v_mfma_f32_16x16x32_bf16 v[84:87], v[166:169], v[204:207], v[84:87]
	v_mfma_f32_16x16x32_bf16 v[76:79], v[174:177], v[204:207], v[76:79]
	v_mfma_f32_16x16x32_bf16 v[72:75], v[166:169], v[212:215], v[72:75]
	v_mfma_f32_16x16x32_bf16 v[68:71], v[174:177], v[212:215], v[68:71]
	s_barrier
	s_setprio 0
	s_mov_b32 m0, s0
	v_lshl_add_u64 v[140:141], v[140:141], 0, s[90:91]
	ds_read_b128 v[178:181], v144 offset:49152
	ds_read_b128 v[182:185], v144 offset:50176
	ds_read_b128 v[186:189], v144 offset:51200
	ds_read_b128 v[190:193], v144 offset:52224
	ds_read_b128 v[200:203], v144 offset:53248
	ds_read_b128 v[204:207], v144 offset:54272
	ds_read_b128 v[208:211], v144 offset:55296
	ds_read_b128 v[212:215], v144 offset:56320
	global_load_lds_dwordx4 v[140:141], off
	v_lshl_add_u64 v[140:141], v[194:195], 0, s[90:91]
	s_mov_b32 m0, s80
	s_nop 0
	global_load_lds_dwordx4 v[140:141], off
	v_lshl_add_u64 v[140:141], s[36:37], 0, v[136:137]
	s_mov_b32 m0, s83
	s_nop 0
	global_load_lds_dwordx4 v[140:141], off
	v_lshl_add_u64 v[140:141], s[36:37], 0, v[132:133]
	s_mov_b32 m0, s82
	s_nop 0
	global_load_lds_dwordx4 v[140:141], off
	v_lshl_add_u64 v[140:141], v[198:199], 0, s[90:91]
	s_mov_b32 m0, s61
	s_nop 0
	global_load_lds_dwordx4 v[140:141], off
	v_lshl_add_u64 v[140:141], v[216:217], 0, s[90:91]
	s_mov_b32 m0, s74
	s_nop 0
	global_load_lds_dwordx4 v[140:141], off
	s_waitcnt vmcnt(8)
	s_waitcnt lgkmcnt(0)
	s_setprio 1
	s_barrier
	v_mfma_f32_16x16x32_bf16 v[64:67], v[146:149], v[178:181], v[64:67]
	v_mfma_f32_16x16x32_bf16 v[60:63], v[154:157], v[178:181], v[60:63]
	v_mfma_f32_16x16x32_bf16 v[56:59], v[146:149], v[186:189], v[56:59]
	v_mfma_f32_16x16x32_bf16 v[48:51], v[154:157], v[186:189], v[48:51]
	v_mfma_f32_16x16x32_bf16 v[40:43], v[146:149], v[200:203], v[40:43]
	v_mfma_f32_16x16x32_bf16 v[32:35], v[154:157], v[200:203], v[32:35]
	v_mfma_f32_16x16x32_bf16 v[24:27], v[146:149], v[208:211], v[24:27]
	v_mfma_f32_16x16x32_bf16 v[16:19], v[154:157], v[208:211], v[16:19]
	v_mfma_f32_16x16x32_bf16 v[64:67], v[150:153], v[182:185], v[64:67]
	v_mfma_f32_16x16x32_bf16 v[60:63], v[158:161], v[182:185], v[60:63]
	v_mfma_f32_16x16x32_bf16 v[56:59], v[150:153], v[190:193], v[56:59]
	v_mfma_f32_16x16x32_bf16 v[48:51], v[158:161], v[190:193], v[48:51]
	v_mfma_f32_16x16x32_bf16 v[40:43], v[150:153], v[204:207], v[40:43]
	v_mfma_f32_16x16x32_bf16 v[32:35], v[158:161], v[204:207], v[32:35]
	v_mfma_f32_16x16x32_bf16 v[24:27], v[150:153], v[212:215], v[24:27]
	v_mfma_f32_16x16x32_bf16 v[16:19], v[158:161], v[212:215], v[16:19]
	s_setprio 0
	s_setprio 1
	v_mfma_f32_16x16x32_bf16 v[52:55], v[162:165], v[178:181], v[52:55]
	v_mfma_f32_16x16x32_bf16 v[44:47], v[170:173], v[178:181], v[44:47]
	v_mfma_f32_16x16x32_bf16 v[36:39], v[162:165], v[186:189], v[36:39]
	v_mfma_f32_16x16x32_bf16 v[28:31], v[170:173], v[186:189], v[28:31]
	v_mfma_f32_16x16x32_bf16 v[20:23], v[162:165], v[200:203], v[20:23]
	v_mfma_f32_16x16x32_bf16 v[12:15], v[170:173], v[200:203], v[12:15]
	v_mfma_f32_16x16x32_bf16 v[8:11], v[162:165], v[208:211], v[8:11]
	v_mfma_f32_16x16x32_bf16 v[4:7], v[170:173], v[208:211], v[4:7]
	v_mfma_f32_16x16x32_bf16 v[52:55], v[166:169], v[182:185], v[52:55]
	v_mfma_f32_16x16x32_bf16 v[44:47], v[174:177], v[182:185], v[44:47]
	v_mfma_f32_16x16x32_bf16 v[36:39], v[166:169], v[190:193], v[36:39]
	v_mfma_f32_16x16x32_bf16 v[28:31], v[174:177], v[190:193], v[28:31]
	v_mfma_f32_16x16x32_bf16 v[20:23], v[166:169], v[204:207], v[20:23]
	v_mfma_f32_16x16x32_bf16 v[12:15], v[174:177], v[204:207], v[12:15]
	v_mfma_f32_16x16x32_bf16 v[8:11], v[166:169], v[212:215], v[8:11]
	v_mfma_f32_16x16x32_bf16 v[4:7], v[174:177], v[212:215], v[4:7]
	s_barrier
	s_setprio 0
	s_movk_i32 s30, 0x100
	s_andn2_b64 vcc, exec, s[66:67]
	s_mov_b64 s[36:37], -1
	s_mov_b64 s[66:67], 0
	s_cbranch_vccz .LBB0_1186
	s_and_b64 vcc, exec, s[20:21]
	s_cbranch_vccz .LBB0_1189
	s_barrier

.LBB0_1273:
	s_add_i32 s74, s30, 2
	s_add_u32 s62, s36, 0x100
	s_addc_u32 s63, s37, 0
	s_add_i32 s0, 0, 0x10000
	s_cmp_eq_u32 s29, s30
	s_cselect_b32 s35, s43, s63
	s_cselect_b32 s34, s42, s62
	s_cselect_b32 s31, s45, s72
	s_cselect_b32 s30, s44, s69
	s_add_i32 s6, 0, 0x14000
	v_add_u32_e32 v144, s0, v3
	v_add_u32_e32 v160, s6, v3
	ds_read_b128 v[124:127], v144
	ds_read_b128 v[128:131], v144 offset:1024
	ds_read_b128 v[140:143], v144 offset:2048
	ds_read_b128 v[144:147], v144 offset:3072
	ds_read_b128 v[148:151], v160
	ds_read_b128 v[152:155], v160 offset:1024
	ds_read_b128 v[156:159], v160 offset:2048
	ds_read_b128 v[160:163], v160 offset:3072
	v_lshl_add_u64 v[198:199], s[36:37], 0, v[212:213]
	s_add_i32 m0, s33, 0xc000
	ds_read_b128 v[164:167], v250
	ds_read_b128 v[168:171], v250 offset:1024
	ds_read_b128 v[172:175], v250 offset:2048
	ds_read_b128 v[176:179], v250 offset:3072
	ds_read_b128 v[180:183], v250 offset:4096
	ds_read_b128 v[184:187], v250 offset:5120
	ds_read_b128 v[188:191], v250 offset:6144
	ds_read_b128 v[192:195], v250 offset:7168
	global_load_lds_dwordx4 v[198:199], off
	v_lshl_add_u64 v[198:199], s[36:37], 0, v[214:215]
	s_add_i32 m0, s33, 0xe000
	s_nop 0
	global_load_lds_dwordx4 v[198:199], off
	s_waitcnt vmcnt(8)
	s_waitcnt lgkmcnt(0)
	s_setprio 1
	s_barrier
	v_mfma_f32_16x16x32_bf16 v[136:139], v[124:127], v[164:167], v[136:139]
	v_mfma_f32_16x16x32_bf16 v[132:135], v[140:143], v[164:167], v[132:135]
	v_mfma_f32_16x16x32_bf16 v[112:115], v[124:127], v[172:175], v[112:115]
	v_mfma_f32_16x16x32_bf16 v[108:111], v[140:143], v[172:175], v[108:111]
	v_mfma_f32_16x16x32_bf16 v[96:99], v[124:127], v[180:183], v[96:99]
	v_mfma_f32_16x16x32_bf16 v[92:95], v[140:143], v[180:183], v[92:95]
	v_mfma_f32_16x16x32_bf16 v[80:83], v[124:127], v[188:191], v[80:83]
	v_mfma_f32_16x16x32_bf16 v[76:79], v[140:143], v[188:191], v[76:79]
	v_mfma_f32_16x16x32_bf16 v[136:139], v[128:131], v[168:171], v[136:139]
	v_mfma_f32_16x16x32_bf16 v[132:135], v[144:147], v[168:171], v[132:135]
	v_mfma_f32_16x16x32_bf16 v[112:115], v[128:131], v[176:179], v[112:115]
	v_mfma_f32_16x16x32_bf16 v[108:111], v[144:147], v[176:179], v[108:111]
	v_mfma_f32_16x16x32_bf16 v[96:99], v[128:131], v[184:187], v[96:99]
	v_mfma_f32_16x16x32_bf16 v[92:95], v[144:147], v[184:187], v[92:95]
	v_mfma_f32_16x16x32_bf16 v[80:83], v[128:131], v[192:195], v[80:83]
	v_mfma_f32_16x16x32_bf16 v[76:79], v[144:147], v[192:195], v[76:79]
	s_setprio 0
	s_setprio 1
	v_mfma_f32_16x16x32_bf16 v[120:123], v[148:151], v[164:167], v[120:123]
	v_mfma_f32_16x16x32_bf16 v[116:119], v[156:159], v[164:167], v[116:119]
	v_mfma_f32_16x16x32_bf16 v[104:107], v[148:151], v[172:175], v[104:107]
	v_mfma_f32_16x16x32_bf16 v[100:103], v[156:159], v[172:175], v[100:103]
	v_mfma_f32_16x16x32_bf16 v[88:91], v[148:151], v[180:183], v[88:91]
	v_mfma_f32_16x16x32_bf16 v[84:87], v[156:159], v[180:183], v[84:87]
	v_mfma_f32_16x16x32_bf16 v[72:75], v[148:151], v[188:191], v[72:75]
	v_mfma_f32_16x16x32_bf16 v[68:71], v[156:159], v[188:191], v[68:71]
	v_mfma_f32_16x16x32_bf16 v[120:123], v[152:155], v[168:171], v[120:123]
	v_mfma_f32_16x16x32_bf16 v[116:119], v[160:163], v[168:171], v[116:119]
	v_mfma_f32_16x16x32_bf16 v[104:107], v[152:155], v[176:179], v[104:107]
	v_mfma_f32_16x16x32_bf16 v[100:103], v[160:163], v[176:179], v[100:103]
	v_mfma_f32_16x16x32_bf16 v[88:91], v[152:155], v[184:187], v[88:91]
	v_mfma_f32_16x16x32_bf16 v[84:87], v[160:163], v[184:187], v[84:87]
	v_mfma_f32_16x16x32_bf16 v[72:75], v[152:155], v[192:195], v[72:75]
	v_mfma_f32_16x16x32_bf16 v[68:71], v[160:163], v[192:195], v[68:71]
	s_barrier
	s_setprio 0
	s_add_i32 s0, s0, s27
	v_lshl_add_u64 v[198:199], s[30:31], 0, v[202:203]
	s_mov_b32 m0, s0
	ds_read_b128 v[164:167], v250 offset:16384
	ds_read_b128 v[168:171], v250 offset:17408
	ds_read_b128 v[172:175], v250 offset:18432
	ds_read_b128 v[176:179], v250 offset:19456
	ds_read_b128 v[180:183], v250 offset:20480
	ds_read_b128 v[184:187], v250 offset:21504
	ds_read_b128 v[188:191], v250 offset:22528
	ds_read_b128 v[192:195], v250 offset:23552
	global_load_lds_dwordx4 v[198:199], off
	s_add_i32 m0, s0, 0x2000
	s_add_u32 s36, s30, 0x204000
	v_lshl_add_u64 v[216:217], s[30:31], 0, v[206:207]
	s_addc_u32 s37, s31, 0
	s_add_i32 s0, s6, s27
	global_load_lds_dwordx4 v[216:217], off
	v_lshl_add_u64 v[218:219], s[36:37], 0, v[202:203]
	s_mov_b32 m0, s0
	v_lshl_add_u64 v[220:221], s[34:35], 0, v[204:205]
	global_load_lds_dwordx4 v[218:219], off
	v_lshl_add_u64 v[218:219], s[36:37], 0, v[206:207]
	s_add_i32 m0, s0, 0x2000
	s_nop 0
	global_load_lds_dwordx4 v[218:219], off
	v_lshl_add_u64 v[218:219], s[34:35], 0, v[200:201]
	s_mov_b32 m0, s33
	s_nop 0
	global_load_lds_dwordx4 v[218:219], off
	s_mov_b32 m0, s38
	s_nop 0
	global_load_lds_dwordx4 v[220:221], off
	s_waitcnt vmcnt(8)
	s_waitcnt lgkmcnt(0)
	s_setprio 1
	s_barrier
	v_mfma_f32_16x16x32_bf16 v[64:67], v[124:127], v[164:167], v[64:67]
	v_mfma_f32_16x16x32_bf16 v[60:63], v[140:143], v[164:167], v[60:63]
	v_mfma_f32_16x16x32_bf16 v[48:51], v[124:127], v[172:175], v[48:51]
	v_mfma_f32_16x16x32_bf16 v[44:47], v[140:143], v[172:175], v[44:47]
	v_mfma_f32_16x16x32_bf16 v[32:35], v[124:127], v[180:183], v[32:35]
	v_mfma_f32_16x16x32_bf16 v[28:31], v[140:143], v[180:183], v[28:31]
	v_mfma_f32_16x16x32_bf16 v[16:19], v[124:127], v[188:191], v[16:19]
	v_mfma_f32_16x16x32_bf16 v[12:15], v[140:143], v[188:191], v[12:15]
	v_mfma_f32_16x16x32_bf16 v[64:67], v[128:131], v[168:171], v[64:67]
	v_mfma_f32_16x16x32_bf16 v[60:63], v[144:147], v[168:171], v[60:63]
	v_mfma_f32_16x16x32_bf16 v[48:51], v[128:131], v[176:179], v[48:51]
	v_mfma_f32_16x16x32_bf16 v[44:47], v[144:147], v[176:179], v[44:47]
	v_mfma_f32_16x16x32_bf16 v[32:35], v[128:131], v[184:187], v[32:35]
	v_mfma_f32_16x16x32_bf16 v[28:31], v[144:147], v[184:187], v[28:31]
	v_mfma_f32_16x16x32_bf16 v[16:19], v[128:131], v[192:195], v[16:19]
	v_mfma_f32_16x16x32_bf16 v[12:15], v[144:147], v[192:195], v[12:15]
	s_setprio 0
	s_setprio 1
	v_mfma_f32_16x16x32_bf16 v[56:59], v[148:151], v[164:167], v[56:59]
	v_mfma_f32_16x16x32_bf16 v[52:55], v[156:159], v[164:167], v[52:55]
	v_mfma_f32_16x16x32_bf16 v[40:43], v[148:151], v[172:175], v[40:43]
	v_mfma_f32_16x16x32_bf16 v[36:39], v[156:159], v[172:175], v[36:39]
	v_mfma_f32_16x16x32_bf16 v[24:27], v[148:151], v[180:183], v[24:27]
	v_mfma_f32_16x16x32_bf16 v[20:23], v[156:159], v[180:183], v[20:23]
	v_mfma_f32_16x16x32_bf16 v[8:11], v[148:151], v[188:191], v[8:11]
	v_mfma_f32_16x16x32_bf16 v[4:7], v[156:159], v[188:191], v[4:7]
	v_mfma_f32_16x16x32_bf16 v[56:59], v[152:155], v[168:171], v[56:59]
	v_mfma_f32_16x16x32_bf16 v[52:55], v[160:163], v[168:171], v[52:55]
	v_mfma_f32_16x16x32_bf16 v[40:43], v[152:155], v[176:179], v[40:43]
	v_mfma_f32_16x16x32_bf16 v[36:39], v[160:163], v[176:179], v[36:39]
	v_mfma_f32_16x16x32_bf16 v[24:27], v[152:155], v[184:187], v[24:27]
	v_mfma_f32_16x16x32_bf16 v[20:23], v[160:163], v[184:187], v[20:23]
	v_mfma_f32_16x16x32_bf16 v[8:11], v[152:155], v[192:195], v[8:11]
	v_mfma_f32_16x16x32_bf16 v[4:7], v[160:163], v[192:195], v[4:7]
	s_barrier
	s_setprio 0
	s_add_i32 s0, 0, 0x18000
	s_add_i32 s6, 0, 0x1c000
	v_add_u32_e32 v144, s0, v3
	v_add_u32_e32 v160, s6, v3
	ds_read_b128 v[124:127], v144
	ds_read_b128 v[128:131], v144 offset:1024
	ds_read_b128 v[140:143], v144 offset:2048
	ds_read_b128 v[144:147], v144 offset:3072
	ds_read_b128 v[148:151], v160
	ds_read_b128 v[152:155], v160 offset:1024
	ds_read_b128 v[156:159], v160 offset:2048
	ds_read_b128 v[160:163], v160 offset:3072
	s_add_u32 s34, s34, 0x204000
	s_addc_u32 s35, s35, 0
	s_mov_b32 m0, s39
	v_lshl_add_u64 v[222:223], s[34:35], 0, v[200:201]
	ds_read_b128 v[164:167], v250 offset:32768
	ds_read_b128 v[168:171], v250 offset:33792
	ds_read_b128 v[172:175], v250 offset:34816
	ds_read_b128 v[176:179], v250 offset:35840
	ds_read_b128 v[180:183], v250 offset:36864
	ds_read_b128 v[184:187], v250 offset:37888
	ds_read_b128 v[188:191], v250 offset:38912
	ds_read_b128 v[192:195], v250 offset:39936
	global_load_lds_dwordx4 v[222:223], off
	v_lshl_add_u64 v[222:223], s[34:35], 0, v[204:205]
	s_mov_b32 m0, s40
	s_nop 0
	global_load_lds_dwordx4 v[222:223], off
	s_waitcnt vmcnt(8)
	s_waitcnt lgkmcnt(0)
	s_setprio 1
	s_barrier
	v_mfma_f32_16x16x32_bf16 v[136:139], v[124:127], v[164:167], v[136:139]
	v_mfma_f32_16x16x32_bf16 v[132:135], v[140:143], v[164:167], v[132:135]
	v_mfma_f32_16x16x32_bf16 v[112:115], v[124:127], v[172:175], v[112:115]
	v_mfma_f32_16x16x32_bf16 v[108:111], v[140:143], v[172:175], v[108:111]
	v_mfma_f32_16x16x32_bf16 v[96:99], v[124:127], v[180:183], v[96:99]
	v_mfma_f32_16x16x32_bf16 v[92:95], v[140:143], v[180:183], v[92:95]
	v_mfma_f32_16x16x32_bf16 v[80:83], v[124:127], v[188:191], v[80:83]
	v_mfma_f32_16x16x32_bf16 v[76:79], v[140:143], v[188:191], v[76:79]
	v_mfma_f32_16x16x32_bf16 v[136:139], v[128:131], v[168:171], v[136:139]
	v_mfma_f32_16x16x32_bf16 v[132:135], v[144:147], v[168:171], v[132:135]
	v_mfma_f32_16x16x32_bf16 v[112:115], v[128:131], v[176:179], v[112:115]
	v_mfma_f32_16x16x32_bf16 v[108:111], v[144:147], v[176:179], v[108:111]
	v_mfma_f32_16x16x32_bf16 v[96:99], v[128:131], v[184:187], v[96:99]
	v_mfma_f32_16x16x32_bf16 v[92:95], v[144:147], v[184:187], v[92:95]
	v_mfma_f32_16x16x32_bf16 v[80:83], v[128:131], v[192:195], v[80:83]
	v_mfma_f32_16x16x32_bf16 v[76:79], v[144:147], v[192:195], v[76:79]
	s_setprio 0
	s_setprio 1
	v_mfma_f32_16x16x32_bf16 v[120:123], v[148:151], v[164:167], v[120:123]
	v_mfma_f32_16x16x32_bf16 v[116:119], v[156:159], v[164:167], v[116:119]
	v_mfma_f32_16x16x32_bf16 v[104:107], v[148:151], v[172:175], v[104:107]
	v_mfma_f32_16x16x32_bf16 v[100:103], v[156:159], v[172:175], v[100:103]
	v_mfma_f32_16x16x32_bf16 v[88:91], v[148:151], v[180:183], v[88:91]
	v_mfma_f32_16x16x32_bf16 v[84:87], v[156:159], v[180:183], v[84:87]
	v_mfma_f32_16x16x32_bf16 v[72:75], v[148:151], v[188:191], v[72:75]
	v_mfma_f32_16x16x32_bf16 v[68:71], v[156:159], v[188:191], v[68:71]
	v_mfma_f32_16x16x32_bf16 v[120:123], v[152:155], v[168:171], v[120:123]
	v_mfma_f32_16x16x32_bf16 v[116:119], v[160:163], v[168:171], v[116:119]
	v_mfma_f32_16x16x32_bf16 v[104:107], v[152:155], v[176:179], v[104:107]
	v_mfma_f32_16x16x32_bf16 v[100:103], v[160:163], v[176:179], v[100:103]
	v_mfma_f32_16x16x32_bf16 v[88:91], v[152:155], v[184:187], v[88:91]
	v_mfma_f32_16x16x32_bf16 v[84:87], v[160:163], v[184:187], v[84:87]
	v_mfma_f32_16x16x32_bf16 v[72:75], v[152:155], v[192:195], v[72:75]
	v_mfma_f32_16x16x32_bf16 v[68:71], v[160:163], v[192:195], v[68:71]
	s_barrier
	s_setprio 0
	s_add_i32 s0, s0, s27
	v_lshl_add_u64 v[198:199], v[198:199], 0, s[90:91]
	s_mov_b32 m0, s0
	ds_read_b128 v[164:167], v250 offset:49152
	ds_read_b128 v[168:171], v250 offset:50176
	ds_read_b128 v[172:175], v250 offset:51200
	ds_read_b128 v[176:179], v250 offset:52224
	ds_read_b128 v[180:183], v250 offset:53248
	ds_read_b128 v[184:187], v250 offset:54272
	ds_read_b128 v[188:191], v250 offset:55296
	ds_read_b128 v[192:195], v250 offset:56320
	global_load_lds_dwordx4 v[198:199], off
	s_add_i32 m0, s0, 0x2000
	s_add_u32 s30, s30, 0x204080
	v_lshl_add_u64 v[198:199], v[216:217], 0, s[90:91]
	s_addc_u32 s31, s31, 0
	s_add_i32 s0, s6, s27
	global_load_lds_dwordx4 v[198:199], off
	v_lshl_add_u64 v[198:199], s[30:31], 0, v[202:203]
	s_mov_b32 m0, s0
	s_nop 0
	global_load_lds_dwordx4 v[198:199], off
	v_lshl_add_u64 v[198:199], s[30:31], 0, v[206:207]
	s_add_i32 m0, s0, 0x2000
	s_nop 0
	global_load_lds_dwordx4 v[198:199], off
	v_lshl_add_u64 v[198:199], v[218:219], 0, s[90:91]
	s_mov_b32 m0, s50
	s_nop 0
	global_load_lds_dwordx4 v[198:199], off
	v_lshl_add_u64 v[198:199], v[220:221], 0, s[90:91]
	s_mov_b32 m0, s51
	s_nop 0
	global_load_lds_dwordx4 v[198:199], off
	s_waitcnt vmcnt(8)
	s_waitcnt lgkmcnt(0)
	s_setprio 1
	s_barrier
	v_mfma_f32_16x16x32_bf16 v[64:67], v[124:127], v[164:167], v[64:67]
	v_mfma_f32_16x16x32_bf16 v[60:63], v[140:143], v[164:167], v[60:63]
	v_mfma_f32_16x16x32_bf16 v[48:51], v[124:127], v[172:175], v[48:51]
	v_mfma_f32_16x16x32_bf16 v[44:47], v[140:143], v[172:175], v[44:47]
	v_mfma_f32_16x16x32_bf16 v[32:35], v[124:127], v[180:183], v[32:35]
	v_mfma_f32_16x16x32_bf16 v[28:31], v[140:143], v[180:183], v[28:31]
	v_mfma_f32_16x16x32_bf16 v[16:19], v[124:127], v[188:191], v[16:19]
	v_mfma_f32_16x16x32_bf16 v[12:15], v[140:143], v[188:191], v[12:15]
	v_mfma_f32_16x16x32_bf16 v[64:67], v[128:131], v[168:171], v[64:67]
	v_mfma_f32_16x16x32_bf16 v[60:63], v[144:147], v[168:171], v[60:63]
	v_mfma_f32_16x16x32_bf16 v[48:51], v[128:131], v[176:179], v[48:51]
	v_mfma_f32_16x16x32_bf16 v[44:47], v[144:147], v[176:179], v[44:47]
	v_mfma_f32_16x16x32_bf16 v[32:35], v[128:131], v[184:187], v[32:35]
	v_mfma_f32_16x16x32_bf16 v[28:31], v[144:147], v[184:187], v[28:31]
	v_mfma_f32_16x16x32_bf16 v[16:19], v[128:131], v[192:195], v[16:19]
	v_mfma_f32_16x16x32_bf16 v[12:15], v[144:147], v[192:195], v[12:15]
	s_setprio 0
	s_setprio 1
	v_mfma_f32_16x16x32_bf16 v[56:59], v[148:151], v[164:167], v[56:59]
	v_mfma_f32_16x16x32_bf16 v[52:55], v[156:159], v[164:167], v[52:55]
	v_mfma_f32_16x16x32_bf16 v[40:43], v[148:151], v[172:175], v[40:43]
	v_mfma_f32_16x16x32_bf16 v[36:39], v[156:159], v[172:175], v[36:39]
	v_mfma_f32_16x16x32_bf16 v[24:27], v[148:151], v[180:183], v[24:27]
	v_mfma_f32_16x16x32_bf16 v[20:23], v[156:159], v[180:183], v[20:23]
	v_mfma_f32_16x16x32_bf16 v[8:11], v[148:151], v[188:191], v[8:11]
	v_mfma_f32_16x16x32_bf16 v[4:7], v[156:159], v[188:191], v[4:7]
	v_mfma_f32_16x16x32_bf16 v[56:59], v[152:155], v[168:171], v[56:59]
	v_mfma_f32_16x16x32_bf16 v[52:55], v[160:163], v[168:171], v[52:55]
	v_mfma_f32_16x16x32_bf16 v[40:43], v[152:155], v[176:179], v[40:43]
	v_mfma_f32_16x16x32_bf16 v[36:39], v[160:163], v[176:179], v[36:39]
	v_mfma_f32_16x16x32_bf16 v[24:27], v[152:155], v[184:187], v[24:27]
	v_mfma_f32_16x16x32_bf16 v[20:23], v[160:163], v[184:187], v[20:23]
	v_mfma_f32_16x16x32_bf16 v[8:11], v[152:155], v[192:195], v[8:11]
	v_mfma_f32_16x16x32_bf16 v[4:7], v[160:163], v[192:195], v[4:7]
	s_barrier
	s_setprio 0
	s_add_u32 s69, s69, 0x100
	s_addc_u32 s72, s72, 0
	s_cmp_ge_i32 s74, s61
	s_mov_b64 s[36:37], s[62:63]
	s_mov_b32 s30, s74
	s_cbranch_scc0 .LBB0_1273
	s_and_b64 vcc, exec, s[22:23]
	s_cbranch_vccz .LBB0_1276
	s_barrier

.LBB0_1395:
	s_add_u32 s0, s36, 0xfff80080
	s_addc_u32 s6, s37, -1
	s_add_i32 s49, 0, 0x10000
	s_cmp_eq_u32 s67, 28
	s_cselect_b32 s35, s25, s6
	s_cselect_b32 s34, s33, s0
	s_cselect_b32 s31, s43, s39
	s_cselect_b32 s30, s45, s38
	s_add_i32 s0, 0, 0x14000
	v_add_u32_e32 v144, s49, v3
	v_add_u32_e32 v176, s0, v3
	ds_read_b128 v[132:135], v144
	ds_read_b128 v[136:139], v144 offset:1024
	ds_read_b128 v[140:143], v144 offset:2048
	ds_read_b128 v[144:147], v144 offset:3072
	ds_read_b128 v[164:167], v176
	ds_read_b128 v[168:171], v176 offset:1024
	ds_read_b128 v[172:175], v176 offset:2048
	ds_read_b128 v[176:179], v176 offset:3072
	v_lshl_add_u64 v[198:199], s[36:37], 0, v[160:161]
	s_add_i32 m0, s47, 0xc000
	ds_read_b128 v[180:183], v190
	ds_read_b128 v[184:187], v190 offset:1024
	ds_read_b128 v[192:195], v190 offset:2048
	ds_read_b128 v[200:203], v190 offset:3072
	ds_read_b128 v[204:207], v190 offset:4096
	ds_read_b128 v[208:211], v190 offset:5120
	ds_read_b128 v[212:215], v190 offset:6144
	ds_read_b128 v[216:219], v190 offset:7168
	global_load_lds_dwordx4 v[198:199], off
	v_lshl_add_u64 v[198:199], s[36:37], 0, v[162:163]
	s_add_i32 m0, s47, 0xe000
	s_nop 0
	global_load_lds_dwordx4 v[198:199], off
	s_waitcnt vmcnt(8)
	s_waitcnt lgkmcnt(0)
	s_setprio 1
	s_barrier
	v_mfma_f32_16x16x32_bf16 v[128:131], v[132:135], v[180:183], v[128:131]
	v_mfma_f32_16x16x32_bf16 v[124:127], v[140:143], v[180:183], v[124:127]
	v_mfma_f32_16x16x32_bf16 v[112:115], v[132:135], v[192:195], v[112:115]
	v_mfma_f32_16x16x32_bf16 v[108:111], v[140:143], v[192:195], v[108:111]
	v_mfma_f32_16x16x32_bf16 v[96:99], v[132:135], v[204:207], v[96:99]
	v_mfma_f32_16x16x32_bf16 v[92:95], v[140:143], v[204:207], v[92:95]
	v_mfma_f32_16x16x32_bf16 v[80:83], v[132:135], v[212:215], v[80:83]
	v_mfma_f32_16x16x32_bf16 v[76:79], v[140:143], v[212:215], v[76:79]
	v_mfma_f32_16x16x32_bf16 v[128:131], v[136:139], v[184:187], v[128:131]
	v_mfma_f32_16x16x32_bf16 v[124:127], v[144:147], v[184:187], v[124:127]
	v_mfma_f32_16x16x32_bf16 v[112:115], v[136:139], v[200:203], v[112:115]
	v_mfma_f32_16x16x32_bf16 v[108:111], v[144:147], v[200:203], v[108:111]
	v_mfma_f32_16x16x32_bf16 v[96:99], v[136:139], v[208:211], v[96:99]
	v_mfma_f32_16x16x32_bf16 v[92:95], v[144:147], v[208:211], v[92:95]
	v_mfma_f32_16x16x32_bf16 v[80:83], v[136:139], v[216:219], v[80:83]
	v_mfma_f32_16x16x32_bf16 v[76:79], v[144:147], v[216:219], v[76:79]
	s_setprio 0
	s_setprio 1
	v_mfma_f32_16x16x32_bf16 v[120:123], v[164:167], v[180:183], v[120:123]
	v_mfma_f32_16x16x32_bf16 v[116:119], v[172:175], v[180:183], v[116:119]
	v_mfma_f32_16x16x32_bf16 v[104:107], v[164:167], v[192:195], v[104:107]
	v_mfma_f32_16x16x32_bf16 v[100:103], v[172:175], v[192:195], v[100:103]
	v_mfma_f32_16x16x32_bf16 v[88:91], v[164:167], v[204:207], v[88:91]
	v_mfma_f32_16x16x32_bf16 v[84:87], v[172:175], v[204:207], v[84:87]
	v_mfma_f32_16x16x32_bf16 v[72:75], v[164:167], v[212:215], v[72:75]
	v_mfma_f32_16x16x32_bf16 v[68:71], v[172:175], v[212:215], v[68:71]
	v_mfma_f32_16x16x32_bf16 v[120:123], v[168:171], v[184:187], v[120:123]
	v_mfma_f32_16x16x32_bf16 v[116:119], v[176:179], v[184:187], v[116:119]
	v_mfma_f32_16x16x32_bf16 v[104:107], v[168:171], v[200:203], v[104:107]
	v_mfma_f32_16x16x32_bf16 v[100:103], v[176:179], v[200:203], v[100:103]
	v_mfma_f32_16x16x32_bf16 v[88:91], v[168:171], v[208:211], v[88:91]
	v_mfma_f32_16x16x32_bf16 v[84:87], v[176:179], v[208:211], v[84:87]
	v_mfma_f32_16x16x32_bf16 v[72:75], v[168:171], v[216:219], v[72:75]
	v_mfma_f32_16x16x32_bf16 v[68:71], v[176:179], v[216:219], v[68:71]
	s_barrier
	s_setprio 0
	s_add_i32 s6, s49, s4
	v_lshl_add_u64 v[198:199], s[30:31], 0, v[152:153]
	s_mov_b32 m0, s6
	ds_read_b128 v[180:183], v190 offset:16384
	ds_read_b128 v[184:187], v190 offset:17408
	ds_read_b128 v[192:195], v190 offset:18432
	ds_read_b128 v[200:203], v190 offset:19456
	ds_read_b128 v[204:207], v190 offset:20480
	ds_read_b128 v[208:211], v190 offset:21504
	ds_read_b128 v[212:215], v190 offset:22528
	ds_read_b128 v[216:219], v190 offset:23552
	global_load_lds_dwordx4 v[198:199], off
	s_add_i32 m0, s6, 0x2000
	s_add_u32 s68, s30, 0x80000
	v_lshl_add_u64 v[220:221], s[30:31], 0, v[148:149]
	s_addc_u32 s69, s31, 0
	s_add_i32 s0, s0, s4
	global_load_lds_dwordx4 v[220:221], off
	v_lshl_add_u64 v[222:223], s[68:69], 0, v[152:153]
	s_mov_b32 m0, s0
	v_lshl_add_u64 v[224:225], s[34:35], 0, v[150:151]
	global_load_lds_dwordx4 v[222:223], off
	v_lshl_add_u64 v[222:223], s[68:69], 0, v[148:149]
	s_add_i32 m0, s0, 0x2000
	s_nop 0
	global_load_lds_dwordx4 v[222:223], off
	v_lshl_add_u64 v[222:223], s[34:35], 0, v[154:155]
	s_mov_b32 m0, s47
	s_nop 0
	global_load_lds_dwordx4 v[222:223], off
	s_mov_b32 m0, s52
	s_nop 0
	global_load_lds_dwordx4 v[224:225], off
	s_waitcnt vmcnt(8)
	s_waitcnt lgkmcnt(0)
	s_setprio 1
	s_barrier
	v_mfma_f32_16x16x32_bf16 v[64:67], v[132:135], v[180:183], v[64:67]
	v_mfma_f32_16x16x32_bf16 v[60:63], v[140:143], v[180:183], v[60:63]
	v_mfma_f32_16x16x32_bf16 v[48:51], v[132:135], v[192:195], v[48:51]
	v_mfma_f32_16x16x32_bf16 v[44:47], v[140:143], v[192:195], v[44:47]
	v_mfma_f32_16x16x32_bf16 v[32:35], v[132:135], v[204:207], v[32:35]
	v_mfma_f32_16x16x32_bf16 v[28:31], v[140:143], v[204:207], v[28:31]
	v_mfma_f32_16x16x32_bf16 v[16:19], v[132:135], v[212:215], v[16:19]
	v_mfma_f32_16x16x32_bf16 v[12:15], v[140:143], v[212:215], v[12:15]
	v_mfma_f32_16x16x32_bf16 v[64:67], v[136:139], v[184:187], v[64:67]
	v_mfma_f32_16x16x32_bf16 v[60:63], v[144:147], v[184:187], v[60:63]
	v_mfma_f32_16x16x32_bf16 v[48:51], v[136:139], v[200:203], v[48:51]
	v_mfma_f32_16x16x32_bf16 v[44:47], v[144:147], v[200:203], v[44:47]
	v_mfma_f32_16x16x32_bf16 v[32:35], v[136:139], v[208:211], v[32:35]
	v_mfma_f32_16x16x32_bf16 v[28:31], v[144:147], v[208:211], v[28:31]
	v_mfma_f32_16x16x32_bf16 v[16:19], v[136:139], v[216:219], v[16:19]
	v_mfma_f32_16x16x32_bf16 v[12:15], v[144:147], v[216:219], v[12:15]
	s_setprio 0
	s_setprio 1
	v_mfma_f32_16x16x32_bf16 v[56:59], v[164:167], v[180:183], v[56:59]
	v_mfma_f32_16x16x32_bf16 v[52:55], v[172:175], v[180:183], v[52:55]
	v_mfma_f32_16x16x32_bf16 v[40:43], v[164:167], v[192:195], v[40:43]
	v_mfma_f32_16x16x32_bf16 v[36:39], v[172:175], v[192:195], v[36:39]
	v_mfma_f32_16x16x32_bf16 v[24:27], v[164:167], v[204:207], v[24:27]
	v_mfma_f32_16x16x32_bf16 v[20:23], v[172:175], v[204:207], v[20:23]
	v_mfma_f32_16x16x32_bf16 v[8:11], v[164:167], v[212:215], v[8:11]
	v_mfma_f32_16x16x32_bf16 v[4:7], v[172:175], v[212:215], v[4:7]
	v_mfma_f32_16x16x32_bf16 v[56:59], v[168:171], v[184:187], v[56:59]
	v_mfma_f32_16x16x32_bf16 v[52:55], v[176:179], v[184:187], v[52:55]
	v_mfma_f32_16x16x32_bf16 v[40:43], v[168:171], v[200:203], v[40:43]
	v_mfma_f32_16x16x32_bf16 v[36:39], v[176:179], v[200:203], v[36:39]
	v_mfma_f32_16x16x32_bf16 v[24:27], v[168:171], v[208:211], v[24:27]
	v_mfma_f32_16x16x32_bf16 v[20:23], v[176:179], v[208:211], v[20:23]
	v_mfma_f32_16x16x32_bf16 v[8:11], v[168:171], v[216:219], v[8:11]
	v_mfma_f32_16x16x32_bf16 v[4:7], v[176:179], v[216:219], v[4:7]
	s_barrier
	s_setprio 0
	s_add_i32 s0, 0, 0x18000
	s_add_i32 s6, 0, 0x1c000
	v_add_u32_e32 v144, s0, v3
	v_add_u32_e32 v176, s6, v3
	ds_read_b128 v[132:135], v144
	ds_read_b128 v[136:139], v144 offset:1024
	ds_read_b128 v[140:143], v144 offset:2048
	ds_read_b128 v[144:147], v144 offset:3072
	ds_read_b128 v[164:167], v176
	ds_read_b128 v[168:171], v176 offset:1024
	ds_read_b128 v[172:175], v176 offset:2048
	ds_read_b128 v[176:179], v176 offset:3072
	s_add_u32 s34, s34, 0x80000
	s_addc_u32 s35, s35, 0
	s_mov_b32 m0, s53
	v_lshl_add_u64 v[226:227], s[34:35], 0, v[154:155]
	ds_read_b128 v[180:183], v190 offset:32768
	ds_read_b128 v[184:187], v190 offset:33792
	ds_read_b128 v[192:195], v190 offset:34816
	ds_read_b128 v[200:203], v190 offset:35840
	ds_read_b128 v[204:207], v190 offset:36864
	ds_read_b128 v[208:211], v190 offset:37888
	ds_read_b128 v[212:215], v190 offset:38912
	ds_read_b128 v[216:219], v190 offset:39936
	global_load_lds_dwordx4 v[226:227], off
	v_lshl_add_u64 v[226:227], s[34:35], 0, v[150:151]
	s_mov_b32 m0, s59
	s_nop 0
	global_load_lds_dwordx4 v[226:227], off
	s_waitcnt vmcnt(8)
	s_waitcnt lgkmcnt(0)
	s_setprio 1
	s_barrier
	v_mfma_f32_16x16x32_bf16 v[128:131], v[132:135], v[180:183], v[128:131]
	v_mfma_f32_16x16x32_bf16 v[124:127], v[140:143], v[180:183], v[124:127]
	v_mfma_f32_16x16x32_bf16 v[112:115], v[132:135], v[192:195], v[112:115]
	v_mfma_f32_16x16x32_bf16 v[108:111], v[140:143], v[192:195], v[108:111]
	v_mfma_f32_16x16x32_bf16 v[96:99], v[132:135], v[204:207], v[96:99]
	v_mfma_f32_16x16x32_bf16 v[92:95], v[140:143], v[204:207], v[92:95]
	v_mfma_f32_16x16x32_bf16 v[80:83], v[132:135], v[212:215], v[80:83]
	v_mfma_f32_16x16x32_bf16 v[76:79], v[140:143], v[212:215], v[76:79]
	v_mfma_f32_16x16x32_bf16 v[128:131], v[136:139], v[184:187], v[128:131]
	v_mfma_f32_16x16x32_bf16 v[124:127], v[144:147], v[184:187], v[124:127]
	v_mfma_f32_16x16x32_bf16 v[112:115], v[136:139], v[200:203], v[112:115]
	v_mfma_f32_16x16x32_bf16 v[108:111], v[144:147], v[200:203], v[108:111]
	v_mfma_f32_16x16x32_bf16 v[96:99], v[136:139], v[208:211], v[96:99]
	v_mfma_f32_16x16x32_bf16 v[92:95], v[144:147], v[208:211], v[92:95]
	v_mfma_f32_16x16x32_bf16 v[80:83], v[136:139], v[216:219], v[80:83]
	v_mfma_f32_16x16x32_bf16 v[76:79], v[144:147], v[216:219], v[76:79]
	s_setprio 0
	s_setprio 1
	v_mfma_f32_16x16x32_bf16 v[120:123], v[164:167], v[180:183], v[120:123]
	v_mfma_f32_16x16x32_bf16 v[116:119], v[172:175], v[180:183], v[116:119]
	v_mfma_f32_16x16x32_bf16 v[104:107], v[164:167], v[192:195], v[104:107]
	v_mfma_f32_16x16x32_bf16 v[100:103], v[172:175], v[192:195], v[100:103]
	v_mfma_f32_16x16x32_bf16 v[88:91], v[164:167], v[204:207], v[88:91]
	v_mfma_f32_16x16x32_bf16 v[84:87], v[172:175], v[204:207], v[84:87]
	v_mfma_f32_16x16x32_bf16 v[72:75], v[164:167], v[212:215], v[72:75]
	v_mfma_f32_16x16x32_bf16 v[68:71], v[172:175], v[212:215], v[68:71]
	v_mfma_f32_16x16x32_bf16 v[120:123], v[168:171], v[184:187], v[120:123]
	v_mfma_f32_16x16x32_bf16 v[116:119], v[176:179], v[184:187], v[116:119]
	v_mfma_f32_16x16x32_bf16 v[104:107], v[168:171], v[200:203], v[104:107]
	v_mfma_f32_16x16x32_bf16 v[100:103], v[176:179], v[200:203], v[100:103]
	v_mfma_f32_16x16x32_bf16 v[88:91], v[168:171], v[208:211], v[88:91]
	v_mfma_f32_16x16x32_bf16 v[84:87], v[176:179], v[208:211], v[84:87]
	v_mfma_f32_16x16x32_bf16 v[72:75], v[168:171], v[216:219], v[72:75]
	v_mfma_f32_16x16x32_bf16 v[68:71], v[176:179], v[216:219], v[68:71]
	s_barrier
	s_setprio 0
	s_add_i32 s0, s0, s4
	v_lshl_add_u64 v[198:199], v[198:199], 0, s[90:91]
	s_mov_b32 m0, s0
	ds_read_b128 v[180:183], v190 offset:49152
	ds_read_b128 v[184:187], v190 offset:50176
	ds_read_b128 v[192:195], v190 offset:51200
	ds_read_b128 v[200:203], v190 offset:52224
	ds_read_b128 v[204:207], v190 offset:53248
	ds_read_b128 v[208:211], v190 offset:54272
	ds_read_b128 v[212:215], v190 offset:55296
	ds_read_b128 v[216:219], v190 offset:56320
	global_load_lds_dwordx4 v[198:199], off
	s_add_i32 m0, s0, 0x2000
	s_add_u32 s30, s30, 0x80080
	v_lshl_add_u64 v[198:199], v[220:221], 0, s[90:91]
	s_addc_u32 s31, s31, 0
	s_add_i32 s0, s6, s4
	global_load_lds_dwordx4 v[198:199], off
	v_lshl_add_u64 v[198:199], s[30:31], 0, v[152:153]
	s_mov_b32 m0, s0
	s_nop 0
	global_load_lds_dwordx4 v[198:199], off
	v_lshl_add_u64 v[198:199], s[30:31], 0, v[148:149]
	s_add_i32 m0, s0, 0x2000
	s_nop 0
	global_load_lds_dwordx4 v[198:199], off
	v_lshl_add_u64 v[198:199], v[222:223], 0, s[90:91]
	s_mov_b32 m0, s40
	s_nop 0
	global_load_lds_dwordx4 v[198:199], off
	v_lshl_add_u64 v[198:199], v[224:225], 0, s[90:91]
	s_mov_b32 m0, s66
	s_nop 0
	global_load_lds_dwordx4 v[198:199], off
	s_waitcnt vmcnt(8)
	s_waitcnt lgkmcnt(0)
	s_setprio 1
	s_barrier
	v_mfma_f32_16x16x32_bf16 v[64:67], v[132:135], v[180:183], v[64:67]
	v_mfma_f32_16x16x32_bf16 v[60:63], v[140:143], v[180:183], v[60:63]
	v_mfma_f32_16x16x32_bf16 v[48:51], v[132:135], v[192:195], v[48:51]
	v_mfma_f32_16x16x32_bf16 v[44:47], v[140:143], v[192:195], v[44:47]
	v_mfma_f32_16x16x32_bf16 v[32:35], v[132:135], v[204:207], v[32:35]
	v_mfma_f32_16x16x32_bf16 v[28:31], v[140:143], v[204:207], v[28:31]
	v_mfma_f32_16x16x32_bf16 v[16:19], v[132:135], v[212:215], v[16:19]
	v_mfma_f32_16x16x32_bf16 v[12:15], v[140:143], v[212:215], v[12:15]
	v_mfma_f32_16x16x32_bf16 v[64:67], v[136:139], v[184:187], v[64:67]
	v_mfma_f32_16x16x32_bf16 v[60:63], v[144:147], v[184:187], v[60:63]
	v_mfma_f32_16x16x32_bf16 v[48:51], v[136:139], v[200:203], v[48:51]
	v_mfma_f32_16x16x32_bf16 v[44:47], v[144:147], v[200:203], v[44:47]
	v_mfma_f32_16x16x32_bf16 v[32:35], v[136:139], v[208:211], v[32:35]
	v_mfma_f32_16x16x32_bf16 v[28:31], v[144:147], v[208:211], v[28:31]
	v_mfma_f32_16x16x32_bf16 v[16:19], v[136:139], v[216:219], v[16:19]
	v_mfma_f32_16x16x32_bf16 v[12:15], v[144:147], v[216:219], v[12:15]
	s_setprio 0
	s_setprio 1
	v_mfma_f32_16x16x32_bf16 v[56:59], v[164:167], v[180:183], v[56:59]
	v_mfma_f32_16x16x32_bf16 v[52:55], v[172:175], v[180:183], v[52:55]
	v_mfma_f32_16x16x32_bf16 v[40:43], v[164:167], v[192:195], v[40:43]
	v_mfma_f32_16x16x32_bf16 v[36:39], v[172:175], v[192:195], v[36:39]
	v_mfma_f32_16x16x32_bf16 v[24:27], v[164:167], v[204:207], v[24:27]
	v_mfma_f32_16x16x32_bf16 v[20:23], v[172:175], v[204:207], v[20:23]
	v_mfma_f32_16x16x32_bf16 v[8:11], v[164:167], v[212:215], v[8:11]
	v_mfma_f32_16x16x32_bf16 v[4:7], v[172:175], v[212:215], v[4:7]
	v_mfma_f32_16x16x32_bf16 v[56:59], v[168:171], v[184:187], v[56:59]
	v_mfma_f32_16x16x32_bf16 v[52:55], v[176:179], v[184:187], v[52:55]
	v_mfma_f32_16x16x32_bf16 v[40:43], v[168:171], v[200:203], v[40:43]
	v_mfma_f32_16x16x32_bf16 v[36:39], v[176:179], v[200:203], v[36:39]
	v_mfma_f32_16x16x32_bf16 v[24:27], v[168:171], v[208:211], v[24:27]
	v_mfma_f32_16x16x32_bf16 v[20:23], v[176:179], v[208:211], v[20:23]
	v_mfma_f32_16x16x32_bf16 v[8:11], v[168:171], v[216:219], v[8:11]
	v_mfma_f32_16x16x32_bf16 v[4:7], v[176:179], v[216:219], v[4:7]
	s_barrier
	s_setprio 0
	s_add_i32 s67, s67, 2
	s_add_u32 s36, s36, 0x100
	s_addc_u32 s37, s37, 0
	s_add_u32 s38, s38, 0x100
	s_addc_u32 s39, s39, 0
	s_cmp_gt_u32 s67, 29
	s_cbranch_scc0 .LBB0_1395
	s_and_b64 vcc, exec, s[28:29]
	s_cbranch_vccz .LBB0_1398
	s_barrier

.LBB0_1441:
	s_add_u32 s0, s62, s30
	s_addc_u32 s6, s63, 0
	s_add_u32 s31, s0, 0x100
	s_addc_u32 s46, s6, 0
	s_and_b64 s[34:35], s[38:39], exec
	s_cselect_b32 s53, s43, s46
	s_cselect_b32 s52, s75, s31
	s_add_u32 s30, s66, s30
	s_addc_u32 s31, s67, 0
	s_add_u32 s34, s30, 0x100
	s_addc_u32 s35, s31, 0
	s_add_i32 s83, 0, 0x10000
	s_and_b64 s[30:31], s[38:39], exec
	s_cselect_b32 s31, s45, s35
	s_cselect_b32 s30, s81, s34
	s_add_i32 s39, 0, 0x14000
	s_add_u32 s46, s0, 0x80080
	s_addc_u32 s47, s6, 0
	s_add_i32 s49, s83, s4
	s_add_i32 m0, s59, 0xc000
	s_add_i32 s97, s59, 0xe000
	s_add_i32 s82, s49, 0x2000
	s_add_u32 s34, s30, 0x80000
	v_add_u32_e32 v144, s83, v3
	v_add_u32_e32 v172, s39, v3
	s_addc_u32 s35, s31, 0
	s_add_i32 s85, s39, s4
	ds_read_b128 v[132:135], v144
	ds_read_b128 v[136:139], v144 offset:1024
	ds_read_b128 v[140:143], v144 offset:2048
	ds_read_b128 v[144:147], v144 offset:3072
	ds_read_b128 v[160:163], v172
	ds_read_b128 v[164:167], v172 offset:1024
	ds_read_b128 v[168:171], v172 offset:2048
	ds_read_b128 v[172:175], v172 offset:3072
	s_add_i32 s84, s85, 0x2000
	s_add_i32 s0, 0, 0x18000
	s_add_i32 s54, 0, 0x1c000
	s_add_u32 vcc_lo, s52, 0x80000
	s_addc_u32 vcc_hi, s53, 0
	s_add_i32 s73, s0, s4
	s_add_i32 s6, s73, 0x2000
	s_add_u32 s38, s30, 0x80080
	s_addc_u32 s39, s31, 0
	s_add_i32 s83, s54, s4
	s_add_i32 s96, s83, 0x2000
	v_lshl_add_u64 v[198:199], s[46:47], 0, v[154:155]
	ds_read_b128 v[176:179], v186
	ds_read_b128 v[180:183], v186 offset:1024
	ds_read_b128 v[188:191], v186 offset:2048
	ds_read_b128 v[192:195], v186 offset:3072
	ds_read_b128 v[200:203], v186 offset:4096
	ds_read_b128 v[204:207], v186 offset:5120
	ds_read_b128 v[208:211], v186 offset:6144
	ds_read_b128 v[212:215], v186 offset:7168
	global_load_lds_dwordx4 v[198:199], off
	v_lshl_add_u64 v[198:199], s[46:47], 0, v[150:151]
	s_mov_b32 m0, s97
	s_nop 0
	global_load_lds_dwordx4 v[198:199], off
	s_waitcnt vmcnt(8)
	s_waitcnt lgkmcnt(0)
	s_setprio 1
	s_barrier
	v_mfma_f32_16x16x32_bf16 v[128:131], v[132:135], v[176:179], v[128:131]
	v_mfma_f32_16x16x32_bf16 v[124:127], v[140:143], v[176:179], v[124:127]
	v_mfma_f32_16x16x32_bf16 v[112:115], v[132:135], v[188:191], v[112:115]
	v_mfma_f32_16x16x32_bf16 v[108:111], v[140:143], v[188:191], v[108:111]
	v_mfma_f32_16x16x32_bf16 v[96:99], v[132:135], v[200:203], v[96:99]
	v_mfma_f32_16x16x32_bf16 v[92:95], v[140:143], v[200:203], v[92:95]
	v_mfma_f32_16x16x32_bf16 v[80:83], v[132:135], v[208:211], v[80:83]
	v_mfma_f32_16x16x32_bf16 v[76:79], v[140:143], v[208:211], v[76:79]
	v_mfma_f32_16x16x32_bf16 v[128:131], v[136:139], v[180:183], v[128:131]
	v_mfma_f32_16x16x32_bf16 v[124:127], v[144:147], v[180:183], v[124:127]
	v_mfma_f32_16x16x32_bf16 v[112:115], v[136:139], v[192:195], v[112:115]
	v_mfma_f32_16x16x32_bf16 v[108:111], v[144:147], v[192:195], v[108:111]
	v_mfma_f32_16x16x32_bf16 v[96:99], v[136:139], v[204:207], v[96:99]
	v_mfma_f32_16x16x32_bf16 v[92:95], v[144:147], v[204:207], v[92:95]
	v_mfma_f32_16x16x32_bf16 v[80:83], v[136:139], v[212:215], v[80:83]
	v_mfma_f32_16x16x32_bf16 v[76:79], v[144:147], v[212:215], v[76:79]
	s_setprio 0
	s_setprio 1
	v_mfma_f32_16x16x32_bf16 v[120:123], v[160:163], v[176:179], v[120:123]
	v_mfma_f32_16x16x32_bf16 v[116:119], v[168:171], v[176:179], v[116:119]
	v_mfma_f32_16x16x32_bf16 v[104:107], v[160:163], v[188:191], v[104:107]
	v_mfma_f32_16x16x32_bf16 v[100:103], v[168:171], v[188:191], v[100:103]
	v_mfma_f32_16x16x32_bf16 v[88:91], v[160:163], v[200:203], v[88:91]
	v_mfma_f32_16x16x32_bf16 v[84:87], v[168:171], v[200:203], v[84:87]
	v_mfma_f32_16x16x32_bf16 v[72:75], v[160:163], v[208:211], v[72:75]
	v_mfma_f32_16x16x32_bf16 v[68:71], v[168:171], v[208:211], v[68:71]
	v_mfma_f32_16x16x32_bf16 v[120:123], v[164:167], v[180:183], v[120:123]
	v_mfma_f32_16x16x32_bf16 v[116:119], v[172:175], v[180:183], v[116:119]
	v_mfma_f32_16x16x32_bf16 v[104:107], v[164:167], v[192:195], v[104:107]
	v_mfma_f32_16x16x32_bf16 v[100:103], v[172:175], v[192:195], v[100:103]
	v_mfma_f32_16x16x32_bf16 v[88:91], v[164:167], v[204:207], v[88:91]
	v_mfma_f32_16x16x32_bf16 v[84:87], v[172:175], v[204:207], v[84:87]
	v_mfma_f32_16x16x32_bf16 v[72:75], v[164:167], v[212:215], v[72:75]
	v_mfma_f32_16x16x32_bf16 v[68:71], v[172:175], v[212:215], v[68:71]
	s_barrier
	s_setprio 0
	s_mov_b32 m0, s49
	v_lshl_add_u64 v[198:199], s[30:31], 0, v[152:153]
	ds_read_b128 v[176:179], v186 offset:16384
	ds_read_b128 v[180:183], v186 offset:17408
	ds_read_b128 v[188:191], v186 offset:18432
	ds_read_b128 v[192:195], v186 offset:19456
	ds_read_b128 v[200:203], v186 offset:20480
	ds_read_b128 v[204:207], v186 offset:21504
	ds_read_b128 v[208:211], v186 offset:22528
	ds_read_b128 v[212:215], v186 offset:23552
	global_load_lds_dwordx4 v[198:199], off
	v_lshl_add_u64 v[216:217], s[30:31], 0, v[148:149]
	s_mov_b32 m0, s82
	v_lshl_add_u64 v[218:219], s[34:35], 0, v[152:153]
	global_load_lds_dwordx4 v[216:217], off
	s_mov_b32 m0, s85
	v_lshl_add_u64 v[220:221], s[52:53], 0, v[150:151]
	global_load_lds_dwordx4 v[218:219], off
	v_lshl_add_u64 v[218:219], s[34:35], 0, v[148:149]
	s_mov_b32 m0, s84
	s_nop 0
	global_load_lds_dwordx4 v[218:219], off
	v_lshl_add_u64 v[218:219], s[52:53], 0, v[154:155]
	s_mov_b32 m0, s59
	s_nop 0
	global_load_lds_dwordx4 v[218:219], off
	s_mov_b32 m0, s40
	s_nop 0
	global_load_lds_dwordx4 v[220:221], off
	s_waitcnt vmcnt(8)
	s_waitcnt lgkmcnt(0)
	s_setprio 1
	s_barrier
	v_mfma_f32_16x16x32_bf16 v[64:67], v[132:135], v[176:179], v[64:67]
	v_mfma_f32_16x16x32_bf16 v[60:63], v[140:143], v[176:179], v[60:63]
	v_mfma_f32_16x16x32_bf16 v[48:51], v[132:135], v[188:191], v[48:51]
	v_mfma_f32_16x16x32_bf16 v[44:47], v[140:143], v[188:191], v[44:47]
	v_mfma_f32_16x16x32_bf16 v[32:35], v[132:135], v[200:203], v[32:35]
	v_mfma_f32_16x16x32_bf16 v[28:31], v[140:143], v[200:203], v[28:31]
	v_mfma_f32_16x16x32_bf16 v[16:19], v[132:135], v[208:211], v[16:19]
	v_mfma_f32_16x16x32_bf16 v[12:15], v[140:143], v[208:211], v[12:15]
	v_mfma_f32_16x16x32_bf16 v[64:67], v[136:139], v[180:183], v[64:67]
	v_mfma_f32_16x16x32_bf16 v[60:63], v[144:147], v[180:183], v[60:63]
	v_mfma_f32_16x16x32_bf16 v[48:51], v[136:139], v[192:195], v[48:51]
	v_mfma_f32_16x16x32_bf16 v[44:47], v[144:147], v[192:195], v[44:47]
	v_mfma_f32_16x16x32_bf16 v[32:35], v[136:139], v[204:207], v[32:35]
	v_mfma_f32_16x16x32_bf16 v[28:31], v[144:147], v[204:207], v[28:31]
	v_mfma_f32_16x16x32_bf16 v[16:19], v[136:139], v[212:215], v[16:19]
	v_mfma_f32_16x16x32_bf16 v[12:15], v[144:147], v[212:215], v[12:15]
	s_setprio 0
	s_setprio 1
	v_mfma_f32_16x16x32_bf16 v[56:59], v[160:163], v[176:179], v[56:59]
	v_mfma_f32_16x16x32_bf16 v[52:55], v[168:171], v[176:179], v[52:55]
	v_mfma_f32_16x16x32_bf16 v[40:43], v[160:163], v[188:191], v[40:43]
	v_mfma_f32_16x16x32_bf16 v[36:39], v[168:171], v[188:191], v[36:39]
	v_mfma_f32_16x16x32_bf16 v[24:27], v[160:163], v[200:203], v[24:27]
	v_mfma_f32_16x16x32_bf16 v[20:23], v[168:171], v[200:203], v[20:23]
	v_mfma_f32_16x16x32_bf16 v[8:11], v[160:163], v[208:211], v[8:11]
	v_mfma_f32_16x16x32_bf16 v[4:7], v[168:171], v[208:211], v[4:7]
	v_mfma_f32_16x16x32_bf16 v[56:59], v[164:167], v[180:183], v[56:59]
	v_mfma_f32_16x16x32_bf16 v[52:55], v[172:175], v[180:183], v[52:55]
	v_mfma_f32_16x16x32_bf16 v[40:43], v[164:167], v[192:195], v[40:43]
	v_mfma_f32_16x16x32_bf16 v[36:39], v[172:175], v[192:195], v[36:39]
	v_mfma_f32_16x16x32_bf16 v[24:27], v[164:167], v[204:207], v[24:27]
	v_mfma_f32_16x16x32_bf16 v[20:23], v[172:175], v[204:207], v[20:23]
	v_mfma_f32_16x16x32_bf16 v[8:11], v[164:167], v[212:215], v[8:11]
	v_mfma_f32_16x16x32_bf16 v[4:7], v[172:175], v[212:215], v[4:7]
	s_barrier
	s_setprio 0
	v_add_u32_e32 v144, s0, v3
	v_add_u32_e32 v172, s54, v3
	ds_read_b128 v[132:135], v144
	ds_read_b128 v[136:139], v144 offset:1024
	ds_read_b128 v[140:143], v144 offset:2048
	ds_read_b128 v[144:147], v144 offset:3072
	ds_read_b128 v[160:163], v172
	ds_read_b128 v[164:167], v172 offset:1024
	ds_read_b128 v[168:171], v172 offset:2048
	ds_read_b128 v[172:175], v172 offset:3072
	s_mov_b32 m0, s55
	v_lshl_add_u64 v[222:223], vcc, 0, v[154:155]
	ds_read_b128 v[176:179], v186 offset:32768
	ds_read_b128 v[180:183], v186 offset:33792
	ds_read_b128 v[188:191], v186 offset:34816
	ds_read_b128 v[192:195], v186 offset:35840
	ds_read_b128 v[200:203], v186 offset:36864
	ds_read_b128 v[204:207], v186 offset:37888
	ds_read_b128 v[208:211], v186 offset:38912
	ds_read_b128 v[212:215], v186 offset:39936
	global_load_lds_dwordx4 v[222:223], off
	v_lshl_add_u64 v[222:223], vcc, 0, v[150:151]
	s_mov_b32 m0, s50
	s_nop 0
	global_load_lds_dwordx4 v[222:223], off
	s_waitcnt vmcnt(8)
	s_waitcnt lgkmcnt(0)
	s_setprio 1
	s_barrier
	v_mfma_f32_16x16x32_bf16 v[128:131], v[132:135], v[176:179], v[128:131]
	v_mfma_f32_16x16x32_bf16 v[124:127], v[140:143], v[176:179], v[124:127]
	v_mfma_f32_16x16x32_bf16 v[112:115], v[132:135], v[188:191], v[112:115]
	v_mfma_f32_16x16x32_bf16 v[108:111], v[140:143], v[188:191], v[108:111]
	v_mfma_f32_16x16x32_bf16 v[96:99], v[132:135], v[200:203], v[96:99]
	v_mfma_f32_16x16x32_bf16 v[92:95], v[140:143], v[200:203], v[92:95]
	v_mfma_f32_16x16x32_bf16 v[80:83], v[132:135], v[208:211], v[80:83]
	v_mfma_f32_16x16x32_bf16 v[76:79], v[140:143], v[208:211], v[76:79]
	v_mfma_f32_16x16x32_bf16 v[128:131], v[136:139], v[180:183], v[128:131]
	v_mfma_f32_16x16x32_bf16 v[124:127], v[144:147], v[180:183], v[124:127]
	v_mfma_f32_16x16x32_bf16 v[112:115], v[136:139], v[192:195], v[112:115]
	v_mfma_f32_16x16x32_bf16 v[108:111], v[144:147], v[192:195], v[108:111]
	v_mfma_f32_16x16x32_bf16 v[96:99], v[136:139], v[204:207], v[96:99]
	v_mfma_f32_16x16x32_bf16 v[92:95], v[144:147], v[204:207], v[92:95]
	v_mfma_f32_16x16x32_bf16 v[80:83], v[136:139], v[212:215], v[80:83]
	v_mfma_f32_16x16x32_bf16 v[76:79], v[144:147], v[212:215], v[76:79]
	s_setprio 0
	s_setprio 1
	v_mfma_f32_16x16x32_bf16 v[120:123], v[160:163], v[176:179], v[120:123]
	v_mfma_f32_16x16x32_bf16 v[116:119], v[168:171], v[176:179], v[116:119]
	v_mfma_f32_16x16x32_bf16 v[104:107], v[160:163], v[188:191], v[104:107]
	v_mfma_f32_16x16x32_bf16 v[100:103], v[168:171], v[188:191], v[100:103]
	v_mfma_f32_16x16x32_bf16 v[88:91], v[160:163], v[200:203], v[88:91]
	v_mfma_f32_16x16x32_bf16 v[84:87], v[168:171], v[200:203], v[84:87]
	v_mfma_f32_16x16x32_bf16 v[72:75], v[160:163], v[208:211], v[72:75]
	v_mfma_f32_16x16x32_bf16 v[68:71], v[168:171], v[208:211], v[68:71]
	v_mfma_f32_16x16x32_bf16 v[120:123], v[164:167], v[180:183], v[120:123]
	v_mfma_f32_16x16x32_bf16 v[116:119], v[172:175], v[180:183], v[116:119]
	v_mfma_f32_16x16x32_bf16 v[104:107], v[164:167], v[192:195], v[104:107]
	v_mfma_f32_16x16x32_bf16 v[100:103], v[172:175], v[192:195], v[100:103]
	v_mfma_f32_16x16x32_bf16 v[88:91], v[164:167], v[204:207], v[88:91]
	v_mfma_f32_16x16x32_bf16 v[84:87], v[172:175], v[204:207], v[84:87]
	v_mfma_f32_16x16x32_bf16 v[72:75], v[164:167], v[212:215], v[72:75]
	v_mfma_f32_16x16x32_bf16 v[68:71], v[172:175], v[212:215], v[68:71]
	s_barrier
	s_setprio 0
	s_mov_b32 m0, s73
	v_lshl_add_u64 v[198:199], v[198:199], 0, s[90:91]
	ds_read_b128 v[176:179], v186 offset:49152
	ds_read_b128 v[180:183], v186 offset:50176
	ds_read_b128 v[188:191], v186 offset:51200
	ds_read_b128 v[192:195], v186 offset:52224
	ds_read_b128 v[200:203], v186 offset:53248
	ds_read_b128 v[204:207], v186 offset:54272
	ds_read_b128 v[208:211], v186 offset:55296
	ds_read_b128 v[212:215], v186 offset:56320
	global_load_lds_dwordx4 v[198:199], off
	v_lshl_add_u64 v[198:199], v[216:217], 0, s[90:91]
	s_mov_b32 m0, s6
	s_nop 0
	global_load_lds_dwordx4 v[198:199], off
	v_lshl_add_u64 v[198:199], s[38:39], 0, v[152:153]
	s_mov_b32 m0, s83
	s_nop 0
	global_load_lds_dwordx4 v[198:199], off
	v_lshl_add_u64 v[198:199], s[38:39], 0, v[148:149]
	s_mov_b32 m0, s96
	s_nop 0
	global_load_lds_dwordx4 v[198:199], off
	v_lshl_add_u64 v[198:199], v[218:219], 0, s[90:91]
	s_mov_b32 m0, s1
	s_nop 0
	global_load_lds_dwordx4 v[198:199], off
	v_lshl_add_u64 v[198:199], v[220:221], 0, s[90:91]
	s_mov_b32 m0, s24
	s_nop 0
	global_load_lds_dwordx4 v[198:199], off
	s_waitcnt vmcnt(8)
	s_waitcnt lgkmcnt(0)
	s_setprio 1
	s_barrier
	v_mfma_f32_16x16x32_bf16 v[64:67], v[132:135], v[176:179], v[64:67]
	v_mfma_f32_16x16x32_bf16 v[60:63], v[140:143], v[176:179], v[60:63]
	v_mfma_f32_16x16x32_bf16 v[48:51], v[132:135], v[188:191], v[48:51]
	v_mfma_f32_16x16x32_bf16 v[44:47], v[140:143], v[188:191], v[44:47]
	v_mfma_f32_16x16x32_bf16 v[32:35], v[132:135], v[200:203], v[32:35]
	v_mfma_f32_16x16x32_bf16 v[28:31], v[140:143], v[200:203], v[28:31]
	v_mfma_f32_16x16x32_bf16 v[16:19], v[132:135], v[208:211], v[16:19]
	v_mfma_f32_16x16x32_bf16 v[12:15], v[140:143], v[208:211], v[12:15]
	v_mfma_f32_16x16x32_bf16 v[64:67], v[136:139], v[180:183], v[64:67]
	v_mfma_f32_16x16x32_bf16 v[60:63], v[144:147], v[180:183], v[60:63]
	v_mfma_f32_16x16x32_bf16 v[48:51], v[136:139], v[192:195], v[48:51]
	v_mfma_f32_16x16x32_bf16 v[44:47], v[144:147], v[192:195], v[44:47]
	v_mfma_f32_16x16x32_bf16 v[32:35], v[136:139], v[204:207], v[32:35]
	v_mfma_f32_16x16x32_bf16 v[28:31], v[144:147], v[204:207], v[28:31]
	v_mfma_f32_16x16x32_bf16 v[16:19], v[136:139], v[212:215], v[16:19]
	v_mfma_f32_16x16x32_bf16 v[12:15], v[144:147], v[212:215], v[12:15]
	s_setprio 0
	s_setprio 1
	v_mfma_f32_16x16x32_bf16 v[56:59], v[160:163], v[176:179], v[56:59]
	v_mfma_f32_16x16x32_bf16 v[52:55], v[168:171], v[176:179], v[52:55]
	v_mfma_f32_16x16x32_bf16 v[40:43], v[160:163], v[188:191], v[40:43]
	v_mfma_f32_16x16x32_bf16 v[36:39], v[168:171], v[188:191], v[36:39]
	v_mfma_f32_16x16x32_bf16 v[24:27], v[160:163], v[200:203], v[24:27]
	v_mfma_f32_16x16x32_bf16 v[20:23], v[168:171], v[200:203], v[20:23]
	v_mfma_f32_16x16x32_bf16 v[8:11], v[160:163], v[208:211], v[8:11]
	v_mfma_f32_16x16x32_bf16 v[4:7], v[168:171], v[208:211], v[4:7]
	v_mfma_f32_16x16x32_bf16 v[56:59], v[164:167], v[180:183], v[56:59]
	v_mfma_f32_16x16x32_bf16 v[52:55], v[172:175], v[180:183], v[52:55]
	v_mfma_f32_16x16x32_bf16 v[40:43], v[164:167], v[192:195], v[40:43]
	v_mfma_f32_16x16x32_bf16 v[36:39], v[172:175], v[192:195], v[36:39]
	v_mfma_f32_16x16x32_bf16 v[24:27], v[164:167], v[204:207], v[24:27]
	v_mfma_f32_16x16x32_bf16 v[20:23], v[172:175], v[204:207], v[20:23]
	v_mfma_f32_16x16x32_bf16 v[8:11], v[164:167], v[212:215], v[8:11]
	v_mfma_f32_16x16x32_bf16 v[4:7], v[172:175], v[212:215], v[4:7]
	s_barrier
	s_setprio 0
	s_movk_i32 s30, 0x100
	s_andn2_b64 vcc, exec, s[36:37]
	s_mov_b64 s[38:39], -1
	s_mov_b64 s[36:37], 0
	s_cbranch_vccz .LBB0_1441
	s_and_b64 vcc, exec, s[28:29]
	s_cbranch_vccz .LBB0_1444
	s_barrier
